# lever 9 (7.12-style): the 319 per-element s_cbranch_execz skip branches of the neighbourhood-attention bias step removed (the exec-masked body is a no-op with no active lane)
# baseline (speedup 1.0000x reference)
.LBB0_933:
	v_med3_i32 v72, s0, 4, 28
	v_sub_u32_e32 v8, v72, v80
	v_lshlrev_b32_e32 v8, 6, v8
	v_add_u32_e32 v79, v8, v84
	v_lshlrev_b32_e32 v8, 1, v87
	v_and_b32_e32 v75, 3, v86
	v_and_or_b32 v8, v8, 24, v75
	v_add_u32_e32 v82, v8, v79
	v_lshlrev_b32_e32 v8, 1, v82
	v_ashrrev_i32_e32 v77, 4, v86
	v_bfe_u32 v12, v82, 3, 2
	v_and_b32_e32 v89, 4, v8
	v_bitop3_b32 v8, v12, v77, v89 bitop3:0x36
	v_lshlrev_b32_e32 v20, 7, v82
	v_lshl_add_u32 v21, v8, 4, 0
	v_add_u32_e32 v90, v21, v20
	s_waitcnt vmcnt(0) lgkmcnt(0)
	s_waitcnt vmcnt(0) lgkmcnt(0)
	s_barrier
	ds_read_b128 v[8:11], v90
	v_add_u32_e32 v83, 4, v77
	v_bitop3_b32 v12, v12, v83, v89 bitop3:0x36
	v_lshl_add_u32 v28, v12, 4, 0
	v_add_u32_e32 v91, v28, v20
	ds_read_b128 v[12:15], v91
	ds_read_b128 v[16:19], v90 offset:8192
	s_waitcnt lgkmcnt(2)
	v_mfma_f32_16x16x32_bf16 v[8:11], v[8:11], v[4:7], 0
	v_or_b32_e32 v29, 0x200, v20
	v_add_u32_e32 v20, v21, v29
	ds_read_b128 v[20:23], v20
	ds_read_b128 v[24:27], v91 offset:8192
	s_waitcnt lgkmcnt(3)
	v_mfma_f32_16x16x32_bf16 v[68:71], v[12:15], v[0:3], v[8:11]
	s_mul_i32 s1, s91, 0x744
	v_subrev_u32_e32 v72, s0, v72
	s_movk_i32 s0, 0x7c
	v_add_u32_e32 v8, v28, v29
	ds_read_b128 v[8:11], v8
	s_waitcnt lgkmcnt(2)
	v_mfma_f32_16x16x32_bf16 v[12:15], v[20:23], v[4:7], 0
	v_lshl_add_u32 v99, v77, 3, v84
	s_add_i32 s1, s1, 0
	v_mul_lo_u32 v72, v72, s0
	s_waitcnt lgkmcnt(0)
	v_mfma_f32_16x16x32_bf16 v[64:67], v[8:11], v[0:3], v[12:15]
	v_add_u32_e32 v72, s1, v72
	v_add_u32_e32 v100, 0x22100, v72
	v_mfma_f32_16x16x32_bf16 v[8:11], v[16:19], v[4:7], 0
	v_mfma_f32_16x16x32_bf16 v[60:63], v[24:27], v[0:3], v[8:11]
	s_nop 6
	v_add_u32_e32 v8, 0x44, v82
	v_bfe_u32 v13, v8, 3, 2
	v_lshlrev_b32_e32 v12, 7, v8
	v_bitop3_b32 v8, v13, v77, v89 bitop3:0x36
	v_lshlrev_b32_e32 v8, 4, v8
	v_add3_u32 v8, 0, v8, v12
	ds_read_b128 v[8:11], v8
	v_bitop3_b32 v13, v13, v83, v89 bitop3:0x36
	v_lshlrev_b32_e32 v13, 4, v13
	v_add3_u32 v12, 0, v13, v12
	ds_read_b128 v[12:15], v12
	s_waitcnt lgkmcnt(1)
	v_mfma_f32_16x16x32_bf16 v[8:11], v[8:11], v[4:7], 0
	s_waitcnt lgkmcnt(0)
	v_mfma_f32_16x16x32_bf16 v[56:59], v[12:15], v[0:3], v[8:11]
	s_nop 5
	ds_read_b128 v[8:11], v90 offset:16384
	ds_read_b128 v[12:15], v90 offset:24576
	ds_read_b128 v[16:19], v91 offset:16384
	ds_read_b128 v[20:23], v91 offset:24576
	s_waitcnt lgkmcnt(3)
	v_mfma_f32_16x16x32_bf16 v[8:11], v[8:11], v[4:7], 0
	s_waitcnt lgkmcnt(1)
	v_mfma_f32_16x16x32_bf16 v[52:55], v[16:19], v[0:3], v[8:11]
	s_nop 5
	v_add_u32_e32 v8, 0x84, v82
	v_bfe_u32 v17, v8, 3, 2
	v_lshlrev_b32_e32 v16, 7, v8
	v_bitop3_b32 v8, v17, v77, v89 bitop3:0x36
	v_lshlrev_b32_e32 v8, 4, v8
	v_add3_u32 v8, 0, v8, v16
	ds_read_b128 v[8:11], v8
	v_bitop3_b32 v17, v17, v83, v89 bitop3:0x36
	v_lshlrev_b32_e32 v17, 4, v17
	v_add3_u32 v16, 0, v17, v16
	ds_read_b128 v[16:19], v16
	s_waitcnt lgkmcnt(1)
	v_mfma_f32_16x16x32_bf16 v[8:11], v[8:11], v[4:7], 0
	s_waitcnt lgkmcnt(0)
	v_mfma_f32_16x16x32_bf16 v[48:51], v[16:19], v[0:3], v[8:11]
	v_mfma_f32_16x16x32_bf16 v[8:11], v[12:15], v[4:7], 0
	v_mfma_f32_16x16x32_bf16 v[44:47], v[20:23], v[0:3], v[8:11]
	s_nop 6
	v_add_u32_e32 v8, 0xc4, v82
	v_bfe_u32 v13, v8, 3, 2
	v_lshlrev_b32_e32 v12, 7, v8
	v_bitop3_b32 v8, v13, v77, v89 bitop3:0x36
	v_lshlrev_b32_e32 v8, 4, v8
	v_add3_u32 v8, 0, v8, v12
	ds_read_b128 v[8:11], v8
	v_bitop3_b32 v13, v13, v83, v89 bitop3:0x36
	v_lshlrev_b32_e32 v13, 4, v13
	v_add3_u32 v12, 0, v13, v12
	ds_read_b128 v[12:15], v12
	s_waitcnt lgkmcnt(1)
	v_mfma_f32_16x16x32_bf16 v[8:11], v[8:11], v[4:7], 0
	s_waitcnt lgkmcnt(0)
	v_mfma_f32_16x16x32_bf16 v[40:43], v[12:15], v[0:3], v[8:11]
	s_nop 5
	ds_read_b128 v[8:11], v90 offset:32768
	ds_read_b128 v[12:15], v90 offset:40960
	ds_read_b128 v[16:19], v91 offset:32768
	ds_read_b128 v[20:23], v91 offset:40960
	s_waitcnt lgkmcnt(3)
	v_mfma_f32_16x16x32_bf16 v[8:11], v[8:11], v[4:7], 0
	s_waitcnt lgkmcnt(1)
	v_mfma_f32_16x16x32_bf16 v[36:39], v[16:19], v[0:3], v[8:11]
	s_nop 5
	v_add_u32_e32 v8, 0x104, v82
	v_bfe_u32 v17, v8, 3, 2
	v_lshlrev_b32_e32 v16, 7, v8
	v_bitop3_b32 v8, v17, v77, v89 bitop3:0x36
	v_lshlrev_b32_e32 v8, 4, v8
	v_add3_u32 v8, 0, v8, v16
	ds_read_b128 v[8:11], v8
	v_bitop3_b32 v17, v17, v83, v89 bitop3:0x36
	v_lshlrev_b32_e32 v17, 4, v17
	v_add3_u32 v16, 0, v17, v16
	ds_read_b128 v[16:19], v16
	s_waitcnt lgkmcnt(1)
	v_mfma_f32_16x16x32_bf16 v[8:11], v[8:11], v[4:7], 0
	s_waitcnt lgkmcnt(0)
	v_mfma_f32_16x16x32_bf16 v[32:35], v[16:19], v[0:3], v[8:11]
	v_mfma_f32_16x16x32_bf16 v[8:11], v[12:15], v[4:7], 0
	v_mfma_f32_16x16x32_bf16 v[28:31], v[20:23], v[0:3], v[8:11]
	s_nop 6
	v_add_u32_e32 v8, 0x144, v82
	v_bfe_u32 v13, v8, 3, 2
	v_lshlrev_b32_e32 v12, 7, v8
	v_bitop3_b32 v8, v13, v77, v89 bitop3:0x36
	v_lshlrev_b32_e32 v8, 4, v8
	v_add3_u32 v8, 0, v8, v12
	ds_read_b128 v[8:11], v8
	v_bitop3_b32 v13, v13, v83, v89 bitop3:0x36
	v_lshlrev_b32_e32 v13, 4, v13
	v_add3_u32 v12, 0, v13, v12
	ds_read_b128 v[12:15], v12
	s_waitcnt lgkmcnt(1)
	v_mfma_f32_16x16x32_bf16 v[8:11], v[8:11], v[4:7], 0
	s_waitcnt lgkmcnt(0)
	v_mfma_f32_16x16x32_bf16 v[24:27], v[12:15], v[0:3], v[8:11]
	s_nop 5
	ds_read_b128 v[8:11], v90 offset:49152
	ds_read_b128 v[12:15], v90 offset:57344
	ds_read_b128 v[16:19], v91 offset:49152
	ds_read_b128 v[90:93], v91 offset:57344
	s_waitcnt lgkmcnt(3)
	v_mfma_f32_16x16x32_bf16 v[8:11], v[8:11], v[4:7], 0
	s_waitcnt lgkmcnt(1)
	v_mfma_f32_16x16x32_bf16 v[20:23], v[16:19], v[0:3], v[8:11]
	s_nop 5
	v_add_u32_e32 v8, 0x184, v82
	v_bfe_u32 v17, v8, 3, 2
	v_lshlrev_b32_e32 v16, 7, v8
	v_bitop3_b32 v8, v17, v77, v89 bitop3:0x36
	v_lshlrev_b32_e32 v8, 4, v8
	v_add3_u32 v8, 0, v8, v16
	ds_read_b128 v[8:11], v8
	v_bitop3_b32 v17, v17, v83, v89 bitop3:0x36
	v_lshlrev_b32_e32 v17, 4, v17
	v_add3_u32 v16, 0, v17, v16
	ds_read_b128 v[16:19], v16
	s_waitcnt lgkmcnt(1)
	v_mfma_f32_16x16x32_bf16 v[8:11], v[8:11], v[4:7], 0
	s_waitcnt lgkmcnt(0)
	v_mfma_f32_16x16x32_bf16 v[16:19], v[16:19], v[0:3], v[8:11]
	v_mfma_f32_16x16x32_bf16 v[8:11], v[12:15], v[4:7], 0
	v_add_u32_e32 v12, 0x1c4, v82
	v_bfe_u32 v98, v12, 3, 2
	v_lshlrev_b32_e32 v82, 7, v12
	v_bitop3_b32 v12, v98, v77, v89 bitop3:0x36
	v_lshlrev_b32_e32 v12, 4, v12
	v_add3_u32 v12, 0, v12, v82
	ds_read_b128 v[94:97], v12
	v_mfma_f32_16x16x32_bf16 v[12:15], v[90:93], v[0:3], v[8:11]
	s_nop 2
	v_bitop3_b32 v8, v98, v83, v89 bitop3:0x36
	v_lshlrev_b32_e32 v8, 4, v8
	v_add3_u32 v8, 0, v8, v82
	ds_read_b128 v[8:11], v8
	s_waitcnt lgkmcnt(1)
	v_mfma_f32_16x16x32_bf16 v[90:93], v[94:97], v[4:7], 0
	v_or_b32_e32 v97, s74, v87
	v_med3_u32 v82, v97, 8, 56
	v_add_u32_e32 v98, 8, v82
	s_waitcnt lgkmcnt(0)
	v_mfma_f32_16x16x32_bf16 v[8:11], v[8:11], v[0:3], v[90:93]
	s_nop 2
	v_add_u32_e32 v93, -8, v82
	v_sub_u32_e32 v82, v99, v97
	v_med3_i32 v82, v82, -15, 15
	v_cmp_ge_i32_e32 vcc, v99, v93
	v_cmp_lt_i32_e64 s[0:1], v99, v98
	v_add_u32_e32 v82, 15, v82
	s_and_b64 vcc, vcc, s[0:1]
	v_cndmask_b32_e32 v89, -1, v82, vcc
	v_cmp_lt_i32_e32 vcc, -1, v89
	v_mov_b32_e32 v82, 0xf149f2ca
	v_lshl_add_u32 v72, v89, 2, v100
	v_mov_b32_e32 v89, 0xf149f2ca
	s_and_saveexec_b64 s[0:1], vcc
	s_nop 0
	ds_read_b32 v91, v72 offset:372
	v_mov_b32_e32 v90, v68
	s_waitcnt lgkmcnt(0)
	v_pk_mul_f32 v[90:91], v[90:91], s[70:71]
	s_nop 0
	v_add_f32_e32 v89, v90, v91
.LBB0_935:
	s_or_b64 exec, exec, s[0:1]
	v_or_b32_e32 v68, 1, v99
	v_sub_u32_e32 v90, v68, v97
	v_med3_i32 v90, v90, -15, 15
	v_cmp_ge_i32_e64 s[0:1], v68, v93
	v_cmp_lt_i32_e64 s[4:5], v68, v98
	v_add_u32_e32 v68, 15, v90
	s_and_b64 s[0:1], s[0:1], s[4:5]
	v_cndmask_b32_e64 v68, -1, v68, s[0:1]
	v_cmp_lt_i32_e64 s[4:5], -1, v68
	v_lshl_add_u32 v90, v68, 2, v100
	s_and_saveexec_b64 s[0:1], s[4:5]
	s_nop 0
	ds_read_b32 v95, v90 offset:372
	v_mov_b32_e32 v94, v69
	s_waitcnt lgkmcnt(0)
	v_pk_mul_f32 v[68:69], v[94:95], s[70:71]
	s_nop 0
	v_add_f32_e32 v82, v68, v69
.LBB0_937:
	s_or_b64 exec, exec, s[0:1]
	v_or_b32_e32 v68, 2, v99
	v_sub_u32_e32 v69, v68, v97
	v_med3_i32 v69, v69, -15, 15
	v_cmp_ge_i32_e64 s[0:1], v68, v93
	v_cmp_lt_i32_e64 s[6:7], v68, v98
	v_add_u32_e32 v68, 15, v69
	s_and_b64 s[0:1], s[0:1], s[6:7]
	v_cndmask_b32_e64 v69, -1, v68, s[0:1]
	v_cmp_lt_i32_e64 s[6:7], -1, v69
	v_mov_b32_e32 v68, 0xf149f2ca
	v_lshl_add_u32 v91, v69, 2, v100
	v_mov_b32_e32 v69, 0xf149f2ca
	s_and_saveexec_b64 s[0:1], s[6:7]
	s_nop 0
	ds_read_b32 v95, v91 offset:372
	v_mov_b32_e32 v94, v70
	s_waitcnt lgkmcnt(0)
	v_pk_mul_f32 v[94:95], v[94:95], s[70:71]
	s_nop 0
	v_add_f32_e32 v69, v94, v95
.LBB0_939:
	s_or_b64 exec, exec, s[0:1]
	v_or_b32_e32 v70, 3, v99
	v_sub_u32_e32 v92, v70, v97
	v_med3_i32 v92, v92, -15, 15
	v_cmp_ge_i32_e64 s[0:1], v70, v93
	v_cmp_lt_i32_e64 s[8:9], v70, v98
	v_add_u32_e32 v70, 15, v92
	s_and_b64 s[0:1], s[0:1], s[8:9]
	v_cndmask_b32_e64 v70, -1, v70, s[0:1]
	v_cmp_lt_i32_e64 s[8:9], -1, v70
	v_lshl_add_u32 v92, v70, 2, v100
	s_and_saveexec_b64 s[0:1], s[8:9]
	s_nop 0
	ds_read_b32 v95, v92 offset:372
	v_mov_b32_e32 v94, v71
	s_waitcnt lgkmcnt(0)
	v_pk_mul_f32 v[70:71], v[94:95], s[70:71]
	s_nop 0
	v_add_f32_e32 v68, v70, v71
.LBB0_941:
	s_or_b64 exec, exec, s[0:1]
	v_or_b32_e32 v70, 4, v99
	v_sub_u32_e32 v71, v70, v97
	v_med3_i32 v71, v71, -15, 15
	v_cmp_ge_i32_e64 s[0:1], v70, v93
	v_cmp_lt_i32_e64 s[10:11], v70, v98
	v_add_u32_e32 v70, 15, v71
	s_and_b64 s[0:1], s[0:1], s[10:11]
	v_cndmask_b32_e64 v71, -1, v70, s[0:1]
	v_cmp_lt_i32_e64 s[10:11], -1, v71
	v_mov_b32_e32 v70, 0xf149f2ca
	v_lshl_add_u32 v94, v71, 2, v100
	v_mov_b32_e32 v71, 0xf149f2ca
	s_and_saveexec_b64 s[0:1], s[10:11]
	s_nop 0
	ds_read_b32 v103, v94 offset:372
	v_mov_b32_e32 v102, v64
	s_waitcnt lgkmcnt(0)
	v_pk_mul_f32 v[102:103], v[102:103], s[70:71]
	s_nop 0
	v_add_f32_e32 v71, v102, v103
.LBB0_943:
	s_or_b64 exec, exec, s[0:1]
	v_or_b32_e32 v64, 5, v99
	v_sub_u32_e32 v95, v64, v97
	v_med3_i32 v95, v95, -15, 15
	v_cmp_ge_i32_e64 s[0:1], v64, v93
	v_cmp_lt_i32_e64 s[12:13], v64, v98
	v_add_u32_e32 v64, 15, v95
	s_and_b64 s[0:1], s[0:1], s[12:13]
	v_cndmask_b32_e64 v64, -1, v64, s[0:1]
	v_cmp_lt_i32_e64 s[12:13], -1, v64
	v_lshl_add_u32 v95, v64, 2, v100
	s_and_saveexec_b64 s[0:1], s[12:13]
	s_nop 0
	ds_read_b32 v103, v95 offset:372
	v_mov_b32_e32 v102, v65
	s_waitcnt lgkmcnt(0)
	v_pk_mul_f32 v[64:65], v[102:103], s[70:71]
	s_nop 0
	v_add_f32_e32 v70, v64, v65
.LBB0_945:
	s_or_b64 exec, exec, s[0:1]
	v_or_b32_e32 v64, 6, v99
	v_sub_u32_e32 v65, v64, v97
	v_med3_i32 v65, v65, -15, 15
	v_cmp_ge_i32_e64 s[0:1], v64, v93
	v_cmp_lt_i32_e64 s[14:15], v64, v98
	v_add_u32_e32 v64, 15, v65
	s_and_b64 s[0:1], s[0:1], s[14:15]
	v_cndmask_b32_e64 v65, -1, v64, s[0:1]
	v_cmp_lt_i32_e64 s[14:15], -1, v65
	v_mov_b32_e32 v64, 0xf149f2ca
	v_lshl_add_u32 v96, v65, 2, v100
	v_mov_b32_e32 v65, 0xf149f2ca
	s_and_saveexec_b64 s[0:1], s[14:15]
	s_nop 0
	ds_read_b32 v103, v96 offset:372
	v_mov_b32_e32 v102, v66
	s_waitcnt lgkmcnt(0)
	v_pk_mul_f32 v[102:103], v[102:103], s[70:71]
	s_nop 0
	v_add_f32_e32 v65, v102, v103
.LBB0_947:
	s_or_b64 exec, exec, s[0:1]
	v_or_b32_e32 v66, 7, v99
	v_sub_u32_e32 v97, v66, v97
	v_med3_i32 v97, v97, -15, 15
	v_cmp_ge_i32_e64 s[0:1], v66, v93
	v_cmp_lt_i32_e64 s[16:17], v66, v98
	v_add_u32_e32 v66, 15, v97
	s_and_b64 s[0:1], s[0:1], s[16:17]
	v_cndmask_b32_e64 v66, -1, v66, s[0:1]
	v_cmp_lt_i32_e64 s[16:17], -1, v66
	v_lshl_add_u32 v97, v66, 2, v100
	s_and_saveexec_b64 s[0:1], s[16:17]
	s_nop 0
	ds_read_b32 v99, v97 offset:372
	v_mov_b32_e32 v98, v67
	s_waitcnt lgkmcnt(0)
	v_pk_mul_f32 v[66:67], v[98:99], s[70:71]
	s_nop 0
	v_add_f32_e32 v64, v66, v67
.LBB0_949:
	s_or_b64 exec, exec, s[0:1]
	v_mov_b32_e32 v66, 0xf149f2ca
	v_mov_b32_e32 v67, 0xf149f2ca
	s_and_saveexec_b64 s[0:1], vcc
	s_nop 0
	ds_read_b32 v99, v72 offset:496
	v_mov_b32_e32 v98, v60
	s_waitcnt lgkmcnt(0)
	v_pk_mul_f32 v[98:99], v[98:99], s[70:71]
	s_nop 0
	v_add_f32_e32 v67, v98, v99
.LBB0_951:
	s_or_b64 exec, exec, s[0:1]
	s_and_saveexec_b64 s[0:1], s[4:5]
	s_nop 0
	ds_read_b32 v99, v90 offset:496
	v_mov_b32_e32 v98, v61
	s_waitcnt lgkmcnt(0)
	v_pk_mul_f32 v[60:61], v[98:99], s[70:71]
	s_nop 0
	v_add_f32_e32 v66, v60, v61
.LBB0_953:
	s_or_b64 exec, exec, s[0:1]
	v_mov_b32_e32 v60, 0xf149f2ca
	v_mov_b32_e32 v61, 0xf149f2ca
	s_and_saveexec_b64 s[0:1], s[6:7]
	s_nop 0
	ds_read_b32 v99, v91 offset:496
	v_mov_b32_e32 v98, v62
	s_waitcnt lgkmcnt(0)
	v_pk_mul_f32 v[98:99], v[98:99], s[70:71]
	s_nop 0
	v_add_f32_e32 v61, v98, v99
.LBB0_955:
	s_or_b64 exec, exec, s[0:1]
	s_and_saveexec_b64 s[0:1], s[8:9]
	s_nop 0
	ds_read_b32 v99, v92 offset:496
	v_mov_b32_e32 v98, v63
	s_waitcnt lgkmcnt(0)
	v_pk_mul_f32 v[62:63], v[98:99], s[70:71]
	s_nop 0
	v_add_f32_e32 v60, v62, v63
.LBB0_957:
	s_or_b64 exec, exec, s[0:1]
	v_mov_b32_e32 v62, 0xf149f2ca
	v_mov_b32_e32 v63, 0xf149f2ca
	s_and_saveexec_b64 s[0:1], s[10:11]
	s_nop 0
	ds_read_b32 v99, v94 offset:496
	v_mov_b32_e32 v98, v56
	s_waitcnt lgkmcnt(0)
	v_pk_mul_f32 v[98:99], v[98:99], s[70:71]
	s_nop 0
	v_add_f32_e32 v63, v98, v99
.LBB0_959:
	s_or_b64 exec, exec, s[0:1]
	s_and_saveexec_b64 s[0:1], s[12:13]
	s_nop 0
	ds_read_b32 v99, v95 offset:496
	v_mov_b32_e32 v98, v57
	s_waitcnt lgkmcnt(0)
	v_pk_mul_f32 v[56:57], v[98:99], s[70:71]
	s_nop 0
	v_add_f32_e32 v62, v56, v57
.LBB0_961:
	s_or_b64 exec, exec, s[0:1]
	v_mov_b32_e32 v57, 0xf149f2ca
	v_mov_b32_e32 v93, 0xf149f2ca
	s_and_saveexec_b64 s[0:1], s[14:15]
	s_nop 0
	ds_read_b32 v99, v96 offset:496
	v_mov_b32_e32 v98, v58
	s_waitcnt lgkmcnt(0)
	v_pk_mul_f32 v[98:99], v[98:99], s[70:71]
	s_nop 0
	v_add_f32_e32 v93, v98, v99
.LBB0_963:
	s_or_b64 exec, exec, s[0:1]
	s_and_saveexec_b64 s[0:1], s[16:17]
	s_nop 0
	ds_read_b32 v57, v97 offset:496
	v_mov_b32_e32 v56, v59
	s_waitcnt lgkmcnt(0)
	v_pk_mul_f32 v[56:57], v[56:57], s[70:71]
	s_nop 0
	v_add_f32_e32 v57, v56, v57
.LBB0_965:
	s_or_b64 exec, exec, s[0:1]
	v_mov_b32_e32 v56, 0xf149f2ca
	v_mov_b32_e32 v58, 0xf149f2ca
	s_and_saveexec_b64 s[0:1], vcc
	s_nop 0
	ds_read_b32 v59, v72 offset:620
	v_mov_b32_e32 v58, v52
	s_waitcnt lgkmcnt(0)
	v_pk_mul_f32 v[58:59], v[58:59], s[70:71]
	s_nop 0
	v_add_f32_e32 v58, v58, v59
.LBB0_967:
	s_or_b64 exec, exec, s[0:1]
	s_and_saveexec_b64 s[0:1], s[4:5]
	s_nop 0
	ds_read_b32 v99, v90 offset:620
	v_mov_b32_e32 v98, v53
	s_waitcnt lgkmcnt(0)
	v_pk_mul_f32 v[52:53], v[98:99], s[70:71]
	s_nop 0
	v_add_f32_e32 v56, v52, v53
.LBB0_969:
	s_or_b64 exec, exec, s[0:1]
	v_mov_b32_e32 v52, 0xf149f2ca
	v_mov_b32_e32 v53, 0xf149f2ca
	s_and_saveexec_b64 s[0:1], s[6:7]
	s_nop 0
	ds_read_b32 v99, v91 offset:620
	v_mov_b32_e32 v98, v54
	s_waitcnt lgkmcnt(0)
	v_pk_mul_f32 v[98:99], v[98:99], s[70:71]
	s_nop 0
	v_add_f32_e32 v53, v98, v99
.LBB0_971:
	s_or_b64 exec, exec, s[0:1]
	s_and_saveexec_b64 s[0:1], s[8:9]
	s_nop 0
	ds_read_b32 v99, v92 offset:620
	v_mov_b32_e32 v98, v55
	s_waitcnt lgkmcnt(0)
	v_pk_mul_f32 v[54:55], v[98:99], s[70:71]
	s_nop 0
	v_add_f32_e32 v52, v54, v55
.LBB0_973:
	s_or_b64 exec, exec, s[0:1]
	v_mov_b32_e32 v54, 0xf149f2ca
	v_mov_b32_e32 v55, 0xf149f2ca
	s_and_saveexec_b64 s[0:1], s[10:11]
	s_nop 0
	ds_read_b32 v99, v94 offset:620
	v_mov_b32_e32 v98, v48
	s_waitcnt lgkmcnt(0)
	v_pk_mul_f32 v[98:99], v[98:99], s[70:71]
	s_nop 0
	v_add_f32_e32 v55, v98, v99
.LBB0_975:
	s_or_b64 exec, exec, s[0:1]
	s_and_saveexec_b64 s[0:1], s[12:13]
	s_nop 0
	ds_read_b32 v99, v95 offset:620
	v_mov_b32_e32 v98, v49
	s_waitcnt lgkmcnt(0)
	v_pk_mul_f32 v[48:49], v[98:99], s[70:71]
	s_nop 0
	v_add_f32_e32 v54, v48, v49
.LBB0_977:
	s_or_b64 exec, exec, s[0:1]
	v_mov_b32_e32 v49, 0xf149f2ca
	v_mov_b32_e32 v59, 0xf149f2ca
	s_and_saveexec_b64 s[0:1], s[14:15]
	s_nop 0
	ds_read_b32 v99, v96 offset:620
	v_mov_b32_e32 v98, v50
	s_waitcnt lgkmcnt(0)
	v_pk_mul_f32 v[98:99], v[98:99], s[70:71]
	s_nop 0
	v_add_f32_e32 v59, v98, v99
.LBB0_979:
	s_or_b64 exec, exec, s[0:1]
	s_and_saveexec_b64 s[0:1], s[16:17]
	s_nop 0
	ds_read_b32 v49, v97 offset:620
	v_mov_b32_e32 v48, v51
	s_waitcnt lgkmcnt(0)
	v_pk_mul_f32 v[48:49], v[48:49], s[70:71]
	s_nop 0
	v_add_f32_e32 v49, v48, v49
.LBB0_981:
	s_or_b64 exec, exec, s[0:1]
	v_mov_b32_e32 v48, 0xf149f2ca
	v_mov_b32_e32 v50, 0xf149f2ca
	s_and_saveexec_b64 s[0:1], vcc
	s_nop 0
	ds_read_b32 v51, v72 offset:744
	v_mov_b32_e32 v50, v44
	s_waitcnt lgkmcnt(0)
	v_pk_mul_f32 v[50:51], v[50:51], s[70:71]
	s_nop 0
	v_add_f32_e32 v50, v50, v51
.LBB0_983:
	s_or_b64 exec, exec, s[0:1]
	s_and_saveexec_b64 s[0:1], s[4:5]
	s_nop 0
	ds_read_b32 v99, v90 offset:744
	v_mov_b32_e32 v98, v45
	s_waitcnt lgkmcnt(0)
	v_pk_mul_f32 v[44:45], v[98:99], s[70:71]
	s_nop 0
	v_add_f32_e32 v48, v44, v45
.LBB0_985:
	s_or_b64 exec, exec, s[0:1]
	v_mov_b32_e32 v44, 0xf149f2ca
	v_mov_b32_e32 v45, 0xf149f2ca
	s_and_saveexec_b64 s[0:1], s[6:7]
	s_nop 0
	ds_read_b32 v99, v91 offset:744
	v_mov_b32_e32 v98, v46
	s_waitcnt lgkmcnt(0)
	v_pk_mul_f32 v[98:99], v[98:99], s[70:71]
	s_nop 0
	v_add_f32_e32 v45, v98, v99
.LBB0_987:
	s_or_b64 exec, exec, s[0:1]
	s_and_saveexec_b64 s[0:1], s[8:9]
	s_nop 0
	ds_read_b32 v99, v92 offset:744
	v_mov_b32_e32 v98, v47
	s_waitcnt lgkmcnt(0)
	v_pk_mul_f32 v[46:47], v[98:99], s[70:71]
	s_nop 0
	v_add_f32_e32 v44, v46, v47
.LBB0_989:
	s_or_b64 exec, exec, s[0:1]
	v_mov_b32_e32 v46, 0xf149f2ca
	v_mov_b32_e32 v47, 0xf149f2ca
	s_and_saveexec_b64 s[0:1], s[10:11]
	s_nop 0
	ds_read_b32 v99, v94 offset:744
	v_mov_b32_e32 v98, v40
	s_waitcnt lgkmcnt(0)
	v_pk_mul_f32 v[98:99], v[98:99], s[70:71]
	s_nop 0
	v_add_f32_e32 v47, v98, v99
.LBB0_991:
	s_or_b64 exec, exec, s[0:1]
	s_and_saveexec_b64 s[0:1], s[12:13]
	s_nop 0
	ds_read_b32 v99, v95 offset:744
	v_mov_b32_e32 v98, v41
	s_waitcnt lgkmcnt(0)
	v_pk_mul_f32 v[40:41], v[98:99], s[70:71]
	s_nop 0
	v_add_f32_e32 v46, v40, v41
.LBB0_993:
	s_or_b64 exec, exec, s[0:1]
	v_mov_b32_e32 v41, 0xf149f2ca
	v_mov_b32_e32 v51, 0xf149f2ca
	s_and_saveexec_b64 s[0:1], s[14:15]
	s_nop 0
	ds_read_b32 v99, v96 offset:744
	v_mov_b32_e32 v98, v42
	s_waitcnt lgkmcnt(0)
	v_pk_mul_f32 v[98:99], v[98:99], s[70:71]
	s_nop 0
	v_add_f32_e32 v51, v98, v99
.LBB0_995:
	s_or_b64 exec, exec, s[0:1]
	s_and_saveexec_b64 s[0:1], s[16:17]
	s_nop 0
	ds_read_b32 v41, v97 offset:744
	v_mov_b32_e32 v40, v43
	s_waitcnt lgkmcnt(0)
	v_pk_mul_f32 v[40:41], v[40:41], s[70:71]
	s_nop 0
	v_add_f32_e32 v41, v40, v41
.LBB0_997:
	s_or_b64 exec, exec, s[0:1]
	v_mov_b32_e32 v40, 0xf149f2ca
	v_mov_b32_e32 v42, 0xf149f2ca
	s_and_saveexec_b64 s[0:1], vcc
	s_nop 0
	ds_read_b32 v43, v72 offset:868
	v_mov_b32_e32 v42, v36
	s_waitcnt lgkmcnt(0)
	v_pk_mul_f32 v[42:43], v[42:43], s[70:71]
	s_nop 0
	v_add_f32_e32 v42, v42, v43
.LBB0_999:
	s_or_b64 exec, exec, s[0:1]
	s_and_saveexec_b64 s[0:1], s[4:5]
	s_nop 0
	ds_read_b32 v99, v90 offset:868
	v_mov_b32_e32 v98, v37
	s_waitcnt lgkmcnt(0)
	v_pk_mul_f32 v[36:37], v[98:99], s[70:71]
	s_nop 0
	v_add_f32_e32 v40, v36, v37
.LBB0_1001:
	s_or_b64 exec, exec, s[0:1]
	v_mov_b32_e32 v36, 0xf149f2ca
	v_mov_b32_e32 v37, 0xf149f2ca
	s_and_saveexec_b64 s[0:1], s[6:7]
	s_nop 0
	ds_read_b32 v99, v91 offset:868
	v_mov_b32_e32 v98, v38
	s_waitcnt lgkmcnt(0)
	v_pk_mul_f32 v[98:99], v[98:99], s[70:71]
	s_nop 0
	v_add_f32_e32 v37, v98, v99
.LBB0_1003:
	s_or_b64 exec, exec, s[0:1]
	s_and_saveexec_b64 s[0:1], s[8:9]
	s_nop 0
	ds_read_b32 v99, v92 offset:868
	v_mov_b32_e32 v98, v39
	s_waitcnt lgkmcnt(0)
	v_pk_mul_f32 v[38:39], v[98:99], s[70:71]
	s_nop 0
	v_add_f32_e32 v36, v38, v39
.LBB0_1005:
	s_or_b64 exec, exec, s[0:1]
	v_mov_b32_e32 v38, 0xf149f2ca
	v_mov_b32_e32 v39, 0xf149f2ca
	s_and_saveexec_b64 s[0:1], s[10:11]
	s_nop 0
	ds_read_b32 v99, v94 offset:868
	v_mov_b32_e32 v98, v32
	s_waitcnt lgkmcnt(0)
	v_pk_mul_f32 v[98:99], v[98:99], s[70:71]
	s_nop 0
	v_add_f32_e32 v39, v98, v99
.LBB0_1007:
	s_or_b64 exec, exec, s[0:1]
	s_and_saveexec_b64 s[0:1], s[12:13]
	s_nop 0
	ds_read_b32 v99, v95 offset:868
	v_mov_b32_e32 v98, v33
	s_waitcnt lgkmcnt(0)
	v_pk_mul_f32 v[32:33], v[98:99], s[70:71]
	s_nop 0
	v_add_f32_e32 v38, v32, v33
.LBB0_1009:
	s_or_b64 exec, exec, s[0:1]
	v_mov_b32_e32 v33, 0xf149f2ca
	v_mov_b32_e32 v43, 0xf149f2ca
	s_and_saveexec_b64 s[0:1], s[14:15]
	s_nop 0
	ds_read_b32 v99, v96 offset:868
	v_mov_b32_e32 v98, v34
	s_waitcnt lgkmcnt(0)
	v_pk_mul_f32 v[98:99], v[98:99], s[70:71]
	s_nop 0
	v_add_f32_e32 v43, v98, v99
.LBB0_1011:
	s_or_b64 exec, exec, s[0:1]
	s_and_saveexec_b64 s[0:1], s[16:17]
	s_nop 0
	ds_read_b32 v33, v97 offset:868
	v_mov_b32_e32 v32, v35
	s_waitcnt lgkmcnt(0)
	v_pk_mul_f32 v[32:33], v[32:33], s[70:71]
	s_nop 0
	v_add_f32_e32 v33, v32, v33
.LBB0_1013:
	s_or_b64 exec, exec, s[0:1]
	v_mov_b32_e32 v32, 0xf149f2ca
	v_mov_b32_e32 v34, 0xf149f2ca
	s_and_saveexec_b64 s[0:1], vcc
	s_nop 0
	ds_read_b32 v35, v72 offset:992
	v_mov_b32_e32 v34, v28
	s_waitcnt lgkmcnt(0)
	v_pk_mul_f32 v[34:35], v[34:35], s[70:71]
	s_nop 0
	v_add_f32_e32 v34, v34, v35
.LBB0_1015:
	s_or_b64 exec, exec, s[0:1]
	s_and_saveexec_b64 s[0:1], s[4:5]
	s_nop 0
	ds_read_b32 v99, v90 offset:992
	v_mov_b32_e32 v98, v29
	s_waitcnt lgkmcnt(0)
	v_pk_mul_f32 v[28:29], v[98:99], s[70:71]
	s_nop 0
	v_add_f32_e32 v32, v28, v29
.LBB0_1017:
	s_or_b64 exec, exec, s[0:1]
	v_mov_b32_e32 v28, 0xf149f2ca
	v_mov_b32_e32 v29, 0xf149f2ca
	s_and_saveexec_b64 s[0:1], s[6:7]
	s_nop 0
	ds_read_b32 v99, v91 offset:992
	v_mov_b32_e32 v98, v30
	s_waitcnt lgkmcnt(0)
	v_pk_mul_f32 v[98:99], v[98:99], s[70:71]
	s_nop 0
	v_add_f32_e32 v29, v98, v99
.LBB0_1019:
	s_or_b64 exec, exec, s[0:1]
	s_and_saveexec_b64 s[0:1], s[8:9]
	s_nop 0
	ds_read_b32 v99, v92 offset:992
	v_mov_b32_e32 v98, v31
	s_waitcnt lgkmcnt(0)
	v_pk_mul_f32 v[30:31], v[98:99], s[70:71]
	s_nop 0
	v_add_f32_e32 v28, v30, v31
.LBB0_1021:
	s_or_b64 exec, exec, s[0:1]
	v_mov_b32_e32 v30, 0xf149f2ca
	v_mov_b32_e32 v31, 0xf149f2ca
	s_and_saveexec_b64 s[0:1], s[10:11]
	s_nop 0
	ds_read_b32 v99, v94 offset:992
	v_mov_b32_e32 v98, v24
	s_waitcnt lgkmcnt(0)
	v_pk_mul_f32 v[98:99], v[98:99], s[70:71]
	s_nop 0
	v_add_f32_e32 v31, v98, v99
.LBB0_1023:
	s_or_b64 exec, exec, s[0:1]
	s_and_saveexec_b64 s[0:1], s[12:13]
	s_nop 0
	ds_read_b32 v99, v95 offset:992
	v_mov_b32_e32 v98, v25
	s_waitcnt lgkmcnt(0)
	v_pk_mul_f32 v[24:25], v[98:99], s[70:71]
	s_nop 0
	v_add_f32_e32 v30, v24, v25
.LBB0_1025:
	s_or_b64 exec, exec, s[0:1]
	v_mov_b32_e32 v25, 0xf149f2ca
	v_mov_b32_e32 v35, 0xf149f2ca
	s_and_saveexec_b64 s[0:1], s[14:15]
	s_nop 0
	ds_read_b32 v99, v96 offset:992
	v_mov_b32_e32 v98, v26
	s_waitcnt lgkmcnt(0)
	v_pk_mul_f32 v[98:99], v[98:99], s[70:71]
	s_nop 0
	v_add_f32_e32 v35, v98, v99
.LBB0_1027:
	s_or_b64 exec, exec, s[0:1]
	s_and_saveexec_b64 s[0:1], s[16:17]
	s_nop 0
	ds_read_b32 v25, v97 offset:992
	v_mov_b32_e32 v24, v27
	s_waitcnt lgkmcnt(0)
	v_pk_mul_f32 v[24:25], v[24:25], s[70:71]
	s_nop 0
	v_add_f32_e32 v25, v24, v25
.LBB0_1029:
	s_or_b64 exec, exec, s[0:1]
	v_mov_b32_e32 v24, 0xf149f2ca
	v_mov_b32_e32 v26, 0xf149f2ca
	s_and_saveexec_b64 s[0:1], vcc
	s_nop 0
	ds_read_b32 v27, v72 offset:1116
	v_mov_b32_e32 v26, v20
	s_waitcnt lgkmcnt(0)
	v_pk_mul_f32 v[26:27], v[26:27], s[70:71]
	s_nop 0
	v_add_f32_e32 v26, v26, v27
.LBB0_1031:
	s_or_b64 exec, exec, s[0:1]
	s_and_saveexec_b64 s[0:1], s[4:5]
	s_nop 0
	ds_read_b32 v99, v90 offset:1116
	v_mov_b32_e32 v98, v21
	s_waitcnt lgkmcnt(0)
	v_pk_mul_f32 v[20:21], v[98:99], s[70:71]
	s_nop 0
	v_add_f32_e32 v24, v20, v21
.LBB0_1033:
	s_or_b64 exec, exec, s[0:1]
	v_mov_b32_e32 v20, 0xf149f2ca
	v_mov_b32_e32 v21, 0xf149f2ca
	s_and_saveexec_b64 s[0:1], s[6:7]
	s_nop 0
	ds_read_b32 v99, v91 offset:1116
	v_mov_b32_e32 v98, v22
	s_waitcnt lgkmcnt(0)
	v_pk_mul_f32 v[98:99], v[98:99], s[70:71]
	s_nop 0
	v_add_f32_e32 v21, v98, v99
.LBB0_1035:
	s_or_b64 exec, exec, s[0:1]
	s_and_saveexec_b64 s[0:1], s[8:9]
	s_nop 0
	ds_read_b32 v99, v92 offset:1116
	v_mov_b32_e32 v98, v23
	s_waitcnt lgkmcnt(0)
	v_pk_mul_f32 v[22:23], v[98:99], s[70:71]
	s_nop 0
	v_add_f32_e32 v20, v22, v23
.LBB0_1037:
	s_or_b64 exec, exec, s[0:1]
	v_mov_b32_e32 v22, 0xf149f2ca
	v_mov_b32_e32 v23, 0xf149f2ca
	s_and_saveexec_b64 s[0:1], s[10:11]
	s_nop 0
	ds_read_b32 v99, v94 offset:1116
	v_mov_b32_e32 v98, v16
	s_waitcnt lgkmcnt(0)
	v_pk_mul_f32 v[98:99], v[98:99], s[70:71]
	s_nop 0
	v_add_f32_e32 v23, v98, v99
.LBB0_1039:
	s_or_b64 exec, exec, s[0:1]
	s_and_saveexec_b64 s[0:1], s[12:13]
	s_nop 0
	ds_read_b32 v99, v95 offset:1116
	v_mov_b32_e32 v98, v17
	s_waitcnt lgkmcnt(0)
	v_pk_mul_f32 v[16:17], v[98:99], s[70:71]
	s_nop 0
	v_add_f32_e32 v22, v16, v17
.LBB0_1041:
	s_or_b64 exec, exec, s[0:1]
	v_mov_b32_e32 v27, 0xf149f2ca
	v_mov_b32_e32 v98, 0xf149f2ca
	s_and_saveexec_b64 s[0:1], s[14:15]
	s_nop 0
	ds_read_b32 v17, v96 offset:1116
	v_mov_b32_e32 v16, v18
	s_waitcnt lgkmcnt(0)
	v_pk_mul_f32 v[16:17], v[16:17], s[70:71]
	s_nop 0
	v_add_f32_e32 v98, v16, v17
.LBB0_1043:
	s_or_b64 exec, exec, s[0:1]
	s_and_saveexec_b64 s[0:1], s[16:17]
	s_nop 0
	ds_read_b32 v17, v97 offset:1116
	v_mov_b32_e32 v16, v19
	s_waitcnt lgkmcnt(0)
	v_pk_mul_f32 v[16:17], v[16:17], s[70:71]
	s_nop 0
	v_add_f32_e32 v27, v16, v17
.LBB0_1045:
	s_or_b64 exec, exec, s[0:1]
	v_mov_b32_e32 v16, 0xf149f2ca
	v_mov_b32_e32 v17, 0xf149f2ca
	s_and_saveexec_b64 s[0:1], vcc
	s_nop 0
	ds_read_b32 v19, v72 offset:1240
	v_mov_b32_e32 v18, v12
	s_waitcnt lgkmcnt(0)
	v_pk_mul_f32 v[18:19], v[18:19], s[70:71]
	s_nop 0
	v_add_f32_e32 v17, v18, v19
.LBB0_1047:
	s_or_b64 exec, exec, s[0:1]
	s_and_saveexec_b64 s[0:1], s[4:5]
	s_nop 0
	ds_read_b32 v19, v90 offset:1240
	v_mov_b32_e32 v18, v13
	s_waitcnt lgkmcnt(0)
	v_pk_mul_f32 v[12:13], v[18:19], s[70:71]
	s_nop 0
	v_add_f32_e32 v16, v12, v13
.LBB0_1049:
	s_or_b64 exec, exec, s[0:1]
	v_mov_b32_e32 v12, 0xf149f2ca
	v_mov_b32_e32 v13, 0xf149f2ca
	s_and_saveexec_b64 s[0:1], s[6:7]
	s_nop 0
	ds_read_b32 v19, v91 offset:1240
	v_mov_b32_e32 v18, v14
	s_waitcnt lgkmcnt(0)
	v_pk_mul_f32 v[18:19], v[18:19], s[70:71]
	s_nop 0
	v_add_f32_e32 v13, v18, v19
.LBB0_1051:
	s_or_b64 exec, exec, s[0:1]
	s_and_saveexec_b64 s[0:1], s[8:9]
	s_nop 0
	ds_read_b32 v19, v92 offset:1240
	v_mov_b32_e32 v18, v15
	s_waitcnt lgkmcnt(0)
	v_pk_mul_f32 v[14:15], v[18:19], s[70:71]
	s_nop 0
	v_add_f32_e32 v12, v14, v15
.LBB0_1053:
	s_or_b64 exec, exec, s[0:1]
	v_mov_b32_e32 v14, 0xf149f2ca
	v_mov_b32_e32 v15, 0xf149f2ca
	s_and_saveexec_b64 s[0:1], s[10:11]
	s_nop 0
	ds_read_b32 v19, v94 offset:1240
	v_mov_b32_e32 v18, v8
	s_waitcnt lgkmcnt(0)
	v_pk_mul_f32 v[18:19], v[18:19], s[70:71]
	s_nop 0
	v_add_f32_e32 v15, v18, v19
.LBB0_1055:
	s_or_b64 exec, exec, s[0:1]
	s_and_saveexec_b64 s[0:1], s[12:13]
	s_nop 0
	ds_read_b32 v19, v95 offset:1240
	v_mov_b32_e32 v18, v9
	s_waitcnt lgkmcnt(0)
	v_pk_mul_f32 v[8:9], v[18:19], s[70:71]
	s_nop 0
	v_add_f32_e32 v14, v8, v9
.LBB0_1057:
	s_or_b64 exec, exec, s[0:1]
	v_mov_b32_e32 v18, 0xf149f2ca
	v_mov_b32_e32 v19, 0xf149f2ca
	s_and_saveexec_b64 s[0:1], s[14:15]
	s_nop 0
	ds_read_b32 v9, v96 offset:1240
	v_mov_b32_e32 v8, v10
	s_waitcnt lgkmcnt(0)
	v_pk_mul_f32 v[8:9], v[8:9], s[70:71]
	s_nop 0
	v_add_f32_e32 v19, v8, v9
.LBB0_1059:
	s_or_b64 exec, exec, s[0:1]
	s_and_saveexec_b64 s[0:1], s[16:17]
	s_nop 0
	ds_read_b32 v9, v97 offset:1240
	v_mov_b32_e32 v8, v11
	s_waitcnt lgkmcnt(0)
	v_pk_mul_f32 v[8:9], v[8:9], s[70:71]
	s_nop 0
	v_add_f32_e32 v18, v8, v9

.LBB0_1090:
	v_med3_u32 v80, s8, 4, 28
	v_subrev_u32_e32 v8, s9, v80
	v_lshlrev_b32_e32 v8, 6, v8
	v_add_u32_e32 v78, v8, v84
	v_lshlrev_b32_e32 v8, 1, v79
	v_and_b32_e32 v72, 3, v85
	v_and_or_b32 v8, v8, 24, v72
	v_add_u32_e32 v87, v8, v78
	v_lshlrev_b32_e32 v8, 1, v87
	v_ashrrev_i32_e32 v81, 4, v85
	v_bfe_u32 v12, v87, 3, 2
	v_and_b32_e32 v96, 4, v8
	v_bitop3_b32 v8, v12, v81, v96 bitop3:0x36
	v_lshlrev_b32_e32 v20, 7, v87
	v_lshl_add_u32 v21, v8, 4, 0
	v_add_u32_e32 v88, v21, v20
	s_waitcnt vmcnt(0) lgkmcnt(0)
	s_waitcnt vmcnt(0) lgkmcnt(0)
	s_barrier
	ds_read_b128 v[8:11], v88
	v_add_u32_e32 v86, 4, v81
	v_bitop3_b32 v12, v12, v86, v96 bitop3:0x36
	v_lshl_add_u32 v28, v12, 4, 0
	v_add_u32_e32 v89, v28, v20
	ds_read_b128 v[12:15], v89
	ds_read_b128 v[16:19], v88 offset:8192
	s_waitcnt lgkmcnt(2)
	v_mfma_f32_16x16x32_bf16 v[8:11], v[8:11], v[4:7], 0
	v_or_b32_e32 v29, 0x200, v20
	v_add_u32_e32 v20, v21, v29
	ds_read_b128 v[20:23], v20
	ds_read_b128 v[24:27], v89 offset:8192
	s_waitcnt lgkmcnt(3)
	v_mfma_f32_16x16x32_bf16 v[68:71], v[12:15], v[0:3], v[8:11]
	s_mul_i32 s0, s42, 0x744
	s_add_i32 s34, s0, 0
	v_subrev_u32_e32 v80, s8, v80
	v_add_u32_e32 v8, v28, v29
	ds_read_b128 v[8:11], v8
	s_waitcnt lgkmcnt(2)
	v_mfma_f32_16x16x32_bf16 v[12:15], v[20:23], v[4:7], 0
	s_movk_i32 s0, 0x7c
	s_add_i32 s34, s34, 0x22100
	v_mul_lo_u32 v80, v80, s0
	s_waitcnt lgkmcnt(0)
	v_mfma_f32_16x16x32_bf16 v[64:67], v[8:11], v[0:3], v[12:15]
	v_mfma_f32_16x16x32_bf16 v[8:11], v[16:19], v[4:7], 0
	v_mfma_f32_16x16x32_bf16 v[60:63], v[24:27], v[0:3], v[8:11]
	s_nop 6
	v_add_u32_e32 v8, 0x44, v87
	v_bfe_u32 v13, v8, 3, 2
	v_lshlrev_b32_e32 v12, 7, v8
	v_bitop3_b32 v8, v13, v81, v96 bitop3:0x36
	v_lshlrev_b32_e32 v8, 4, v8
	v_add3_u32 v8, 0, v8, v12
	ds_read_b128 v[8:11], v8
	v_bitop3_b32 v13, v13, v86, v96 bitop3:0x36
	v_lshlrev_b32_e32 v13, 4, v13
	v_add3_u32 v12, 0, v13, v12
	ds_read_b128 v[12:15], v12
	s_waitcnt lgkmcnt(1)
	v_mfma_f32_16x16x32_bf16 v[8:11], v[8:11], v[4:7], 0
	s_waitcnt lgkmcnt(0)
	v_mfma_f32_16x16x32_bf16 v[56:59], v[12:15], v[0:3], v[8:11]
	s_nop 5
	ds_read_b128 v[8:11], v88 offset:16384
	ds_read_b128 v[12:15], v88 offset:24576
	ds_read_b128 v[16:19], v89 offset:16384
	ds_read_b128 v[20:23], v89 offset:24576
	s_waitcnt lgkmcnt(3)
	v_mfma_f32_16x16x32_bf16 v[8:11], v[8:11], v[4:7], 0
	s_waitcnt lgkmcnt(1)
	v_mfma_f32_16x16x32_bf16 v[52:55], v[16:19], v[0:3], v[8:11]
	s_nop 5
	v_add_u32_e32 v8, 0x84, v87
	v_bfe_u32 v17, v8, 3, 2
	v_lshlrev_b32_e32 v16, 7, v8
	v_bitop3_b32 v8, v17, v81, v96 bitop3:0x36
	v_lshlrev_b32_e32 v8, 4, v8
	v_add3_u32 v8, 0, v8, v16
	ds_read_b128 v[8:11], v8
	v_bitop3_b32 v17, v17, v86, v96 bitop3:0x36
	v_lshlrev_b32_e32 v17, 4, v17
	v_add3_u32 v16, 0, v17, v16
	ds_read_b128 v[16:19], v16
	s_waitcnt lgkmcnt(1)
	v_mfma_f32_16x16x32_bf16 v[8:11], v[8:11], v[4:7], 0
	s_waitcnt lgkmcnt(0)
	v_mfma_f32_16x16x32_bf16 v[48:51], v[16:19], v[0:3], v[8:11]
	v_mfma_f32_16x16x32_bf16 v[8:11], v[12:15], v[4:7], 0
	v_mfma_f32_16x16x32_bf16 v[44:47], v[20:23], v[0:3], v[8:11]
	s_nop 6
	v_add_u32_e32 v8, 0xc4, v87
	v_bfe_u32 v13, v8, 3, 2
	v_lshlrev_b32_e32 v12, 7, v8
	v_bitop3_b32 v8, v13, v81, v96 bitop3:0x36
	v_lshlrev_b32_e32 v8, 4, v8
	v_add3_u32 v8, 0, v8, v12
	ds_read_b128 v[8:11], v8
	v_bitop3_b32 v13, v13, v86, v96 bitop3:0x36
	v_lshlrev_b32_e32 v13, 4, v13
	v_add3_u32 v12, 0, v13, v12
	ds_read_b128 v[12:15], v12
	s_waitcnt lgkmcnt(1)
	v_mfma_f32_16x16x32_bf16 v[8:11], v[8:11], v[4:7], 0
	s_waitcnt lgkmcnt(0)
	v_mfma_f32_16x16x32_bf16 v[40:43], v[12:15], v[0:3], v[8:11]
	s_nop 5
	ds_read_b128 v[8:11], v88 offset:32768
	ds_read_b128 v[12:15], v88 offset:40960
	ds_read_b128 v[16:19], v89 offset:32768
	ds_read_b128 v[20:23], v89 offset:40960
	s_waitcnt lgkmcnt(3)
	v_mfma_f32_16x16x32_bf16 v[8:11], v[8:11], v[4:7], 0
	s_waitcnt lgkmcnt(1)
	v_mfma_f32_16x16x32_bf16 v[36:39], v[16:19], v[0:3], v[8:11]
	s_nop 5
	v_add_u32_e32 v8, 0x104, v87
	v_bfe_u32 v17, v8, 3, 2
	v_lshlrev_b32_e32 v16, 7, v8
	v_bitop3_b32 v8, v17, v81, v96 bitop3:0x36
	v_lshlrev_b32_e32 v8, 4, v8
	v_add3_u32 v8, 0, v8, v16
	ds_read_b128 v[8:11], v8
	v_bitop3_b32 v17, v17, v86, v96 bitop3:0x36
	v_lshlrev_b32_e32 v17, 4, v17
	v_add3_u32 v16, 0, v17, v16
	ds_read_b128 v[16:19], v16
	s_waitcnt lgkmcnt(1)
	v_mfma_f32_16x16x32_bf16 v[8:11], v[8:11], v[4:7], 0
	s_waitcnt lgkmcnt(0)
	v_mfma_f32_16x16x32_bf16 v[32:35], v[16:19], v[0:3], v[8:11]
	v_mfma_f32_16x16x32_bf16 v[8:11], v[12:15], v[4:7], 0
	v_mfma_f32_16x16x32_bf16 v[28:31], v[20:23], v[0:3], v[8:11]
	s_nop 6
	v_add_u32_e32 v8, 0x144, v87
	v_bfe_u32 v13, v8, 3, 2
	v_lshlrev_b32_e32 v12, 7, v8
	v_bitop3_b32 v8, v13, v81, v96 bitop3:0x36
	v_lshlrev_b32_e32 v8, 4, v8
	v_add3_u32 v8, 0, v8, v12
	ds_read_b128 v[8:11], v8
	v_bitop3_b32 v13, v13, v86, v96 bitop3:0x36
	v_lshlrev_b32_e32 v13, 4, v13
	v_add3_u32 v12, 0, v13, v12
	ds_read_b128 v[12:15], v12
	s_waitcnt lgkmcnt(1)
	v_mfma_f32_16x16x32_bf16 v[8:11], v[8:11], v[4:7], 0
	s_waitcnt lgkmcnt(0)
	v_mfma_f32_16x16x32_bf16 v[24:27], v[12:15], v[0:3], v[8:11]
	s_nop 5
	ds_read_b128 v[8:11], v88 offset:49152
	ds_read_b128 v[12:15], v88 offset:57344
	ds_read_b128 v[16:19], v89 offset:49152
	ds_read_b128 v[88:91], v89 offset:57344
	s_waitcnt lgkmcnt(3)
	v_mfma_f32_16x16x32_bf16 v[8:11], v[8:11], v[4:7], 0
	s_waitcnt lgkmcnt(1)
	v_mfma_f32_16x16x32_bf16 v[20:23], v[16:19], v[0:3], v[8:11]
	s_nop 5
	v_add_u32_e32 v8, 0x184, v87
	v_bfe_u32 v17, v8, 3, 2
	v_lshlrev_b32_e32 v16, 7, v8
	v_bitop3_b32 v8, v17, v81, v96 bitop3:0x36
	v_lshlrev_b32_e32 v8, 4, v8
	v_add3_u32 v8, 0, v8, v16
	ds_read_b128 v[8:11], v8
	v_bitop3_b32 v17, v17, v86, v96 bitop3:0x36
	v_lshlrev_b32_e32 v17, 4, v17
	v_add3_u32 v16, 0, v17, v16
	ds_read_b128 v[16:19], v16
	s_waitcnt lgkmcnt(1)
	v_mfma_f32_16x16x32_bf16 v[8:11], v[8:11], v[4:7], 0
	s_waitcnt lgkmcnt(0)
	v_mfma_f32_16x16x32_bf16 v[16:19], v[16:19], v[0:3], v[8:11]
	v_mfma_f32_16x16x32_bf16 v[8:11], v[12:15], v[4:7], 0
	v_add_u32_e32 v12, 0x1c4, v87
	v_lshlrev_b32_e32 v13, 7, v12
	v_bfe_u32 v12, v12, 3, 2
	v_bitop3_b32 v14, v12, v81, v96 bitop3:0x36
	v_lshlrev_b32_e32 v14, 4, v14
	v_add3_u32 v14, 0, v14, v13
	ds_read_b128 v[92:95], v14
	v_bitop3_b32 v12, v12, v86, v96 bitop3:0x36
	v_lshlrev_b32_e32 v12, 4, v12
	v_add3_u32 v12, 0, v12, v13
	ds_read_b128 v[96:99], v12
	v_mfma_f32_16x16x32_bf16 v[12:15], v[88:91], v[0:3], v[8:11]
	v_add_u32_e32 v90, s34, v80
	s_waitcnt lgkmcnt(1)
	v_mfma_f32_16x16x32_bf16 v[8:11], v[92:95], v[4:7], 0
	s_waitcnt lgkmcnt(0)
	v_mfma_f32_16x16x32_bf16 v[8:11], v[96:99], v[0:3], v[8:11]
	v_or_b32_e32 v97, s74, v79
	v_med3_u32 v80, v97, 8, 56
	v_lshl_add_u32 v99, v81, 3, v84
	v_add_u32_e32 v96, -8, v80
	v_add_u32_e32 v98, 8, v80
	v_sub_u32_e32 v80, v99, v97
	v_med3_i32 v80, v80, -15, 15
	v_cmp_ge_i32_e32 vcc, v99, v96
	v_cmp_lt_i32_e64 s[0:1], v99, v98
	v_add_u32_e32 v80, 15, v80
	s_and_b64 vcc, vcc, s[0:1]
	v_cndmask_b32_e32 v87, -1, v80, vcc
	v_cmp_lt_i32_e32 vcc, -1, v87
	v_mov_b32_e32 v80, 0xf149f2ca
	v_lshl_add_u32 v88, v87, 2, v90
	v_mov_b32_e32 v87, 0xf149f2ca
	s_and_saveexec_b64 s[0:1], vcc
	s_nop 0
	ds_read_b32 v93, v88 offset:372
	s_mov_b32 s8, 0x3e38aa3b
	v_mov_b32_e32 v92, v68
	s_mov_b32 s9, 0x3fb8aa3b
	s_waitcnt lgkmcnt(0)
	v_pk_mul_f32 v[92:93], v[92:93], s[8:9]
	s_nop 0
	v_add_f32_e32 v87, v92, v93
.LBB0_1092:
	s_or_b64 exec, exec, s[0:1]
	v_or_b32_e32 v68, 1, v99
	v_sub_u32_e32 v89, v68, v97
	v_med3_i32 v89, v89, -15, 15
	v_cmp_ge_i32_e64 s[0:1], v68, v96
	v_cmp_lt_i32_e64 s[8:9], v68, v98
	v_add_u32_e32 v68, 15, v89
	s_and_b64 s[0:1], s[0:1], s[8:9]
	v_cndmask_b32_e64 v68, -1, v68, s[0:1]
	v_cmp_lt_i32_e64 s[8:9], -1, v68
	v_lshl_add_u32 v89, v68, 2, v90
	s_and_saveexec_b64 s[0:1], s[8:9]
	s_nop 0
	ds_read_b32 v93, v89 offset:372
	s_mov_b32 s10, 0x3e38aa3b
	v_mov_b32_e32 v92, v69
	s_mov_b32 s11, 0x3fb8aa3b
	s_waitcnt lgkmcnt(0)
	v_pk_mul_f32 v[68:69], v[92:93], s[10:11]
	s_nop 0
	v_add_f32_e32 v80, v68, v69
.LBB0_1094:
	s_or_b64 exec, exec, s[0:1]
	v_or_b32_e32 v68, 2, v99
	v_sub_u32_e32 v69, v68, v97
	v_med3_i32 v69, v69, -15, 15
	v_cmp_ge_i32_e64 s[0:1], v68, v96
	v_cmp_lt_i32_e64 s[10:11], v68, v98
	v_add_u32_e32 v68, 15, v69
	s_and_b64 s[0:1], s[0:1], s[10:11]
	v_cndmask_b32_e64 v69, -1, v68, s[0:1]
	v_cmp_lt_i32_e64 s[10:11], -1, v69
	v_mov_b32_e32 v68, 0xf149f2ca
	v_lshl_add_u32 v91, v69, 2, v90
	v_mov_b32_e32 v69, 0xf149f2ca
	s_and_saveexec_b64 s[0:1], s[10:11]
	s_nop 0
	ds_read_b32 v93, v91 offset:372
	s_mov_b32 s12, 0x3e38aa3b
	v_mov_b32_e32 v92, v70
	s_mov_b32 s13, 0x3fb8aa3b
	s_waitcnt lgkmcnt(0)
	v_pk_mul_f32 v[92:93], v[92:93], s[12:13]
	s_nop 0
	v_add_f32_e32 v69, v92, v93
.LBB0_1096:
	s_or_b64 exec, exec, s[0:1]
	v_or_b32_e32 v70, 3, v99
	v_sub_u32_e32 v92, v70, v97
	v_med3_i32 v92, v92, -15, 15
	v_cmp_ge_i32_e64 s[0:1], v70, v96
	v_cmp_lt_i32_e64 s[12:13], v70, v98
	v_add_u32_e32 v70, 15, v92
	s_and_b64 s[0:1], s[0:1], s[12:13]
	v_cndmask_b32_e64 v70, -1, v70, s[0:1]
	v_cmp_lt_i32_e64 s[12:13], -1, v70
	v_lshl_add_u32 v92, v70, 2, v90
	s_and_saveexec_b64 s[0:1], s[12:13]
	s_nop 0
	ds_read_b32 v95, v92 offset:372
	s_mov_b32 s14, 0x3e38aa3b
	v_mov_b32_e32 v94, v71
	s_mov_b32 s15, 0x3fb8aa3b
	s_waitcnt lgkmcnt(0)
	v_pk_mul_f32 v[70:71], v[94:95], s[14:15]
	s_nop 0
	v_add_f32_e32 v68, v70, v71
.LBB0_1098:
	s_or_b64 exec, exec, s[0:1]
	v_or_b32_e32 v70, 4, v99
	v_sub_u32_e32 v71, v70, v97
	v_med3_i32 v71, v71, -15, 15
	v_cmp_ge_i32_e64 s[0:1], v70, v96
	v_cmp_lt_i32_e64 s[14:15], v70, v98
	v_add_u32_e32 v70, 15, v71
	s_and_b64 s[0:1], s[0:1], s[14:15]
	v_cndmask_b32_e64 v71, -1, v70, s[0:1]
	v_cmp_lt_i32_e64 s[14:15], -1, v71
	v_mov_b32_e32 v70, 0xf149f2ca
	v_lshl_add_u32 v93, v71, 2, v90
	v_mov_b32_e32 v71, 0xf149f2ca
	s_and_saveexec_b64 s[0:1], s[14:15]
	s_nop 0
	ds_read_b32 v95, v93 offset:372
	s_mov_b32 s16, 0x3e38aa3b
	v_mov_b32_e32 v94, v64
	s_mov_b32 s17, 0x3fb8aa3b
	s_waitcnt lgkmcnt(0)
	v_pk_mul_f32 v[94:95], v[94:95], s[16:17]
	s_nop 0
	v_add_f32_e32 v71, v94, v95
.LBB0_1100:
	s_or_b64 exec, exec, s[0:1]
	v_or_b32_e32 v64, 5, v99
	v_sub_u32_e32 v94, v64, v97
	v_med3_i32 v94, v94, -15, 15
	v_cmp_ge_i32_e64 s[0:1], v64, v96
	v_cmp_lt_i32_e64 s[16:17], v64, v98
	v_add_u32_e32 v64, 15, v94
	s_and_b64 s[0:1], s[0:1], s[16:17]
	v_cndmask_b32_e64 v64, -1, v64, s[0:1]
	v_cmp_lt_i32_e64 s[16:17], -1, v64
	v_lshl_add_u32 v94, v64, 2, v90
	s_and_saveexec_b64 s[0:1], s[16:17]
	s_nop 0
	ds_read_b32 v101, v94 offset:372
	s_mov_b32 s18, 0x3e38aa3b
	v_mov_b32_e32 v100, v65
	s_mov_b32 s19, 0x3fb8aa3b
	s_waitcnt lgkmcnt(0)
	v_pk_mul_f32 v[64:65], v[100:101], s[18:19]
	s_nop 0
	v_add_f32_e32 v70, v64, v65
.LBB0_1102:
	s_or_b64 exec, exec, s[0:1]
	v_or_b32_e32 v64, 6, v99
	v_sub_u32_e32 v65, v64, v97
	v_med3_i32 v65, v65, -15, 15
	v_cmp_ge_i32_e64 s[0:1], v64, v96
	v_cmp_lt_i32_e64 s[18:19], v64, v98
	v_add_u32_e32 v64, 15, v65
	s_and_b64 s[0:1], s[0:1], s[18:19]
	v_cndmask_b32_e64 v65, -1, v64, s[0:1]
	v_cmp_lt_i32_e64 s[18:19], -1, v65
	v_mov_b32_e32 v64, 0xf149f2ca
	v_lshl_add_u32 v95, v65, 2, v90
	v_mov_b32_e32 v65, 0xf149f2ca
	s_and_saveexec_b64 s[0:1], s[18:19]
	s_nop 0
	ds_read_b32 v101, v95 offset:372
	s_mov_b32 s20, 0x3e38aa3b
	v_mov_b32_e32 v100, v66
	s_mov_b32 s21, 0x3fb8aa3b
	s_waitcnt lgkmcnt(0)
	v_pk_mul_f32 v[100:101], v[100:101], s[20:21]
	s_nop 0
	v_add_f32_e32 v65, v100, v101
.LBB0_1104:
	s_or_b64 exec, exec, s[0:1]
	v_or_b32_e32 v66, 7, v99
	v_sub_u32_e32 v97, v66, v97
	v_med3_i32 v97, v97, -15, 15
	v_cmp_ge_i32_e64 s[0:1], v66, v96
	v_cmp_lt_i32_e64 s[20:21], v66, v98
	v_add_u32_e32 v66, 15, v97
	s_and_b64 s[0:1], s[0:1], s[20:21]
	v_cndmask_b32_e64 v66, -1, v66, s[0:1]
	v_cmp_lt_i32_e64 s[20:21], -1, v66
	v_lshl_add_u32 v96, v66, 2, v90
	s_and_saveexec_b64 s[0:1], s[20:21]
	s_nop 0
	ds_read_b32 v99, v96 offset:372
	s_mov_b32 s58, 0x3e38aa3b
	v_mov_b32_e32 v98, v67
	s_mov_b32 s59, 0x3fb8aa3b
	s_waitcnt lgkmcnt(0)
	v_pk_mul_f32 v[66:67], v[98:99], s[58:59]
	s_nop 0
	v_add_f32_e32 v64, v66, v67
.LBB0_1106:
	s_or_b64 exec, exec, s[0:1]
	v_mov_b32_e32 v66, 0xf149f2ca
	v_mov_b32_e32 v67, 0xf149f2ca
	s_and_saveexec_b64 s[0:1], vcc
	s_nop 0
	ds_read_b32 v99, v88 offset:496
	s_mov_b32 s58, 0x3e38aa3b
	v_mov_b32_e32 v98, v60
	s_mov_b32 s59, 0x3fb8aa3b
	s_waitcnt lgkmcnt(0)
	v_pk_mul_f32 v[98:99], v[98:99], s[58:59]
	s_nop 0
	v_add_f32_e32 v67, v98, v99
.LBB0_1108:
	s_or_b64 exec, exec, s[0:1]
	s_and_saveexec_b64 s[0:1], s[8:9]
	s_nop 0
	ds_read_b32 v99, v89 offset:496
	s_mov_b32 s58, 0x3e38aa3b
	v_mov_b32_e32 v98, v61
	s_mov_b32 s59, 0x3fb8aa3b
	s_waitcnt lgkmcnt(0)
	v_pk_mul_f32 v[60:61], v[98:99], s[58:59]
	s_nop 0
	v_add_f32_e32 v66, v60, v61
.LBB0_1110:
	s_or_b64 exec, exec, s[0:1]
	v_mov_b32_e32 v60, 0xf149f2ca
	v_mov_b32_e32 v61, 0xf149f2ca
	s_and_saveexec_b64 s[0:1], s[10:11]
	s_nop 0
	ds_read_b32 v99, v91 offset:496
	s_mov_b32 s58, 0x3e38aa3b
	v_mov_b32_e32 v98, v62
	s_mov_b32 s59, 0x3fb8aa3b
	s_waitcnt lgkmcnt(0)
	v_pk_mul_f32 v[98:99], v[98:99], s[58:59]
	s_nop 0
	v_add_f32_e32 v61, v98, v99
.LBB0_1112:
	s_or_b64 exec, exec, s[0:1]
	s_and_saveexec_b64 s[0:1], s[12:13]
	s_nop 0
	ds_read_b32 v99, v92 offset:496
	s_mov_b32 s58, 0x3e38aa3b
	v_mov_b32_e32 v98, v63
	s_mov_b32 s59, 0x3fb8aa3b
	s_waitcnt lgkmcnt(0)
	v_pk_mul_f32 v[62:63], v[98:99], s[58:59]
	s_nop 0
	v_add_f32_e32 v60, v62, v63
.LBB0_1114:
	s_or_b64 exec, exec, s[0:1]
	v_mov_b32_e32 v62, 0xf149f2ca
	v_mov_b32_e32 v63, 0xf149f2ca
	s_and_saveexec_b64 s[0:1], s[14:15]
	s_nop 0
	ds_read_b32 v99, v93 offset:496
	s_mov_b32 s58, 0x3e38aa3b
	v_mov_b32_e32 v98, v56
	s_mov_b32 s59, 0x3fb8aa3b
	s_waitcnt lgkmcnt(0)
	v_pk_mul_f32 v[98:99], v[98:99], s[58:59]
	s_nop 0
	v_add_f32_e32 v63, v98, v99
.LBB0_1116:
	s_or_b64 exec, exec, s[0:1]
	s_and_saveexec_b64 s[0:1], s[16:17]
	s_nop 0
	ds_read_b32 v99, v94 offset:496
	s_mov_b32 s58, 0x3e38aa3b
	v_mov_b32_e32 v98, v57
	s_mov_b32 s59, 0x3fb8aa3b
	s_waitcnt lgkmcnt(0)
	v_pk_mul_f32 v[56:57], v[98:99], s[58:59]
	s_nop 0
	v_add_f32_e32 v62, v56, v57
.LBB0_1118:
	s_or_b64 exec, exec, s[0:1]
	v_mov_b32_e32 v56, 0xf149f2ca
	v_mov_b32_e32 v90, 0xf149f2ca
	s_and_saveexec_b64 s[0:1], s[18:19]
	s_nop 0
	ds_read_b32 v99, v95 offset:496
	s_mov_b32 s58, 0x3e38aa3b
	v_mov_b32_e32 v98, v58
	s_mov_b32 s59, 0x3fb8aa3b
	s_waitcnt lgkmcnt(0)
	v_pk_mul_f32 v[98:99], v[98:99], s[58:59]
	s_nop 0
	v_add_f32_e32 v90, v98, v99
.LBB0_1120:
	s_or_b64 exec, exec, s[0:1]
	s_and_saveexec_b64 s[0:1], s[20:21]
	s_nop 0
	ds_read_b32 v57, v96 offset:496
	s_mov_b32 s58, 0x3e38aa3b
	v_mov_b32_e32 v56, v59
	s_mov_b32 s59, 0x3fb8aa3b
	s_waitcnt lgkmcnt(0)
	v_pk_mul_f32 v[56:57], v[56:57], s[58:59]
	s_nop 0
	v_add_f32_e32 v56, v56, v57
.LBB0_1122:
	s_or_b64 exec, exec, s[0:1]
	v_mov_b32_e32 v57, 0xf149f2ca
	v_mov_b32_e32 v58, 0xf149f2ca
	s_and_saveexec_b64 s[0:1], vcc
	s_nop 0
	ds_read_b32 v59, v88 offset:620
	s_mov_b32 s58, 0x3e38aa3b
	v_mov_b32_e32 v58, v52
	s_mov_b32 s59, 0x3fb8aa3b
	s_waitcnt lgkmcnt(0)
	v_pk_mul_f32 v[58:59], v[58:59], s[58:59]
	s_nop 0
	v_add_f32_e32 v58, v58, v59
.LBB0_1124:
	s_or_b64 exec, exec, s[0:1]
	s_and_saveexec_b64 s[0:1], s[8:9]
	s_nop 0
	ds_read_b32 v99, v89 offset:620
	s_mov_b32 s58, 0x3e38aa3b
	v_mov_b32_e32 v98, v53
	s_mov_b32 s59, 0x3fb8aa3b
	s_waitcnt lgkmcnt(0)
	v_pk_mul_f32 v[52:53], v[98:99], s[58:59]
	s_nop 0
	v_add_f32_e32 v57, v52, v53
.LBB0_1126:
	s_or_b64 exec, exec, s[0:1]
	v_mov_b32_e32 v52, 0xf149f2ca
	v_mov_b32_e32 v53, 0xf149f2ca
	s_and_saveexec_b64 s[0:1], s[10:11]
	s_nop 0
	ds_read_b32 v99, v91 offset:620
	s_mov_b32 s58, 0x3e38aa3b
	v_mov_b32_e32 v98, v54
	s_mov_b32 s59, 0x3fb8aa3b
	s_waitcnt lgkmcnt(0)
	v_pk_mul_f32 v[98:99], v[98:99], s[58:59]
	s_nop 0
	v_add_f32_e32 v53, v98, v99
.LBB0_1128:
	s_or_b64 exec, exec, s[0:1]
	s_and_saveexec_b64 s[0:1], s[12:13]
	s_nop 0
	ds_read_b32 v99, v92 offset:620
	s_mov_b32 s58, 0x3e38aa3b
	v_mov_b32_e32 v98, v55
	s_mov_b32 s59, 0x3fb8aa3b
	s_waitcnt lgkmcnt(0)
	v_pk_mul_f32 v[54:55], v[98:99], s[58:59]
	s_nop 0
	v_add_f32_e32 v52, v54, v55
.LBB0_1130:
	s_or_b64 exec, exec, s[0:1]
	v_mov_b32_e32 v54, 0xf149f2ca
	v_mov_b32_e32 v55, 0xf149f2ca
	s_and_saveexec_b64 s[0:1], s[14:15]
	s_nop 0
	ds_read_b32 v99, v93 offset:620
	s_mov_b32 s58, 0x3e38aa3b
	v_mov_b32_e32 v98, v48
	s_mov_b32 s59, 0x3fb8aa3b
	s_waitcnt lgkmcnt(0)
	v_pk_mul_f32 v[98:99], v[98:99], s[58:59]
	s_nop 0
	v_add_f32_e32 v55, v98, v99
.LBB0_1132:
	s_or_b64 exec, exec, s[0:1]
	s_and_saveexec_b64 s[0:1], s[16:17]
	s_nop 0
	ds_read_b32 v99, v94 offset:620
	s_mov_b32 s58, 0x3e38aa3b
	v_mov_b32_e32 v98, v49
	s_mov_b32 s59, 0x3fb8aa3b
	s_waitcnt lgkmcnt(0)
	v_pk_mul_f32 v[48:49], v[98:99], s[58:59]
	s_nop 0
	v_add_f32_e32 v54, v48, v49
.LBB0_1134:
	s_or_b64 exec, exec, s[0:1]
	v_mov_b32_e32 v48, 0xf149f2ca
	v_mov_b32_e32 v59, 0xf149f2ca
	s_and_saveexec_b64 s[0:1], s[18:19]
	s_nop 0
	ds_read_b32 v99, v95 offset:620
	s_mov_b32 s58, 0x3e38aa3b
	v_mov_b32_e32 v98, v50
	s_mov_b32 s59, 0x3fb8aa3b
	s_waitcnt lgkmcnt(0)
	v_pk_mul_f32 v[98:99], v[98:99], s[58:59]
	s_nop 0
	v_add_f32_e32 v59, v98, v99
.LBB0_1136:
	s_or_b64 exec, exec, s[0:1]
	s_and_saveexec_b64 s[0:1], s[20:21]
	s_nop 0
	ds_read_b32 v49, v96 offset:620
	s_mov_b32 s58, 0x3e38aa3b
	v_mov_b32_e32 v48, v51
	s_mov_b32 s59, 0x3fb8aa3b
	s_waitcnt lgkmcnt(0)
	v_pk_mul_f32 v[48:49], v[48:49], s[58:59]
	s_nop 0
	v_add_f32_e32 v48, v48, v49
.LBB0_1138:
	s_or_b64 exec, exec, s[0:1]
	v_mov_b32_e32 v49, 0xf149f2ca
	v_mov_b32_e32 v50, 0xf149f2ca
	s_and_saveexec_b64 s[0:1], vcc
	s_nop 0
	ds_read_b32 v51, v88 offset:744
	s_mov_b32 s58, 0x3e38aa3b
	v_mov_b32_e32 v50, v44
	s_mov_b32 s59, 0x3fb8aa3b
	s_waitcnt lgkmcnt(0)
	v_pk_mul_f32 v[50:51], v[50:51], s[58:59]
	s_nop 0
	v_add_f32_e32 v50, v50, v51
.LBB0_1140:
	s_or_b64 exec, exec, s[0:1]
	s_and_saveexec_b64 s[0:1], s[8:9]
	s_nop 0
	ds_read_b32 v99, v89 offset:744
	s_mov_b32 s58, 0x3e38aa3b
	v_mov_b32_e32 v98, v45
	s_mov_b32 s59, 0x3fb8aa3b
	s_waitcnt lgkmcnt(0)
	v_pk_mul_f32 v[44:45], v[98:99], s[58:59]
	s_nop 0
	v_add_f32_e32 v49, v44, v45
.LBB0_1142:
	s_or_b64 exec, exec, s[0:1]
	v_mov_b32_e32 v44, 0xf149f2ca
	v_mov_b32_e32 v45, 0xf149f2ca
	s_and_saveexec_b64 s[0:1], s[10:11]
	s_nop 0
	ds_read_b32 v99, v91 offset:744
	s_mov_b32 s58, 0x3e38aa3b
	v_mov_b32_e32 v98, v46
	s_mov_b32 s59, 0x3fb8aa3b
	s_waitcnt lgkmcnt(0)
	v_pk_mul_f32 v[98:99], v[98:99], s[58:59]
	s_nop 0
	v_add_f32_e32 v45, v98, v99
.LBB0_1144:
	s_or_b64 exec, exec, s[0:1]
	s_and_saveexec_b64 s[0:1], s[12:13]
	s_nop 0
	ds_read_b32 v99, v92 offset:744
	s_mov_b32 s58, 0x3e38aa3b
	v_mov_b32_e32 v98, v47
	s_mov_b32 s59, 0x3fb8aa3b
	s_waitcnt lgkmcnt(0)
	v_pk_mul_f32 v[46:47], v[98:99], s[58:59]
	s_nop 0
	v_add_f32_e32 v44, v46, v47
.LBB0_1146:
	s_or_b64 exec, exec, s[0:1]
	v_mov_b32_e32 v46, 0xf149f2ca
	v_mov_b32_e32 v47, 0xf149f2ca
	s_and_saveexec_b64 s[0:1], s[14:15]
	s_nop 0
	ds_read_b32 v99, v93 offset:744
	s_mov_b32 s58, 0x3e38aa3b
	v_mov_b32_e32 v98, v40
	s_mov_b32 s59, 0x3fb8aa3b
	s_waitcnt lgkmcnt(0)
	v_pk_mul_f32 v[98:99], v[98:99], s[58:59]
	s_nop 0
	v_add_f32_e32 v47, v98, v99
.LBB0_1148:
	s_or_b64 exec, exec, s[0:1]
	s_and_saveexec_b64 s[0:1], s[16:17]
	s_nop 0
	ds_read_b32 v99, v94 offset:744
	s_mov_b32 s58, 0x3e38aa3b
	v_mov_b32_e32 v98, v41
	s_mov_b32 s59, 0x3fb8aa3b
	s_waitcnt lgkmcnt(0)
	v_pk_mul_f32 v[40:41], v[98:99], s[58:59]
	s_nop 0
	v_add_f32_e32 v46, v40, v41
.LBB0_1150:
	s_or_b64 exec, exec, s[0:1]
	v_mov_b32_e32 v40, 0xf149f2ca
	v_mov_b32_e32 v51, 0xf149f2ca
	s_and_saveexec_b64 s[0:1], s[18:19]
	s_nop 0
	ds_read_b32 v99, v95 offset:744
	s_mov_b32 s58, 0x3e38aa3b
	v_mov_b32_e32 v98, v42
	s_mov_b32 s59, 0x3fb8aa3b
	s_waitcnt lgkmcnt(0)
	v_pk_mul_f32 v[98:99], v[98:99], s[58:59]
	s_nop 0
	v_add_f32_e32 v51, v98, v99
.LBB0_1152:
	s_or_b64 exec, exec, s[0:1]
	s_and_saveexec_b64 s[0:1], s[20:21]
	s_nop 0
	ds_read_b32 v41, v96 offset:744
	s_mov_b32 s58, 0x3e38aa3b
	v_mov_b32_e32 v40, v43
	s_mov_b32 s59, 0x3fb8aa3b
	s_waitcnt lgkmcnt(0)
	v_pk_mul_f32 v[40:41], v[40:41], s[58:59]
	s_nop 0
	v_add_f32_e32 v40, v40, v41
.LBB0_1154:
	s_or_b64 exec, exec, s[0:1]
	v_mov_b32_e32 v41, 0xf149f2ca
	v_mov_b32_e32 v42, 0xf149f2ca
	s_and_saveexec_b64 s[0:1], vcc
	s_nop 0
	ds_read_b32 v43, v88 offset:868
	s_mov_b32 s58, 0x3e38aa3b
	v_mov_b32_e32 v42, v36
	s_mov_b32 s59, 0x3fb8aa3b
	s_waitcnt lgkmcnt(0)
	v_pk_mul_f32 v[42:43], v[42:43], s[58:59]
	s_nop 0
	v_add_f32_e32 v42, v42, v43
.LBB0_1156:
	s_or_b64 exec, exec, s[0:1]
	s_and_saveexec_b64 s[0:1], s[8:9]
	s_nop 0
	ds_read_b32 v99, v89 offset:868
	s_mov_b32 s58, 0x3e38aa3b
	v_mov_b32_e32 v98, v37
	s_mov_b32 s59, 0x3fb8aa3b
	s_waitcnt lgkmcnt(0)
	v_pk_mul_f32 v[36:37], v[98:99], s[58:59]
	s_nop 0
	v_add_f32_e32 v41, v36, v37
.LBB0_1158:
	s_or_b64 exec, exec, s[0:1]
	v_mov_b32_e32 v36, 0xf149f2ca
	v_mov_b32_e32 v37, 0xf149f2ca
	s_and_saveexec_b64 s[0:1], s[10:11]
	s_nop 0
	ds_read_b32 v99, v91 offset:868
	s_mov_b32 s58, 0x3e38aa3b
	v_mov_b32_e32 v98, v38
	s_mov_b32 s59, 0x3fb8aa3b
	s_waitcnt lgkmcnt(0)
	v_pk_mul_f32 v[98:99], v[98:99], s[58:59]
	s_nop 0
	v_add_f32_e32 v37, v98, v99
.LBB0_1160:
	s_or_b64 exec, exec, s[0:1]
	s_and_saveexec_b64 s[0:1], s[12:13]
	s_nop 0
	ds_read_b32 v99, v92 offset:868
	s_mov_b32 s58, 0x3e38aa3b
	v_mov_b32_e32 v98, v39
	s_mov_b32 s59, 0x3fb8aa3b
	s_waitcnt lgkmcnt(0)
	v_pk_mul_f32 v[38:39], v[98:99], s[58:59]
	s_nop 0
	v_add_f32_e32 v36, v38, v39
.LBB0_1162:
	s_or_b64 exec, exec, s[0:1]
	v_mov_b32_e32 v38, 0xf149f2ca
	v_mov_b32_e32 v39, 0xf149f2ca
	s_and_saveexec_b64 s[0:1], s[14:15]
	s_nop 0
	ds_read_b32 v99, v93 offset:868
	s_mov_b32 s58, 0x3e38aa3b
	v_mov_b32_e32 v98, v32
	s_mov_b32 s59, 0x3fb8aa3b
	s_waitcnt lgkmcnt(0)
	v_pk_mul_f32 v[98:99], v[98:99], s[58:59]
	s_nop 0
	v_add_f32_e32 v39, v98, v99
.LBB0_1164:
	s_or_b64 exec, exec, s[0:1]
	s_and_saveexec_b64 s[0:1], s[16:17]
	s_nop 0
	ds_read_b32 v99, v94 offset:868
	s_mov_b32 s58, 0x3e38aa3b
	v_mov_b32_e32 v98, v33
	s_mov_b32 s59, 0x3fb8aa3b
	s_waitcnt lgkmcnt(0)
	v_pk_mul_f32 v[32:33], v[98:99], s[58:59]
	s_nop 0
	v_add_f32_e32 v38, v32, v33
.LBB0_1166:
	s_or_b64 exec, exec, s[0:1]
	v_mov_b32_e32 v32, 0xf149f2ca
	v_mov_b32_e32 v43, 0xf149f2ca
	s_and_saveexec_b64 s[0:1], s[18:19]
	s_nop 0
	ds_read_b32 v99, v95 offset:868
	s_mov_b32 s58, 0x3e38aa3b
	v_mov_b32_e32 v98, v34
	s_mov_b32 s59, 0x3fb8aa3b
	s_waitcnt lgkmcnt(0)
	v_pk_mul_f32 v[98:99], v[98:99], s[58:59]
	s_nop 0
	v_add_f32_e32 v43, v98, v99
.LBB0_1168:
	s_or_b64 exec, exec, s[0:1]
	s_and_saveexec_b64 s[0:1], s[20:21]
	s_nop 0
	ds_read_b32 v33, v96 offset:868
	s_mov_b32 s58, 0x3e38aa3b
	v_mov_b32_e32 v32, v35
	s_mov_b32 s59, 0x3fb8aa3b
	s_waitcnt lgkmcnt(0)
	v_pk_mul_f32 v[32:33], v[32:33], s[58:59]
	s_nop 0
	v_add_f32_e32 v32, v32, v33
.LBB0_1170:
	s_or_b64 exec, exec, s[0:1]
	v_mov_b32_e32 v33, 0xf149f2ca
	v_mov_b32_e32 v34, 0xf149f2ca
	s_and_saveexec_b64 s[0:1], vcc
	s_nop 0
	ds_read_b32 v35, v88 offset:992
	s_mov_b32 s58, 0x3e38aa3b
	v_mov_b32_e32 v34, v28
	s_mov_b32 s59, 0x3fb8aa3b
	s_waitcnt lgkmcnt(0)
	v_pk_mul_f32 v[34:35], v[34:35], s[58:59]
	s_nop 0
	v_add_f32_e32 v34, v34, v35
.LBB0_1172:
	s_or_b64 exec, exec, s[0:1]
	s_and_saveexec_b64 s[0:1], s[8:9]
	s_nop 0
	ds_read_b32 v99, v89 offset:992
	s_mov_b32 s58, 0x3e38aa3b
	v_mov_b32_e32 v98, v29
	s_mov_b32 s59, 0x3fb8aa3b
	s_waitcnt lgkmcnt(0)
	v_pk_mul_f32 v[28:29], v[98:99], s[58:59]
	s_nop 0
	v_add_f32_e32 v33, v28, v29
.LBB0_1174:
	s_or_b64 exec, exec, s[0:1]
	v_mov_b32_e32 v28, 0xf149f2ca
	v_mov_b32_e32 v29, 0xf149f2ca
	s_and_saveexec_b64 s[0:1], s[10:11]
	s_nop 0
	ds_read_b32 v99, v91 offset:992
	s_mov_b32 s58, 0x3e38aa3b
	v_mov_b32_e32 v98, v30
	s_mov_b32 s59, 0x3fb8aa3b
	s_waitcnt lgkmcnt(0)
	v_pk_mul_f32 v[98:99], v[98:99], s[58:59]
	s_nop 0
	v_add_f32_e32 v29, v98, v99
.LBB0_1176:
	s_or_b64 exec, exec, s[0:1]
	s_and_saveexec_b64 s[0:1], s[12:13]
	s_nop 0
	ds_read_b32 v99, v92 offset:992
	s_mov_b32 s58, 0x3e38aa3b
	v_mov_b32_e32 v98, v31
	s_mov_b32 s59, 0x3fb8aa3b
	s_waitcnt lgkmcnt(0)
	v_pk_mul_f32 v[30:31], v[98:99], s[58:59]
	s_nop 0
	v_add_f32_e32 v28, v30, v31
.LBB0_1178:
	s_or_b64 exec, exec, s[0:1]
	v_mov_b32_e32 v30, 0xf149f2ca
	v_mov_b32_e32 v31, 0xf149f2ca
	s_and_saveexec_b64 s[0:1], s[14:15]
	s_nop 0
	ds_read_b32 v99, v93 offset:992
	s_mov_b32 s58, 0x3e38aa3b
	v_mov_b32_e32 v98, v24
	s_mov_b32 s59, 0x3fb8aa3b
	s_waitcnt lgkmcnt(0)
	v_pk_mul_f32 v[98:99], v[98:99], s[58:59]
	s_nop 0
	v_add_f32_e32 v31, v98, v99
.LBB0_1180:
	s_or_b64 exec, exec, s[0:1]
	s_and_saveexec_b64 s[0:1], s[16:17]
	s_nop 0
	ds_read_b32 v99, v94 offset:992
	s_mov_b32 s58, 0x3e38aa3b
	v_mov_b32_e32 v98, v25
	s_mov_b32 s59, 0x3fb8aa3b
	s_waitcnt lgkmcnt(0)
	v_pk_mul_f32 v[24:25], v[98:99], s[58:59]
	s_nop 0
	v_add_f32_e32 v30, v24, v25
.LBB0_1182:
	s_or_b64 exec, exec, s[0:1]
	v_mov_b32_e32 v24, 0xf149f2ca
	v_mov_b32_e32 v35, 0xf149f2ca
	s_and_saveexec_b64 s[0:1], s[18:19]
	s_nop 0
	ds_read_b32 v99, v95 offset:992
	s_mov_b32 s58, 0x3e38aa3b
	v_mov_b32_e32 v98, v26
	s_mov_b32 s59, 0x3fb8aa3b
	s_waitcnt lgkmcnt(0)
	v_pk_mul_f32 v[98:99], v[98:99], s[58:59]
	s_nop 0
	v_add_f32_e32 v35, v98, v99
.LBB0_1184:
	s_or_b64 exec, exec, s[0:1]
	s_and_saveexec_b64 s[0:1], s[20:21]
	s_nop 0
	ds_read_b32 v25, v96 offset:992
	s_mov_b32 s58, 0x3e38aa3b
	v_mov_b32_e32 v24, v27
	s_mov_b32 s59, 0x3fb8aa3b
	s_waitcnt lgkmcnt(0)
	v_pk_mul_f32 v[24:25], v[24:25], s[58:59]
	s_nop 0
	v_add_f32_e32 v24, v24, v25
.LBB0_1186:
	s_or_b64 exec, exec, s[0:1]
	v_mov_b32_e32 v25, 0xf149f2ca
	v_mov_b32_e32 v26, 0xf149f2ca
	s_and_saveexec_b64 s[0:1], vcc
	s_nop 0
	ds_read_b32 v27, v88 offset:1116
	s_mov_b32 s58, 0x3e38aa3b
	v_mov_b32_e32 v26, v20
	s_mov_b32 s59, 0x3fb8aa3b
	s_waitcnt lgkmcnt(0)
	v_pk_mul_f32 v[26:27], v[26:27], s[58:59]
	s_nop 0
	v_add_f32_e32 v26, v26, v27
.LBB0_1188:
	s_or_b64 exec, exec, s[0:1]
	s_and_saveexec_b64 s[0:1], s[8:9]
	s_nop 0
	ds_read_b32 v99, v89 offset:1116
	s_mov_b32 s58, 0x3e38aa3b
	v_mov_b32_e32 v98, v21
	s_mov_b32 s59, 0x3fb8aa3b
	s_waitcnt lgkmcnt(0)
	v_pk_mul_f32 v[20:21], v[98:99], s[58:59]
	s_nop 0
	v_add_f32_e32 v25, v20, v21
.LBB0_1190:
	s_or_b64 exec, exec, s[0:1]
	v_mov_b32_e32 v20, 0xf149f2ca
	v_mov_b32_e32 v21, 0xf149f2ca
	s_and_saveexec_b64 s[0:1], s[10:11]
	s_nop 0
	ds_read_b32 v99, v91 offset:1116
	s_mov_b32 s58, 0x3e38aa3b
	v_mov_b32_e32 v98, v22
	s_mov_b32 s59, 0x3fb8aa3b
	s_waitcnt lgkmcnt(0)
	v_pk_mul_f32 v[98:99], v[98:99], s[58:59]
	s_nop 0
	v_add_f32_e32 v21, v98, v99
.LBB0_1192:
	s_or_b64 exec, exec, s[0:1]
	s_and_saveexec_b64 s[0:1], s[12:13]
	s_nop 0
	ds_read_b32 v99, v92 offset:1116
	s_mov_b32 s58, 0x3e38aa3b
	v_mov_b32_e32 v98, v23
	s_mov_b32 s59, 0x3fb8aa3b
	s_waitcnt lgkmcnt(0)
	v_pk_mul_f32 v[22:23], v[98:99], s[58:59]
	s_nop 0
	v_add_f32_e32 v20, v22, v23
.LBB0_1194:
	s_or_b64 exec, exec, s[0:1]
	v_mov_b32_e32 v22, 0xf149f2ca
	v_mov_b32_e32 v23, 0xf149f2ca
	s_and_saveexec_b64 s[0:1], s[14:15]
	s_nop 0
	ds_read_b32 v99, v93 offset:1116
	s_mov_b32 s58, 0x3e38aa3b
	v_mov_b32_e32 v98, v16
	s_mov_b32 s59, 0x3fb8aa3b
	s_waitcnt lgkmcnt(0)
	v_pk_mul_f32 v[98:99], v[98:99], s[58:59]
	s_nop 0
	v_add_f32_e32 v23, v98, v99
.LBB0_1196:
	s_or_b64 exec, exec, s[0:1]
	s_and_saveexec_b64 s[0:1], s[16:17]
	s_nop 0
	ds_read_b32 v99, v94 offset:1116
	s_mov_b32 s58, 0x3e38aa3b
	v_mov_b32_e32 v98, v17
	s_mov_b32 s59, 0x3fb8aa3b
	s_waitcnt lgkmcnt(0)
	v_pk_mul_f32 v[16:17], v[98:99], s[58:59]
	s_nop 0
	v_add_f32_e32 v22, v16, v17
.LBB0_1198:
	s_or_b64 exec, exec, s[0:1]
	v_mov_b32_e32 v17, 0xf149f2ca
	v_mov_b32_e32 v27, 0xf149f2ca
	s_and_saveexec_b64 s[0:1], s[18:19]
	s_nop 0
	ds_read_b32 v99, v95 offset:1116
	s_mov_b32 s58, 0x3e38aa3b
	v_mov_b32_e32 v98, v18
	s_mov_b32 s59, 0x3fb8aa3b
	s_waitcnt lgkmcnt(0)
	v_pk_mul_f32 v[98:99], v[98:99], s[58:59]
	s_nop 0
	v_add_f32_e32 v27, v98, v99
.LBB0_1200:
	s_or_b64 exec, exec, s[0:1]
	s_and_saveexec_b64 s[0:1], s[20:21]
	s_nop 0
	ds_read_b32 v17, v96 offset:1116
	s_mov_b32 s58, 0x3e38aa3b
	v_mov_b32_e32 v16, v19
	s_mov_b32 s59, 0x3fb8aa3b
	s_waitcnt lgkmcnt(0)
	v_pk_mul_f32 v[16:17], v[16:17], s[58:59]
	s_nop 0
	v_add_f32_e32 v17, v16, v17
.LBB0_1202:
	s_or_b64 exec, exec, s[0:1]
	v_mov_b32_e32 v16, 0xf149f2ca
	v_mov_b32_e32 v18, 0xf149f2ca
	s_and_saveexec_b64 s[0:1], vcc
	s_nop 0
	ds_read_b32 v19, v88 offset:1240
	s_mov_b32 s58, 0x3e38aa3b
	v_mov_b32_e32 v18, v12
	s_mov_b32 s59, 0x3fb8aa3b
	s_waitcnt lgkmcnt(0)
	v_pk_mul_f32 v[18:19], v[18:19], s[58:59]
	s_nop 0
	v_add_f32_e32 v18, v18, v19
.LBB0_1204:
	s_or_b64 exec, exec, s[0:1]
	s_and_saveexec_b64 s[0:1], s[8:9]
	s_nop 0
	ds_read_b32 v89, v89 offset:1240
	s_mov_b32 s8, 0x3e38aa3b
	v_mov_b32_e32 v88, v13
	s_mov_b32 s9, 0x3fb8aa3b
	s_waitcnt lgkmcnt(0)
	v_pk_mul_f32 v[12:13], v[88:89], s[8:9]
	s_nop 0
	v_add_f32_e32 v16, v12, v13
.LBB0_1206:
	s_or_b64 exec, exec, s[0:1]
	v_mov_b32_e32 v12, 0xf149f2ca
	v_mov_b32_e32 v13, 0xf149f2ca
	s_and_saveexec_b64 s[0:1], s[10:11]
	s_nop 0
	ds_read_b32 v89, v91 offset:1240
	s_mov_b32 s8, 0x3e38aa3b
	v_mov_b32_e32 v88, v14
	s_mov_b32 s9, 0x3fb8aa3b
	s_waitcnt lgkmcnt(0)
	v_pk_mul_f32 v[88:89], v[88:89], s[8:9]
	s_nop 0
	v_add_f32_e32 v13, v88, v89
.LBB0_1208:
	s_or_b64 exec, exec, s[0:1]
	s_and_saveexec_b64 s[0:1], s[12:13]
	s_nop 0
	ds_read_b32 v89, v92 offset:1240
	s_mov_b32 s8, 0x3e38aa3b
	v_mov_b32_e32 v88, v15
	s_mov_b32 s9, 0x3fb8aa3b
	s_waitcnt lgkmcnt(0)
	v_pk_mul_f32 v[14:15], v[88:89], s[8:9]
	s_nop 0
	v_add_f32_e32 v12, v14, v15
.LBB0_1210:
	s_or_b64 exec, exec, s[0:1]
	v_mov_b32_e32 v14, 0xf149f2ca
	v_mov_b32_e32 v15, 0xf149f2ca
	s_and_saveexec_b64 s[0:1], s[14:15]
	s_nop 0
	ds_read_b32 v89, v93 offset:1240
	s_mov_b32 s8, 0x3e38aa3b
	v_mov_b32_e32 v88, v8
	s_mov_b32 s9, 0x3fb8aa3b
	s_waitcnt lgkmcnt(0)
	v_pk_mul_f32 v[88:89], v[88:89], s[8:9]
	s_nop 0
	v_add_f32_e32 v15, v88, v89
.LBB0_1212:
	s_or_b64 exec, exec, s[0:1]
	s_and_saveexec_b64 s[0:1], s[16:17]
	s_nop 0
	ds_read_b32 v89, v94 offset:1240
	s_mov_b32 s8, 0x3e38aa3b
	v_mov_b32_e32 v88, v9
	s_mov_b32 s9, 0x3fb8aa3b
	s_waitcnt lgkmcnt(0)
	v_pk_mul_f32 v[8:9], v[88:89], s[8:9]
	s_nop 0
	v_add_f32_e32 v14, v8, v9
.LBB0_1214:
	s_or_b64 exec, exec, s[0:1]
	v_mov_b32_e32 v8, 0xf149f2ca
	v_mov_b32_e32 v9, 0xf149f2ca
	s_and_saveexec_b64 s[0:1], s[18:19]
	s_nop 0
	ds_read_b32 v89, v95 offset:1240
	s_mov_b32 s8, 0x3e38aa3b
	v_mov_b32_e32 v88, v10
	s_mov_b32 s9, 0x3fb8aa3b
	s_waitcnt lgkmcnt(0)
	v_pk_mul_f32 v[88:89], v[88:89], s[8:9]
	s_nop 0
	v_add_f32_e32 v9, v88, v89

.LBB0_1230:
	v_med3_u32 v87, s10, 4, 28
	v_sub_u32_e32 v8, v87, v78
	v_lshlrev_b32_e32 v8, 6, v8
	v_add_u32_e32 v80, v8, v84
	v_lshlrev_b32_e32 v8, 1, v79
	v_and_b32_e32 v72, 3, v85
	v_and_or_b32 v8, v8, 24, v72
	v_add_u32_e32 v92, v8, v80
	v_lshlrev_b32_e32 v8, 1, v92
	v_ashrrev_i32_e32 v81, 4, v85
	v_bfe_u32 v12, v92, 3, 2
	v_and_b32_e32 v93, 4, v8
	v_bitop3_b32 v8, v12, v81, v93 bitop3:0x36
	v_lshlrev_b32_e32 v20, 7, v92
	v_lshl_add_u32 v21, v8, 4, 0
	v_add_u32_e32 v88, v21, v20
	s_waitcnt vmcnt(0) lgkmcnt(0)
	s_waitcnt vmcnt(0) lgkmcnt(0)
	s_barrier
	ds_read_b128 v[8:11], v88
	v_add_u32_e32 v86, 4, v81
	v_bitop3_b32 v12, v12, v86, v93 bitop3:0x36
	v_lshl_add_u32 v28, v12, 4, 0
	v_add_u32_e32 v89, v28, v20
	ds_read_b128 v[12:15], v89
	ds_read_b128 v[16:19], v88 offset:8192
	s_waitcnt lgkmcnt(2)
	v_mfma_f32_16x16x32_bf16 v[8:11], v[8:11], v[4:7], 0
	v_or_b32_e32 v29, 0x200, v20
	v_add_u32_e32 v20, v21, v29
	ds_read_b128 v[20:23], v20
	ds_read_b128 v[24:27], v89 offset:8192
	s_waitcnt lgkmcnt(3)
	v_mfma_f32_16x16x32_bf16 v[68:71], v[12:15], v[0:3], v[8:11]
	v_subrev_u32_e32 v87, s10, v87
	s_movk_i32 s0, 0x7c
	v_mul_lo_u32 v87, v87, s0
	v_add_u32_e32 v8, v28, v29
	ds_read_b128 v[8:11], v8
	s_waitcnt lgkmcnt(2)
	v_mfma_f32_16x16x32_bf16 v[12:15], v[20:23], v[4:7], 0
	v_or_b32_e32 v97, s74, v79
	v_lshl_add_u32 v99, v81, 3, v84
	v_sub_u32_e32 v84, v99, v97
	s_waitcnt lgkmcnt(0)
	v_mfma_f32_16x16x32_bf16 v[64:67], v[8:11], v[0:3], v[12:15]
	v_med3_i32 v84, v84, -15, 15
	v_add_u32_e32 v84, 15, v84
	v_mfma_f32_16x16x32_bf16 v[8:11], v[16:19], v[4:7], 0
	v_mfma_f32_16x16x32_bf16 v[60:63], v[24:27], v[0:3], v[8:11]
	s_nop 6
	v_add_u32_e32 v8, 0x44, v92
	v_bfe_u32 v13, v8, 3, 2
	v_lshlrev_b32_e32 v12, 7, v8
	v_bitop3_b32 v8, v13, v81, v93 bitop3:0x36
	v_lshlrev_b32_e32 v8, 4, v8
	v_add3_u32 v8, 0, v8, v12
	ds_read_b128 v[8:11], v8
	v_bitop3_b32 v13, v13, v86, v93 bitop3:0x36
	v_lshlrev_b32_e32 v13, 4, v13
	v_add3_u32 v12, 0, v13, v12
	ds_read_b128 v[12:15], v12
	s_waitcnt lgkmcnt(1)
	v_mfma_f32_16x16x32_bf16 v[8:11], v[8:11], v[4:7], 0
	s_waitcnt lgkmcnt(0)
	v_mfma_f32_16x16x32_bf16 v[56:59], v[12:15], v[0:3], v[8:11]
	s_nop 5
	ds_read_b128 v[8:11], v88 offset:16384
	ds_read_b128 v[12:15], v88 offset:24576
	ds_read_b128 v[16:19], v89 offset:16384
	ds_read_b128 v[20:23], v89 offset:24576
	s_waitcnt lgkmcnt(3)
	v_mfma_f32_16x16x32_bf16 v[8:11], v[8:11], v[4:7], 0
	s_waitcnt lgkmcnt(1)
	v_mfma_f32_16x16x32_bf16 v[52:55], v[16:19], v[0:3], v[8:11]
	s_nop 5
	v_add_u32_e32 v8, 0x84, v92
	v_bfe_u32 v17, v8, 3, 2
	v_lshlrev_b32_e32 v16, 7, v8
	v_bitop3_b32 v8, v17, v81, v93 bitop3:0x36
	v_lshlrev_b32_e32 v8, 4, v8
	v_add3_u32 v8, 0, v8, v16
	ds_read_b128 v[8:11], v8
	v_bitop3_b32 v17, v17, v86, v93 bitop3:0x36
	v_lshlrev_b32_e32 v17, 4, v17
	v_add3_u32 v16, 0, v17, v16
	ds_read_b128 v[16:19], v16
	s_waitcnt lgkmcnt(1)
	v_mfma_f32_16x16x32_bf16 v[8:11], v[8:11], v[4:7], 0
	s_waitcnt lgkmcnt(0)
	v_mfma_f32_16x16x32_bf16 v[48:51], v[16:19], v[0:3], v[8:11]
	v_mfma_f32_16x16x32_bf16 v[8:11], v[12:15], v[4:7], 0
	v_mfma_f32_16x16x32_bf16 v[44:47], v[20:23], v[0:3], v[8:11]
	s_nop 6
	v_add_u32_e32 v8, 0xc4, v92
	v_bfe_u32 v13, v8, 3, 2
	v_lshlrev_b32_e32 v12, 7, v8
	v_bitop3_b32 v8, v13, v81, v93 bitop3:0x36
	v_lshlrev_b32_e32 v8, 4, v8
	v_add3_u32 v8, 0, v8, v12
	ds_read_b128 v[8:11], v8
	v_bitop3_b32 v13, v13, v86, v93 bitop3:0x36
	v_lshlrev_b32_e32 v13, 4, v13
	v_add3_u32 v12, 0, v13, v12
	ds_read_b128 v[12:15], v12
	s_waitcnt lgkmcnt(1)
	v_mfma_f32_16x16x32_bf16 v[8:11], v[8:11], v[4:7], 0
	s_waitcnt lgkmcnt(0)
	v_mfma_f32_16x16x32_bf16 v[40:43], v[12:15], v[0:3], v[8:11]
	s_nop 5
	ds_read_b128 v[8:11], v88 offset:32768
	ds_read_b128 v[12:15], v88 offset:40960
	ds_read_b128 v[16:19], v89 offset:32768
	ds_read_b128 v[20:23], v89 offset:40960
	s_waitcnt lgkmcnt(3)
	v_mfma_f32_16x16x32_bf16 v[8:11], v[8:11], v[4:7], 0
	s_waitcnt lgkmcnt(1)
	v_mfma_f32_16x16x32_bf16 v[36:39], v[16:19], v[0:3], v[8:11]
	s_nop 5
	v_add_u32_e32 v8, 0x104, v92
	v_bfe_u32 v17, v8, 3, 2
	v_lshlrev_b32_e32 v16, 7, v8
	v_bitop3_b32 v8, v17, v81, v93 bitop3:0x36
	v_lshlrev_b32_e32 v8, 4, v8
	v_add3_u32 v8, 0, v8, v16
	ds_read_b128 v[8:11], v8
	v_bitop3_b32 v17, v17, v86, v93 bitop3:0x36
	v_lshlrev_b32_e32 v17, 4, v17
	v_add3_u32 v16, 0, v17, v16
	ds_read_b128 v[16:19], v16
	s_waitcnt lgkmcnt(1)
	v_mfma_f32_16x16x32_bf16 v[8:11], v[8:11], v[4:7], 0
	s_waitcnt lgkmcnt(0)
	v_mfma_f32_16x16x32_bf16 v[32:35], v[16:19], v[0:3], v[8:11]
	v_mfma_f32_16x16x32_bf16 v[8:11], v[12:15], v[4:7], 0
	v_mfma_f32_16x16x32_bf16 v[28:31], v[20:23], v[0:3], v[8:11]
	s_nop 6
	v_add_u32_e32 v8, 0x144, v92
	v_bfe_u32 v13, v8, 3, 2
	v_lshlrev_b32_e32 v12, 7, v8
	v_bitop3_b32 v8, v13, v81, v93 bitop3:0x36
	v_lshlrev_b32_e32 v8, 4, v8
	v_add3_u32 v8, 0, v8, v12
	ds_read_b128 v[8:11], v8
	v_bitop3_b32 v13, v13, v86, v93 bitop3:0x36
	v_lshlrev_b32_e32 v13, 4, v13
	v_add3_u32 v12, 0, v13, v12
	ds_read_b128 v[12:15], v12
	s_waitcnt lgkmcnt(1)
	v_mfma_f32_16x16x32_bf16 v[8:11], v[8:11], v[4:7], 0
	s_waitcnt lgkmcnt(0)
	v_mfma_f32_16x16x32_bf16 v[24:27], v[12:15], v[0:3], v[8:11]
	s_nop 5
	ds_read_b128 v[8:11], v88 offset:49152
	ds_read_b128 v[12:15], v88 offset:57344
	ds_read_b128 v[16:19], v89 offset:49152
	ds_read_b128 v[88:91], v89 offset:57344
	s_waitcnt lgkmcnt(3)
	v_mfma_f32_16x16x32_bf16 v[8:11], v[8:11], v[4:7], 0
	s_waitcnt lgkmcnt(1)
	v_mfma_f32_16x16x32_bf16 v[20:23], v[16:19], v[0:3], v[8:11]
	s_nop 5
	v_add_u32_e32 v8, 0x184, v92
	v_bfe_u32 v17, v8, 3, 2
	v_lshlrev_b32_e32 v16, 7, v8
	v_bitop3_b32 v8, v17, v81, v93 bitop3:0x36
	v_lshlrev_b32_e32 v8, 4, v8
	v_add3_u32 v8, 0, v8, v16
	ds_read_b128 v[8:11], v8
	v_bitop3_b32 v17, v17, v86, v93 bitop3:0x36
	v_lshlrev_b32_e32 v17, 4, v17
	v_add3_u32 v16, 0, v17, v16
	ds_read_b128 v[16:19], v16
	s_waitcnt lgkmcnt(1)
	v_mfma_f32_16x16x32_bf16 v[8:11], v[8:11], v[4:7], 0
	s_waitcnt lgkmcnt(0)
	v_mfma_f32_16x16x32_bf16 v[16:19], v[16:19], v[0:3], v[8:11]
	v_mfma_f32_16x16x32_bf16 v[8:11], v[12:15], v[4:7], 0
	v_mfma_f32_16x16x32_bf16 v[12:15], v[88:91], v[0:3], v[8:11]
	s_nop 6
	v_add_u32_e32 v8, 0x1c4, v92
	v_bfe_u32 v89, v8, 3, 2
	v_lshlrev_b32_e32 v88, 7, v8
	v_bitop3_b32 v8, v89, v81, v93 bitop3:0x36
	v_lshlrev_b32_e32 v8, 4, v8
	v_add3_u32 v8, 0, v8, v88
	ds_read_b128 v[8:11], v8
	v_bitop3_b32 v89, v89, v86, v93 bitop3:0x36
	v_lshlrev_b32_e32 v89, 4, v89
	v_add3_u32 v88, 0, v89, v88
	ds_read_b128 v[88:91], v88
	s_waitcnt lgkmcnt(1)
	v_mfma_f32_16x16x32_bf16 v[8:11], v[8:11], v[4:7], 0
	v_add_u32_e32 v93, s34, v87
	v_med3_u32 v87, v97, 8, 56
	v_add_u32_e32 v96, -8, v87
	v_add_u32_e32 v98, 8, v87
	s_waitcnt lgkmcnt(0)
	v_mfma_f32_16x16x32_bf16 v[8:11], v[88:91], v[0:3], v[8:11]
	v_cmp_ge_i32_e32 vcc, v99, v96
	v_cmp_lt_i32_e64 s[0:1], v99, v98
	s_and_b64 vcc, vcc, s[0:1]
	v_cndmask_b32_e32 v87, -1, v84, vcc
	v_cmp_lt_i32_e32 vcc, -1, v87
	v_mov_b32_e32 v84, 0xf149f2ca
	v_lshl_add_u32 v88, v87, 2, v93
	v_mov_b32_e32 v87, 0xf149f2ca
	s_and_saveexec_b64 s[0:1], vcc
	s_nop 0
	ds_read_b32 v91, v88 offset:372
	s_mov_b32 s10, 0x3e38aa3b
	v_mov_b32_e32 v90, v68
	s_mov_b32 s11, 0x3fb8aa3b
	s_waitcnt lgkmcnt(0)
	v_pk_mul_f32 v[90:91], v[90:91], s[10:11]
	s_nop 0
	v_add_f32_e32 v87, v90, v91
.LBB0_1232:
	s_or_b64 exec, exec, s[0:1]
	v_or_b32_e32 v68, 1, v99
	v_sub_u32_e32 v89, v68, v97
	v_med3_i32 v89, v89, -15, 15
	v_cmp_ge_i32_e64 s[0:1], v68, v96
	v_cmp_lt_i32_e64 s[10:11], v68, v98
	v_add_u32_e32 v68, 15, v89
	s_and_b64 s[0:1], s[0:1], s[10:11]
	v_cndmask_b32_e64 v68, -1, v68, s[0:1]
	v_cmp_lt_i32_e64 s[10:11], -1, v68
	v_lshl_add_u32 v89, v68, 2, v93
	s_and_saveexec_b64 s[0:1], s[10:11]
	s_nop 0
	ds_read_b32 v91, v89 offset:372
	s_mov_b32 s12, 0x3e38aa3b
	v_mov_b32_e32 v90, v69
	s_mov_b32 s13, 0x3fb8aa3b
	s_waitcnt lgkmcnt(0)
	v_pk_mul_f32 v[68:69], v[90:91], s[12:13]
	s_nop 0
	v_add_f32_e32 v84, v68, v69
.LBB0_1234:
	s_or_b64 exec, exec, s[0:1]
	v_or_b32_e32 v68, 2, v99
	v_sub_u32_e32 v69, v68, v97
	v_med3_i32 v69, v69, -15, 15
	v_cmp_ge_i32_e64 s[0:1], v68, v96
	v_cmp_lt_i32_e64 s[12:13], v68, v98
	v_add_u32_e32 v68, 15, v69
	s_and_b64 s[0:1], s[0:1], s[12:13]
	v_cndmask_b32_e64 v69, -1, v68, s[0:1]
	v_cmp_lt_i32_e64 s[12:13], -1, v69
	v_mov_b32_e32 v68, 0xf149f2ca
	v_lshl_add_u32 v90, v69, 2, v93
	v_mov_b32_e32 v69, 0xf149f2ca
	s_and_saveexec_b64 s[0:1], s[12:13]
	s_nop 0
	ds_read_b32 v95, v90 offset:372
	s_mov_b32 s14, 0x3e38aa3b
	v_mov_b32_e32 v94, v70
	s_mov_b32 s15, 0x3fb8aa3b
	s_waitcnt lgkmcnt(0)
	v_pk_mul_f32 v[94:95], v[94:95], s[14:15]
	s_nop 0
	v_add_f32_e32 v69, v94, v95
.LBB0_1236:
	s_or_b64 exec, exec, s[0:1]
	v_or_b32_e32 v70, 3, v99
	v_sub_u32_e32 v91, v70, v97
	v_med3_i32 v91, v91, -15, 15
	v_cmp_ge_i32_e64 s[0:1], v70, v96
	v_cmp_lt_i32_e64 s[14:15], v70, v98
	v_add_u32_e32 v70, 15, v91
	s_and_b64 s[0:1], s[0:1], s[14:15]
	v_cndmask_b32_e64 v70, -1, v70, s[0:1]
	v_cmp_lt_i32_e64 s[14:15], -1, v70
	v_lshl_add_u32 v91, v70, 2, v93
	s_and_saveexec_b64 s[0:1], s[14:15]
	s_nop 0
	ds_read_b32 v95, v91 offset:372
	s_mov_b32 s16, 0x3e38aa3b
	v_mov_b32_e32 v94, v71
	s_mov_b32 s17, 0x3fb8aa3b
	s_waitcnt lgkmcnt(0)
	v_pk_mul_f32 v[70:71], v[94:95], s[16:17]
	s_nop 0
	v_add_f32_e32 v68, v70, v71
.LBB0_1238:
	s_or_b64 exec, exec, s[0:1]
	v_or_b32_e32 v70, 4, v99
	v_sub_u32_e32 v71, v70, v97
	v_med3_i32 v71, v71, -15, 15
	v_cmp_ge_i32_e64 s[0:1], v70, v96
	v_cmp_lt_i32_e64 s[16:17], v70, v98
	v_add_u32_e32 v70, 15, v71
	s_and_b64 s[0:1], s[0:1], s[16:17]
	v_cndmask_b32_e64 v71, -1, v70, s[0:1]
	v_cmp_lt_i32_e64 s[16:17], -1, v71
	v_mov_b32_e32 v70, 0xf149f2ca
	v_lshl_add_u32 v92, v71, 2, v93
	v_mov_b32_e32 v71, 0xf149f2ca
	s_and_saveexec_b64 s[0:1], s[16:17]
	s_nop 0
	ds_read_b32 v95, v92 offset:372
	s_mov_b32 s18, 0x3e38aa3b
	v_mov_b32_e32 v94, v64
	s_mov_b32 s19, 0x3fb8aa3b
	s_waitcnt lgkmcnt(0)
	v_pk_mul_f32 v[94:95], v[94:95], s[18:19]
	s_nop 0
	v_add_f32_e32 v71, v94, v95
.LBB0_1240:
	s_or_b64 exec, exec, s[0:1]
	v_or_b32_e32 v64, 5, v99
	v_sub_u32_e32 v94, v64, v97
	v_med3_i32 v94, v94, -15, 15
	v_cmp_ge_i32_e64 s[0:1], v64, v96
	v_cmp_lt_i32_e64 s[18:19], v64, v98
	v_add_u32_e32 v64, 15, v94
	s_and_b64 s[0:1], s[0:1], s[18:19]
	v_cndmask_b32_e64 v64, -1, v64, s[0:1]
	v_cmp_lt_i32_e64 s[18:19], -1, v64
	v_lshl_add_u32 v94, v64, 2, v93
	s_and_saveexec_b64 s[0:1], s[18:19]
	s_nop 0
	ds_read_b32 v101, v94 offset:372
	s_mov_b32 s20, 0x3e38aa3b
	v_mov_b32_e32 v100, v65
	s_mov_b32 s21, 0x3fb8aa3b
	s_waitcnt lgkmcnt(0)
	v_pk_mul_f32 v[64:65], v[100:101], s[20:21]
	s_nop 0
	v_add_f32_e32 v70, v64, v65
.LBB0_1242:
	s_or_b64 exec, exec, s[0:1]
	v_or_b32_e32 v64, 6, v99
	v_sub_u32_e32 v65, v64, v97
	v_med3_i32 v65, v65, -15, 15
	v_cmp_ge_i32_e64 s[0:1], v64, v96
	v_cmp_lt_i32_e64 s[20:21], v64, v98
	v_add_u32_e32 v64, 15, v65
	s_and_b64 s[0:1], s[0:1], s[20:21]
	v_cndmask_b32_e64 v65, -1, v64, s[0:1]
	v_cmp_lt_i32_e64 s[20:21], -1, v65
	v_mov_b32_e32 v64, 0xf149f2ca
	v_lshl_add_u32 v95, v65, 2, v93
	v_mov_b32_e32 v65, 0xf149f2ca
	s_and_saveexec_b64 s[0:1], s[20:21]
	s_nop 0
	ds_read_b32 v101, v95 offset:372
	s_mov_b32 s22, 0x3e38aa3b
	v_mov_b32_e32 v100, v66
	s_mov_b32 s23, 0x3fb8aa3b
	s_waitcnt lgkmcnt(0)
	v_pk_mul_f32 v[100:101], v[100:101], s[22:23]
	s_nop 0
	v_add_f32_e32 v65, v100, v101
.LBB0_1244:
	s_or_b64 exec, exec, s[0:1]
	v_or_b32_e32 v66, 7, v99
	v_sub_u32_e32 v97, v66, v97
	v_med3_i32 v97, v97, -15, 15
	v_cmp_ge_i32_e64 s[0:1], v66, v96
	v_cmp_lt_i32_e64 s[22:23], v66, v98
	v_add_u32_e32 v66, 15, v97
	s_and_b64 s[0:1], s[0:1], s[22:23]
	v_cndmask_b32_e64 v66, -1, v66, s[0:1]
	v_cmp_lt_i32_e64 s[22:23], -1, v66
	v_lshl_add_u32 v96, v66, 2, v93
	s_and_saveexec_b64 s[0:1], s[22:23]
	s_nop 0
	ds_read_b32 v99, v96 offset:372
	s_mov_b32 s24, 0x3e38aa3b
	v_mov_b32_e32 v98, v67
	s_mov_b32 s25, 0x3fb8aa3b
	s_waitcnt lgkmcnt(0)
	v_pk_mul_f32 v[66:67], v[98:99], s[24:25]
	s_nop 0
	v_add_f32_e32 v64, v66, v67
.LBB0_1246:
	s_or_b64 exec, exec, s[0:1]
	v_mov_b32_e32 v66, 0xf149f2ca
	v_mov_b32_e32 v67, 0xf149f2ca
	s_and_saveexec_b64 s[0:1], vcc
	s_nop 0
	ds_read_b32 v99, v88 offset:496
	s_mov_b32 s24, 0x3e38aa3b
	v_mov_b32_e32 v98, v60
	s_mov_b32 s25, 0x3fb8aa3b
	s_waitcnt lgkmcnt(0)
	v_pk_mul_f32 v[98:99], v[98:99], s[24:25]
	s_nop 0
	v_add_f32_e32 v67, v98, v99
.LBB0_1248:
	s_or_b64 exec, exec, s[0:1]
	s_and_saveexec_b64 s[0:1], s[10:11]
	s_nop 0
	ds_read_b32 v99, v89 offset:496
	s_mov_b32 s24, 0x3e38aa3b
	v_mov_b32_e32 v98, v61
	s_mov_b32 s25, 0x3fb8aa3b
	s_waitcnt lgkmcnt(0)
	v_pk_mul_f32 v[60:61], v[98:99], s[24:25]
	s_nop 0
	v_add_f32_e32 v66, v60, v61
.LBB0_1250:
	s_or_b64 exec, exec, s[0:1]
	v_mov_b32_e32 v60, 0xf149f2ca
	v_mov_b32_e32 v61, 0xf149f2ca
	s_and_saveexec_b64 s[0:1], s[12:13]
	s_nop 0
	ds_read_b32 v99, v90 offset:496
	s_mov_b32 s24, 0x3e38aa3b
	v_mov_b32_e32 v98, v62
	s_mov_b32 s25, 0x3fb8aa3b
	s_waitcnt lgkmcnt(0)
	v_pk_mul_f32 v[98:99], v[98:99], s[24:25]
	s_nop 0
	v_add_f32_e32 v61, v98, v99
.LBB0_1252:
	s_or_b64 exec, exec, s[0:1]
	s_and_saveexec_b64 s[0:1], s[14:15]
	s_nop 0
	ds_read_b32 v99, v91 offset:496
	s_mov_b32 s24, 0x3e38aa3b
	v_mov_b32_e32 v98, v63
	s_mov_b32 s25, 0x3fb8aa3b
	s_waitcnt lgkmcnt(0)
	v_pk_mul_f32 v[62:63], v[98:99], s[24:25]
	s_nop 0
	v_add_f32_e32 v60, v62, v63
.LBB0_1254:
	s_or_b64 exec, exec, s[0:1]
	v_mov_b32_e32 v62, 0xf149f2ca
	v_mov_b32_e32 v63, 0xf149f2ca
	s_and_saveexec_b64 s[0:1], s[16:17]
	s_nop 0
	ds_read_b32 v99, v92 offset:496
	s_mov_b32 s24, 0x3e38aa3b
	v_mov_b32_e32 v98, v56
	s_mov_b32 s25, 0x3fb8aa3b
	s_waitcnt lgkmcnt(0)
	v_pk_mul_f32 v[98:99], v[98:99], s[24:25]
	s_nop 0
	v_add_f32_e32 v63, v98, v99
.LBB0_1256:
	s_or_b64 exec, exec, s[0:1]
	s_and_saveexec_b64 s[0:1], s[18:19]
	s_nop 0
	ds_read_b32 v99, v94 offset:496
	s_mov_b32 s24, 0x3e38aa3b
	v_mov_b32_e32 v98, v57
	s_mov_b32 s25, 0x3fb8aa3b
	s_waitcnt lgkmcnt(0)
	v_pk_mul_f32 v[56:57], v[98:99], s[24:25]
	s_nop 0
	v_add_f32_e32 v62, v56, v57
.LBB0_1258:
	s_or_b64 exec, exec, s[0:1]
	v_mov_b32_e32 v56, 0xf149f2ca
	v_mov_b32_e32 v93, 0xf149f2ca
	s_and_saveexec_b64 s[0:1], s[20:21]
	s_nop 0
	ds_read_b32 v99, v95 offset:496
	s_mov_b32 s24, 0x3e38aa3b
	v_mov_b32_e32 v98, v58
	s_mov_b32 s25, 0x3fb8aa3b
	s_waitcnt lgkmcnt(0)
	v_pk_mul_f32 v[98:99], v[98:99], s[24:25]
	s_nop 0
	v_add_f32_e32 v93, v98, v99
.LBB0_1260:
	s_or_b64 exec, exec, s[0:1]
	s_and_saveexec_b64 s[0:1], s[22:23]
	s_nop 0
	ds_read_b32 v57, v96 offset:496
	s_mov_b32 s24, 0x3e38aa3b
	v_mov_b32_e32 v56, v59
	s_mov_b32 s25, 0x3fb8aa3b
	s_waitcnt lgkmcnt(0)
	v_pk_mul_f32 v[56:57], v[56:57], s[24:25]
	s_nop 0
	v_add_f32_e32 v56, v56, v57
.LBB0_1262:
	s_or_b64 exec, exec, s[0:1]
	v_mov_b32_e32 v57, 0xf149f2ca
	v_mov_b32_e32 v58, 0xf149f2ca
	s_and_saveexec_b64 s[0:1], vcc
	s_nop 0
	ds_read_b32 v59, v88 offset:620
	s_mov_b32 s24, 0x3e38aa3b
	v_mov_b32_e32 v58, v52
	s_mov_b32 s25, 0x3fb8aa3b
	s_waitcnt lgkmcnt(0)
	v_pk_mul_f32 v[58:59], v[58:59], s[24:25]
	s_nop 0
	v_add_f32_e32 v58, v58, v59
.LBB0_1264:
	s_or_b64 exec, exec, s[0:1]
	s_and_saveexec_b64 s[0:1], s[10:11]
	s_nop 0
	ds_read_b32 v99, v89 offset:620
	s_mov_b32 s24, 0x3e38aa3b
	v_mov_b32_e32 v98, v53
	s_mov_b32 s25, 0x3fb8aa3b
	s_waitcnt lgkmcnt(0)
	v_pk_mul_f32 v[52:53], v[98:99], s[24:25]
	s_nop 0
	v_add_f32_e32 v57, v52, v53
.LBB0_1266:
	s_or_b64 exec, exec, s[0:1]
	v_mov_b32_e32 v52, 0xf149f2ca
	v_mov_b32_e32 v53, 0xf149f2ca
	s_and_saveexec_b64 s[0:1], s[12:13]
	s_nop 0
	ds_read_b32 v99, v90 offset:620
	s_mov_b32 s24, 0x3e38aa3b
	v_mov_b32_e32 v98, v54
	s_mov_b32 s25, 0x3fb8aa3b
	s_waitcnt lgkmcnt(0)
	v_pk_mul_f32 v[98:99], v[98:99], s[24:25]
	s_nop 0
	v_add_f32_e32 v53, v98, v99
.LBB0_1268:
	s_or_b64 exec, exec, s[0:1]
	s_and_saveexec_b64 s[0:1], s[14:15]
	s_nop 0
	ds_read_b32 v99, v91 offset:620
	s_mov_b32 s24, 0x3e38aa3b
	v_mov_b32_e32 v98, v55
	s_mov_b32 s25, 0x3fb8aa3b
	s_waitcnt lgkmcnt(0)
	v_pk_mul_f32 v[54:55], v[98:99], s[24:25]
	s_nop 0
	v_add_f32_e32 v52, v54, v55
.LBB0_1270:
	s_or_b64 exec, exec, s[0:1]
	v_mov_b32_e32 v54, 0xf149f2ca
	v_mov_b32_e32 v55, 0xf149f2ca
	s_and_saveexec_b64 s[0:1], s[16:17]
	s_nop 0
	ds_read_b32 v99, v92 offset:620
	s_mov_b32 s24, 0x3e38aa3b
	v_mov_b32_e32 v98, v48
	s_mov_b32 s25, 0x3fb8aa3b
	s_waitcnt lgkmcnt(0)
	v_pk_mul_f32 v[98:99], v[98:99], s[24:25]
	s_nop 0
	v_add_f32_e32 v55, v98, v99
.LBB0_1272:
	s_or_b64 exec, exec, s[0:1]
	s_and_saveexec_b64 s[0:1], s[18:19]
	s_nop 0
	ds_read_b32 v99, v94 offset:620
	s_mov_b32 s24, 0x3e38aa3b
	v_mov_b32_e32 v98, v49
	s_mov_b32 s25, 0x3fb8aa3b
	s_waitcnt lgkmcnt(0)
	v_pk_mul_f32 v[48:49], v[98:99], s[24:25]
	s_nop 0
	v_add_f32_e32 v54, v48, v49
.LBB0_1274:
	s_or_b64 exec, exec, s[0:1]
	v_mov_b32_e32 v48, 0xf149f2ca
	v_mov_b32_e32 v59, 0xf149f2ca
	s_and_saveexec_b64 s[0:1], s[20:21]
	s_nop 0
	ds_read_b32 v99, v95 offset:620
	s_mov_b32 s24, 0x3e38aa3b
	v_mov_b32_e32 v98, v50
	s_mov_b32 s25, 0x3fb8aa3b
	s_waitcnt lgkmcnt(0)
	v_pk_mul_f32 v[98:99], v[98:99], s[24:25]
	s_nop 0
	v_add_f32_e32 v59, v98, v99
.LBB0_1276:
	s_or_b64 exec, exec, s[0:1]
	s_and_saveexec_b64 s[0:1], s[22:23]
	s_nop 0
	ds_read_b32 v49, v96 offset:620
	s_mov_b32 s24, 0x3e38aa3b
	v_mov_b32_e32 v48, v51
	s_mov_b32 s25, 0x3fb8aa3b
	s_waitcnt lgkmcnt(0)
	v_pk_mul_f32 v[48:49], v[48:49], s[24:25]
	s_nop 0
	v_add_f32_e32 v48, v48, v49
.LBB0_1278:
	s_or_b64 exec, exec, s[0:1]
	v_mov_b32_e32 v49, 0xf149f2ca
	v_mov_b32_e32 v50, 0xf149f2ca
	s_and_saveexec_b64 s[0:1], vcc
	s_nop 0
	ds_read_b32 v51, v88 offset:744
	s_mov_b32 s24, 0x3e38aa3b
	v_mov_b32_e32 v50, v44
	s_mov_b32 s25, 0x3fb8aa3b
	s_waitcnt lgkmcnt(0)
	v_pk_mul_f32 v[50:51], v[50:51], s[24:25]
	s_nop 0
	v_add_f32_e32 v50, v50, v51
.LBB0_1280:
	s_or_b64 exec, exec, s[0:1]
	s_and_saveexec_b64 s[0:1], s[10:11]
	s_nop 0
	ds_read_b32 v99, v89 offset:744
	s_mov_b32 s24, 0x3e38aa3b
	v_mov_b32_e32 v98, v45
	s_mov_b32 s25, 0x3fb8aa3b
	s_waitcnt lgkmcnt(0)
	v_pk_mul_f32 v[44:45], v[98:99], s[24:25]
	s_nop 0
	v_add_f32_e32 v49, v44, v45
.LBB0_1282:
	s_or_b64 exec, exec, s[0:1]
	v_mov_b32_e32 v44, 0xf149f2ca
	v_mov_b32_e32 v45, 0xf149f2ca
	s_and_saveexec_b64 s[0:1], s[12:13]
	s_nop 0
	ds_read_b32 v99, v90 offset:744
	s_mov_b32 s24, 0x3e38aa3b
	v_mov_b32_e32 v98, v46
	s_mov_b32 s25, 0x3fb8aa3b
	s_waitcnt lgkmcnt(0)
	v_pk_mul_f32 v[98:99], v[98:99], s[24:25]
	s_nop 0
	v_add_f32_e32 v45, v98, v99
.LBB0_1284:
	s_or_b64 exec, exec, s[0:1]
	s_and_saveexec_b64 s[0:1], s[14:15]
	s_nop 0
	ds_read_b32 v99, v91 offset:744
	s_mov_b32 s24, 0x3e38aa3b
	v_mov_b32_e32 v98, v47
	s_mov_b32 s25, 0x3fb8aa3b
	s_waitcnt lgkmcnt(0)
	v_pk_mul_f32 v[46:47], v[98:99], s[24:25]
	s_nop 0
	v_add_f32_e32 v44, v46, v47
.LBB0_1286:
	s_or_b64 exec, exec, s[0:1]
	v_mov_b32_e32 v46, 0xf149f2ca
	v_mov_b32_e32 v47, 0xf149f2ca
	s_and_saveexec_b64 s[0:1], s[16:17]
	s_nop 0
	ds_read_b32 v99, v92 offset:744
	s_mov_b32 s24, 0x3e38aa3b
	v_mov_b32_e32 v98, v40
	s_mov_b32 s25, 0x3fb8aa3b
	s_waitcnt lgkmcnt(0)
	v_pk_mul_f32 v[98:99], v[98:99], s[24:25]
	s_nop 0
	v_add_f32_e32 v47, v98, v99
.LBB0_1288:
	s_or_b64 exec, exec, s[0:1]
	s_and_saveexec_b64 s[0:1], s[18:19]
	s_nop 0
	ds_read_b32 v99, v94 offset:744
	s_mov_b32 s24, 0x3e38aa3b
	v_mov_b32_e32 v98, v41
	s_mov_b32 s25, 0x3fb8aa3b
	s_waitcnt lgkmcnt(0)
	v_pk_mul_f32 v[40:41], v[98:99], s[24:25]
	s_nop 0
	v_add_f32_e32 v46, v40, v41
.LBB0_1290:
	s_or_b64 exec, exec, s[0:1]
	v_mov_b32_e32 v40, 0xf149f2ca
	v_mov_b32_e32 v51, 0xf149f2ca
	s_and_saveexec_b64 s[0:1], s[20:21]
	s_nop 0
	ds_read_b32 v99, v95 offset:744
	s_mov_b32 s24, 0x3e38aa3b
	v_mov_b32_e32 v98, v42
	s_mov_b32 s25, 0x3fb8aa3b
	s_waitcnt lgkmcnt(0)
	v_pk_mul_f32 v[98:99], v[98:99], s[24:25]
	s_nop 0
	v_add_f32_e32 v51, v98, v99
.LBB0_1292:
	s_or_b64 exec, exec, s[0:1]
	s_and_saveexec_b64 s[0:1], s[22:23]
	s_nop 0
	ds_read_b32 v41, v96 offset:744
	s_mov_b32 s24, 0x3e38aa3b
	v_mov_b32_e32 v40, v43
	s_mov_b32 s25, 0x3fb8aa3b
	s_waitcnt lgkmcnt(0)
	v_pk_mul_f32 v[40:41], v[40:41], s[24:25]
	s_nop 0
	v_add_f32_e32 v40, v40, v41
.LBB0_1294:
	s_or_b64 exec, exec, s[0:1]
	v_mov_b32_e32 v41, 0xf149f2ca
	v_mov_b32_e32 v42, 0xf149f2ca
	s_and_saveexec_b64 s[0:1], vcc
	s_nop 0
	ds_read_b32 v43, v88 offset:868
	s_mov_b32 s24, 0x3e38aa3b
	v_mov_b32_e32 v42, v36
	s_mov_b32 s25, 0x3fb8aa3b
	s_waitcnt lgkmcnt(0)
	v_pk_mul_f32 v[42:43], v[42:43], s[24:25]
	s_nop 0
	v_add_f32_e32 v42, v42, v43
.LBB0_1296:
	s_or_b64 exec, exec, s[0:1]
	s_and_saveexec_b64 s[0:1], s[10:11]
	s_nop 0
	ds_read_b32 v99, v89 offset:868
	s_mov_b32 s24, 0x3e38aa3b
	v_mov_b32_e32 v98, v37
	s_mov_b32 s25, 0x3fb8aa3b
	s_waitcnt lgkmcnt(0)
	v_pk_mul_f32 v[36:37], v[98:99], s[24:25]
	s_nop 0
	v_add_f32_e32 v41, v36, v37
.LBB0_1298:
	s_or_b64 exec, exec, s[0:1]
	v_mov_b32_e32 v36, 0xf149f2ca
	v_mov_b32_e32 v37, 0xf149f2ca
	s_and_saveexec_b64 s[0:1], s[12:13]
	s_nop 0
	ds_read_b32 v99, v90 offset:868
	s_mov_b32 s24, 0x3e38aa3b
	v_mov_b32_e32 v98, v38
	s_mov_b32 s25, 0x3fb8aa3b
	s_waitcnt lgkmcnt(0)
	v_pk_mul_f32 v[98:99], v[98:99], s[24:25]
	s_nop 0
	v_add_f32_e32 v37, v98, v99
.LBB0_1300:
	s_or_b64 exec, exec, s[0:1]
	s_and_saveexec_b64 s[0:1], s[14:15]
	s_nop 0
	ds_read_b32 v99, v91 offset:868
	s_mov_b32 s24, 0x3e38aa3b
	v_mov_b32_e32 v98, v39
	s_mov_b32 s25, 0x3fb8aa3b
	s_waitcnt lgkmcnt(0)
	v_pk_mul_f32 v[38:39], v[98:99], s[24:25]
	s_nop 0
	v_add_f32_e32 v36, v38, v39
.LBB0_1302:
	s_or_b64 exec, exec, s[0:1]
	v_mov_b32_e32 v38, 0xf149f2ca
	v_mov_b32_e32 v39, 0xf149f2ca
	s_and_saveexec_b64 s[0:1], s[16:17]
	s_nop 0
	ds_read_b32 v99, v92 offset:868
	s_mov_b32 s24, 0x3e38aa3b
	v_mov_b32_e32 v98, v32
	s_mov_b32 s25, 0x3fb8aa3b
	s_waitcnt lgkmcnt(0)
	v_pk_mul_f32 v[98:99], v[98:99], s[24:25]
	s_nop 0
	v_add_f32_e32 v39, v98, v99
.LBB0_1304:
	s_or_b64 exec, exec, s[0:1]
	s_and_saveexec_b64 s[0:1], s[18:19]
	s_nop 0
	ds_read_b32 v99, v94 offset:868
	s_mov_b32 s24, 0x3e38aa3b
	v_mov_b32_e32 v98, v33
	s_mov_b32 s25, 0x3fb8aa3b
	s_waitcnt lgkmcnt(0)
	v_pk_mul_f32 v[32:33], v[98:99], s[24:25]
	s_nop 0
	v_add_f32_e32 v38, v32, v33
.LBB0_1306:
	s_or_b64 exec, exec, s[0:1]
	v_mov_b32_e32 v32, 0xf149f2ca
	v_mov_b32_e32 v43, 0xf149f2ca
	s_and_saveexec_b64 s[0:1], s[20:21]
	s_nop 0
	ds_read_b32 v99, v95 offset:868
	s_mov_b32 s24, 0x3e38aa3b
	v_mov_b32_e32 v98, v34
	s_mov_b32 s25, 0x3fb8aa3b
	s_waitcnt lgkmcnt(0)
	v_pk_mul_f32 v[98:99], v[98:99], s[24:25]
	s_nop 0
	v_add_f32_e32 v43, v98, v99
.LBB0_1308:
	s_or_b64 exec, exec, s[0:1]
	s_and_saveexec_b64 s[0:1], s[22:23]
	s_nop 0
	ds_read_b32 v33, v96 offset:868
	s_mov_b32 s24, 0x3e38aa3b
	v_mov_b32_e32 v32, v35
	s_mov_b32 s25, 0x3fb8aa3b
	s_waitcnt lgkmcnt(0)
	v_pk_mul_f32 v[32:33], v[32:33], s[24:25]
	s_nop 0
	v_add_f32_e32 v32, v32, v33
.LBB0_1310:
	s_or_b64 exec, exec, s[0:1]
	v_mov_b32_e32 v33, 0xf149f2ca
	v_mov_b32_e32 v34, 0xf149f2ca
	s_and_saveexec_b64 s[0:1], vcc
	s_nop 0
	ds_read_b32 v35, v88 offset:992
	s_mov_b32 s24, 0x3e38aa3b
	v_mov_b32_e32 v34, v28
	s_mov_b32 s25, 0x3fb8aa3b
	s_waitcnt lgkmcnt(0)
	v_pk_mul_f32 v[34:35], v[34:35], s[24:25]
	s_nop 0
	v_add_f32_e32 v34, v34, v35
.LBB0_1312:
	s_or_b64 exec, exec, s[0:1]
	s_and_saveexec_b64 s[0:1], s[10:11]
	s_nop 0
	ds_read_b32 v99, v89 offset:992
	s_mov_b32 s24, 0x3e38aa3b
	v_mov_b32_e32 v98, v29
	s_mov_b32 s25, 0x3fb8aa3b
	s_waitcnt lgkmcnt(0)
	v_pk_mul_f32 v[28:29], v[98:99], s[24:25]
	s_nop 0
	v_add_f32_e32 v33, v28, v29
.LBB0_1314:
	s_or_b64 exec, exec, s[0:1]
	v_mov_b32_e32 v28, 0xf149f2ca
	v_mov_b32_e32 v29, 0xf149f2ca
	s_and_saveexec_b64 s[0:1], s[12:13]
	s_nop 0
	ds_read_b32 v99, v90 offset:992
	s_mov_b32 s24, 0x3e38aa3b
	v_mov_b32_e32 v98, v30
	s_mov_b32 s25, 0x3fb8aa3b
	s_waitcnt lgkmcnt(0)
	v_pk_mul_f32 v[98:99], v[98:99], s[24:25]
	s_nop 0
	v_add_f32_e32 v29, v98, v99
.LBB0_1316:
	s_or_b64 exec, exec, s[0:1]
	s_and_saveexec_b64 s[0:1], s[14:15]
	s_nop 0
	ds_read_b32 v99, v91 offset:992
	s_mov_b32 s24, 0x3e38aa3b
	v_mov_b32_e32 v98, v31
	s_mov_b32 s25, 0x3fb8aa3b
	s_waitcnt lgkmcnt(0)
	v_pk_mul_f32 v[30:31], v[98:99], s[24:25]
	s_nop 0
	v_add_f32_e32 v28, v30, v31
.LBB0_1318:
	s_or_b64 exec, exec, s[0:1]
	v_mov_b32_e32 v30, 0xf149f2ca
	v_mov_b32_e32 v31, 0xf149f2ca
	s_and_saveexec_b64 s[0:1], s[16:17]
	s_nop 0
	ds_read_b32 v99, v92 offset:992
	s_mov_b32 s24, 0x3e38aa3b
	v_mov_b32_e32 v98, v24
	s_mov_b32 s25, 0x3fb8aa3b
	s_waitcnt lgkmcnt(0)
	v_pk_mul_f32 v[98:99], v[98:99], s[24:25]
	s_nop 0
	v_add_f32_e32 v31, v98, v99
.LBB0_1320:
	s_or_b64 exec, exec, s[0:1]
	s_and_saveexec_b64 s[0:1], s[18:19]
	s_nop 0
	ds_read_b32 v99, v94 offset:992
	s_mov_b32 s24, 0x3e38aa3b
	v_mov_b32_e32 v98, v25
	s_mov_b32 s25, 0x3fb8aa3b
	s_waitcnt lgkmcnt(0)
	v_pk_mul_f32 v[24:25], v[98:99], s[24:25]
	s_nop 0
	v_add_f32_e32 v30, v24, v25
.LBB0_1322:
	s_or_b64 exec, exec, s[0:1]
	v_mov_b32_e32 v24, 0xf149f2ca
	v_mov_b32_e32 v35, 0xf149f2ca
	s_and_saveexec_b64 s[0:1], s[20:21]
	s_nop 0
	ds_read_b32 v99, v95 offset:992
	s_mov_b32 s24, 0x3e38aa3b
	v_mov_b32_e32 v98, v26
	s_mov_b32 s25, 0x3fb8aa3b
	s_waitcnt lgkmcnt(0)
	v_pk_mul_f32 v[98:99], v[98:99], s[24:25]
	s_nop 0
	v_add_f32_e32 v35, v98, v99
.LBB0_1324:
	s_or_b64 exec, exec, s[0:1]
	s_and_saveexec_b64 s[0:1], s[22:23]
	s_nop 0
	ds_read_b32 v25, v96 offset:992
	s_mov_b32 s24, 0x3e38aa3b
	v_mov_b32_e32 v24, v27
	s_mov_b32 s25, 0x3fb8aa3b
	s_waitcnt lgkmcnt(0)
	v_pk_mul_f32 v[24:25], v[24:25], s[24:25]
	s_nop 0
	v_add_f32_e32 v24, v24, v25
.LBB0_1326:
	s_or_b64 exec, exec, s[0:1]
	v_mov_b32_e32 v25, 0xf149f2ca
	v_mov_b32_e32 v26, 0xf149f2ca
	s_and_saveexec_b64 s[0:1], vcc
	s_nop 0
	ds_read_b32 v27, v88 offset:1116
	s_mov_b32 s24, 0x3e38aa3b
	v_mov_b32_e32 v26, v20
	s_mov_b32 s25, 0x3fb8aa3b
	s_waitcnt lgkmcnt(0)
	v_pk_mul_f32 v[26:27], v[26:27], s[24:25]
	s_nop 0
	v_add_f32_e32 v26, v26, v27
.LBB0_1328:
	s_or_b64 exec, exec, s[0:1]
	s_and_saveexec_b64 s[0:1], s[10:11]
	s_nop 0
	ds_read_b32 v99, v89 offset:1116
	s_mov_b32 s24, 0x3e38aa3b
	v_mov_b32_e32 v98, v21
	s_mov_b32 s25, 0x3fb8aa3b
	s_waitcnt lgkmcnt(0)
	v_pk_mul_f32 v[20:21], v[98:99], s[24:25]
	s_nop 0
	v_add_f32_e32 v25, v20, v21
.LBB0_1330:
	s_or_b64 exec, exec, s[0:1]
	v_mov_b32_e32 v20, 0xf149f2ca
	v_mov_b32_e32 v21, 0xf149f2ca
	s_and_saveexec_b64 s[0:1], s[12:13]
	s_nop 0
	ds_read_b32 v99, v90 offset:1116
	s_mov_b32 s24, 0x3e38aa3b
	v_mov_b32_e32 v98, v22
	s_mov_b32 s25, 0x3fb8aa3b
	s_waitcnt lgkmcnt(0)
	v_pk_mul_f32 v[98:99], v[98:99], s[24:25]
	s_nop 0
	v_add_f32_e32 v21, v98, v99
.LBB0_1332:
	s_or_b64 exec, exec, s[0:1]
	s_and_saveexec_b64 s[0:1], s[14:15]
	s_nop 0
	ds_read_b32 v99, v91 offset:1116
	s_mov_b32 s24, 0x3e38aa3b
	v_mov_b32_e32 v98, v23
	s_mov_b32 s25, 0x3fb8aa3b
	s_waitcnt lgkmcnt(0)
	v_pk_mul_f32 v[22:23], v[98:99], s[24:25]
	s_nop 0
	v_add_f32_e32 v20, v22, v23
.LBB0_1334:
	s_or_b64 exec, exec, s[0:1]
	v_mov_b32_e32 v22, 0xf149f2ca
	v_mov_b32_e32 v23, 0xf149f2ca
	s_and_saveexec_b64 s[0:1], s[16:17]
	s_nop 0
	ds_read_b32 v99, v92 offset:1116
	s_mov_b32 s24, 0x3e38aa3b
	v_mov_b32_e32 v98, v16
	s_mov_b32 s25, 0x3fb8aa3b
	s_waitcnt lgkmcnt(0)
	v_pk_mul_f32 v[98:99], v[98:99], s[24:25]
	s_nop 0
	v_add_f32_e32 v23, v98, v99
.LBB0_1336:
	s_or_b64 exec, exec, s[0:1]
	s_and_saveexec_b64 s[0:1], s[18:19]
	s_nop 0
	ds_read_b32 v99, v94 offset:1116
	s_mov_b32 s24, 0x3e38aa3b
	v_mov_b32_e32 v98, v17
	s_mov_b32 s25, 0x3fb8aa3b
	s_waitcnt lgkmcnt(0)
	v_pk_mul_f32 v[16:17], v[98:99], s[24:25]
	s_nop 0
	v_add_f32_e32 v22, v16, v17
.LBB0_1338:
	s_or_b64 exec, exec, s[0:1]
	v_mov_b32_e32 v17, 0xf149f2ca
	v_mov_b32_e32 v27, 0xf149f2ca
	s_and_saveexec_b64 s[0:1], s[20:21]
	s_nop 0
	ds_read_b32 v99, v95 offset:1116
	s_mov_b32 s24, 0x3e38aa3b
	v_mov_b32_e32 v98, v18
	s_mov_b32 s25, 0x3fb8aa3b
	s_waitcnt lgkmcnt(0)
	v_pk_mul_f32 v[98:99], v[98:99], s[24:25]
	s_nop 0
	v_add_f32_e32 v27, v98, v99
.LBB0_1340:
	s_or_b64 exec, exec, s[0:1]
	s_and_saveexec_b64 s[0:1], s[22:23]
	s_nop 0
	ds_read_b32 v17, v96 offset:1116
	s_mov_b32 s24, 0x3e38aa3b
	v_mov_b32_e32 v16, v19
	s_mov_b32 s25, 0x3fb8aa3b
	s_waitcnt lgkmcnt(0)
	v_pk_mul_f32 v[16:17], v[16:17], s[24:25]
	s_nop 0
	v_add_f32_e32 v17, v16, v17
.LBB0_1342:
	s_or_b64 exec, exec, s[0:1]
	v_mov_b32_e32 v16, 0xf149f2ca
	v_mov_b32_e32 v18, 0xf149f2ca
	s_and_saveexec_b64 s[0:1], vcc
	s_nop 0
	ds_read_b32 v19, v88 offset:1240
	s_mov_b32 s24, 0x3e38aa3b
	v_mov_b32_e32 v18, v12
	s_mov_b32 s25, 0x3fb8aa3b
	s_waitcnt lgkmcnt(0)
	v_pk_mul_f32 v[18:19], v[18:19], s[24:25]
	s_nop 0
	v_add_f32_e32 v18, v18, v19
.LBB0_1344:
	s_or_b64 exec, exec, s[0:1]
	s_and_saveexec_b64 s[0:1], s[10:11]
	s_nop 0
	ds_read_b32 v89, v89 offset:1240
	s_mov_b32 s10, 0x3e38aa3b
	v_mov_b32_e32 v88, v13
	s_mov_b32 s11, 0x3fb8aa3b
	s_waitcnt lgkmcnt(0)
	v_pk_mul_f32 v[12:13], v[88:89], s[10:11]
	s_nop 0
	v_add_f32_e32 v16, v12, v13
.LBB0_1346:
	s_or_b64 exec, exec, s[0:1]
	v_mov_b32_e32 v12, 0xf149f2ca
	v_mov_b32_e32 v13, 0xf149f2ca
	s_and_saveexec_b64 s[0:1], s[12:13]
	s_nop 0
	ds_read_b32 v89, v90 offset:1240
	s_mov_b32 s10, 0x3e38aa3b
	v_mov_b32_e32 v88, v14
	s_mov_b32 s11, 0x3fb8aa3b
	s_waitcnt lgkmcnt(0)
	v_pk_mul_f32 v[88:89], v[88:89], s[10:11]
	s_nop 0
	v_add_f32_e32 v13, v88, v89
.LBB0_1348:
	s_or_b64 exec, exec, s[0:1]
	s_and_saveexec_b64 s[0:1], s[14:15]
	s_nop 0
	ds_read_b32 v89, v91 offset:1240
	s_mov_b32 s10, 0x3e38aa3b
	v_mov_b32_e32 v88, v15
	s_mov_b32 s11, 0x3fb8aa3b
	s_waitcnt lgkmcnt(0)
	v_pk_mul_f32 v[14:15], v[88:89], s[10:11]
	s_nop 0
	v_add_f32_e32 v12, v14, v15
.LBB0_1350:
	s_or_b64 exec, exec, s[0:1]
	v_mov_b32_e32 v14, 0xf149f2ca
	v_mov_b32_e32 v15, 0xf149f2ca
	s_and_saveexec_b64 s[0:1], s[16:17]
	s_nop 0
	ds_read_b32 v89, v92 offset:1240
	s_mov_b32 s10, 0x3e38aa3b
	v_mov_b32_e32 v88, v8
	s_mov_b32 s11, 0x3fb8aa3b
	s_waitcnt lgkmcnt(0)
	v_pk_mul_f32 v[88:89], v[88:89], s[10:11]
	s_nop 0
	v_add_f32_e32 v15, v88, v89
.LBB0_1352:
	s_or_b64 exec, exec, s[0:1]
	s_and_saveexec_b64 s[0:1], s[18:19]
	s_nop 0
	ds_read_b32 v89, v94 offset:1240
	s_mov_b32 s10, 0x3e38aa3b
	v_mov_b32_e32 v88, v9
	s_mov_b32 s11, 0x3fb8aa3b
	s_waitcnt lgkmcnt(0)
	v_pk_mul_f32 v[8:9], v[88:89], s[10:11]
	s_nop 0
	v_add_f32_e32 v14, v8, v9
.LBB0_1354:
	s_or_b64 exec, exec, s[0:1]
	v_mov_b32_e32 v19, 0xf149f2ca
	v_mov_b32_e32 v91, 0xf149f2ca
	s_and_saveexec_b64 s[0:1], s[20:21]
	s_nop 0
	ds_read_b32 v9, v95 offset:1240
	s_mov_b32 s10, 0x3e38aa3b
	v_mov_b32_e32 v8, v10
	s_mov_b32 s11, 0x3fb8aa3b
	s_waitcnt lgkmcnt(0)
	v_pk_mul_f32 v[8:9], v[8:9], s[10:11]
	s_nop 0
	v_add_f32_e32 v91, v8, v9
.LBB0_1356:
	s_or_b64 exec, exec, s[0:1]
	s_and_saveexec_b64 s[0:1], s[22:23]
	s_nop 0
	ds_read_b32 v9, v96 offset:1240
	s_mov_b32 s10, 0x3e38aa3b
	v_mov_b32_e32 v8, v11
	s_mov_b32 s11, 0x3fb8aa3b
	s_waitcnt lgkmcnt(0)
	v_pk_mul_f32 v[8:9], v[8:9], s[10:11]
	s_nop 0
	v_add_f32_e32 v19, v8, v9

.LBB0_1439:
	v_med3_u32 v80, s4, 4, 28
	v_med3_u32 v8, s18, 8, 40
	v_add_u32_e32 v84, -8, v8
	v_sub_u32_e32 v8, v80, v10
	v_lshlrev_b32_e32 v8, 6, v8
	v_add_u32_e32 v78, v8, v84
	v_lshlrev_b32_e32 v8, 1, v79
	v_and_b32_e32 v72, 3, v85
	v_and_or_b32 v8, v8, 24, v72
	v_add_u32_e32 v82, v8, v78
	v_lshlrev_b32_e32 v8, 1, v82
	v_ashrrev_i32_e32 v81, 4, v85
	v_bfe_u32 v12, v82, 3, 2
	v_and_b32_e32 v83, 4, v8
	v_bitop3_b32 v8, v12, v81, v83 bitop3:0x36
	v_lshlrev_b32_e32 v20, 7, v82
	v_lshl_add_u32 v21, v8, 4, 0
	v_add_u32_e32 v87, v21, v20
	s_waitcnt vmcnt(0) lgkmcnt(0)
	s_waitcnt vmcnt(0) lgkmcnt(0)
	s_barrier
	ds_read_b128 v[8:11], v87
	v_add_u32_e32 v86, 4, v81
	v_bitop3_b32 v12, v12, v86, v83 bitop3:0x36
	v_lshl_add_u32 v28, v12, 4, 0
	v_add_u32_e32 v88, v28, v20
	ds_read_b128 v[12:15], v88
	ds_read_b128 v[16:19], v87 offset:8192
	s_waitcnt lgkmcnt(2)
	v_mfma_f32_16x16x32_bf16 v[8:11], v[8:11], v[4:7], 0
	v_or_b32_e32 v29, 0x200, v20
	v_add_u32_e32 v20, v21, v29
	ds_read_b128 v[20:23], v20
	ds_read_b128 v[24:27], v88 offset:8192
	s_waitcnt lgkmcnt(3)
	v_mfma_f32_16x16x32_bf16 v[68:71], v[12:15], v[0:3], v[8:11]
	s_mul_i32 s0, s19, 0x744
	v_subrev_u32_e32 v80, s4, v80
	s_movk_i32 s1, 0x7c
	v_add_u32_e32 v8, v28, v29
	ds_read_b128 v[8:11], v8
	s_waitcnt lgkmcnt(2)
	v_mfma_f32_16x16x32_bf16 v[12:15], v[20:23], v[4:7], 0
	s_add_i32 s0, s0, 0
	v_mul_lo_u32 v80, v80, s1
	v_add_u32_e32 v80, s0, v80
	s_waitcnt lgkmcnt(0)
	v_mfma_f32_16x16x32_bf16 v[64:67], v[8:11], v[0:3], v[12:15]
	v_mfma_f32_16x16x32_bf16 v[8:11], v[16:19], v[4:7], 0
	v_mfma_f32_16x16x32_bf16 v[60:63], v[24:27], v[0:3], v[8:11]
	s_nop 6
	v_add_u32_e32 v8, 0x44, v82
	v_bfe_u32 v13, v8, 3, 2
	v_lshlrev_b32_e32 v12, 7, v8
	v_bitop3_b32 v8, v13, v81, v83 bitop3:0x36
	v_lshlrev_b32_e32 v8, 4, v8
	v_add3_u32 v8, 0, v8, v12
	ds_read_b128 v[8:11], v8
	v_bitop3_b32 v13, v13, v86, v83 bitop3:0x36
	v_lshlrev_b32_e32 v13, 4, v13
	v_add3_u32 v12, 0, v13, v12
	ds_read_b128 v[12:15], v12
	s_waitcnt lgkmcnt(1)
	v_mfma_f32_16x16x32_bf16 v[8:11], v[8:11], v[4:7], 0
	s_waitcnt lgkmcnt(0)
	v_mfma_f32_16x16x32_bf16 v[56:59], v[12:15], v[0:3], v[8:11]
	s_nop 5
	ds_read_b128 v[8:11], v87 offset:16384
	ds_read_b128 v[12:15], v87 offset:24576
	ds_read_b128 v[16:19], v88 offset:16384
	ds_read_b128 v[20:23], v88 offset:24576
	s_waitcnt lgkmcnt(3)
	v_mfma_f32_16x16x32_bf16 v[8:11], v[8:11], v[4:7], 0
	s_waitcnt lgkmcnt(1)
	v_mfma_f32_16x16x32_bf16 v[52:55], v[16:19], v[0:3], v[8:11]
	s_nop 5
	v_add_u32_e32 v8, 0x84, v82
	v_bfe_u32 v17, v8, 3, 2
	v_lshlrev_b32_e32 v16, 7, v8
	v_bitop3_b32 v8, v17, v81, v83 bitop3:0x36
	v_lshlrev_b32_e32 v8, 4, v8
	v_add3_u32 v8, 0, v8, v16
	ds_read_b128 v[8:11], v8
	v_bitop3_b32 v17, v17, v86, v83 bitop3:0x36
	v_lshlrev_b32_e32 v17, 4, v17
	v_add3_u32 v16, 0, v17, v16
	ds_read_b128 v[16:19], v16
	s_waitcnt lgkmcnt(1)
	v_mfma_f32_16x16x32_bf16 v[8:11], v[8:11], v[4:7], 0
	s_waitcnt lgkmcnt(0)
	v_mfma_f32_16x16x32_bf16 v[48:51], v[16:19], v[0:3], v[8:11]
	v_mfma_f32_16x16x32_bf16 v[8:11], v[12:15], v[4:7], 0
	v_mfma_f32_16x16x32_bf16 v[44:47], v[20:23], v[0:3], v[8:11]
	s_nop 6
	v_add_u32_e32 v8, 0xc4, v82
	v_bfe_u32 v13, v8, 3, 2
	v_lshlrev_b32_e32 v12, 7, v8
	v_bitop3_b32 v8, v13, v81, v83 bitop3:0x36
	v_lshlrev_b32_e32 v8, 4, v8
	v_add3_u32 v8, 0, v8, v12
	ds_read_b128 v[8:11], v8
	v_bitop3_b32 v13, v13, v86, v83 bitop3:0x36
	v_lshlrev_b32_e32 v13, 4, v13
	v_add3_u32 v12, 0, v13, v12
	ds_read_b128 v[12:15], v12
	s_waitcnt lgkmcnt(1)
	v_mfma_f32_16x16x32_bf16 v[8:11], v[8:11], v[4:7], 0
	s_waitcnt lgkmcnt(0)
	v_mfma_f32_16x16x32_bf16 v[40:43], v[12:15], v[0:3], v[8:11]
	s_nop 5
	ds_read_b128 v[8:11], v87 offset:32768
	ds_read_b128 v[12:15], v87 offset:40960
	ds_read_b128 v[16:19], v88 offset:32768
	ds_read_b128 v[20:23], v88 offset:40960
	s_waitcnt lgkmcnt(3)
	v_mfma_f32_16x16x32_bf16 v[8:11], v[8:11], v[4:7], 0
	s_waitcnt lgkmcnt(1)
	v_mfma_f32_16x16x32_bf16 v[36:39], v[16:19], v[0:3], v[8:11]
	s_nop 5
	v_add_u32_e32 v8, 0x104, v82
	v_bfe_u32 v17, v8, 3, 2
	v_lshlrev_b32_e32 v16, 7, v8
	v_bitop3_b32 v8, v17, v81, v83 bitop3:0x36
	v_lshlrev_b32_e32 v8, 4, v8
	v_add3_u32 v8, 0, v8, v16
	ds_read_b128 v[8:11], v8
	v_bitop3_b32 v17, v17, v86, v83 bitop3:0x36
	v_lshlrev_b32_e32 v17, 4, v17
	v_add3_u32 v16, 0, v17, v16
	ds_read_b128 v[16:19], v16
	s_waitcnt lgkmcnt(1)
	v_mfma_f32_16x16x32_bf16 v[8:11], v[8:11], v[4:7], 0
	s_waitcnt lgkmcnt(0)
	v_mfma_f32_16x16x32_bf16 v[32:35], v[16:19], v[0:3], v[8:11]
	v_mfma_f32_16x16x32_bf16 v[8:11], v[12:15], v[4:7], 0
	v_mfma_f32_16x16x32_bf16 v[28:31], v[20:23], v[0:3], v[8:11]
	s_nop 6
	v_add_u32_e32 v8, 0x144, v82
	v_bfe_u32 v13, v8, 3, 2
	v_lshlrev_b32_e32 v12, 7, v8
	v_bitop3_b32 v8, v13, v81, v83 bitop3:0x36
	v_lshlrev_b32_e32 v8, 4, v8
	v_add3_u32 v8, 0, v8, v12
	ds_read_b128 v[8:11], v8
	v_bitop3_b32 v13, v13, v86, v83 bitop3:0x36
	v_lshlrev_b32_e32 v13, 4, v13
	v_add3_u32 v12, 0, v13, v12
	ds_read_b128 v[12:15], v12
	s_waitcnt lgkmcnt(1)
	v_mfma_f32_16x16x32_bf16 v[8:11], v[8:11], v[4:7], 0
	s_waitcnt lgkmcnt(0)
	v_mfma_f32_16x16x32_bf16 v[24:27], v[12:15], v[0:3], v[8:11]
	s_nop 5
	ds_read_b128 v[8:11], v87 offset:49152
	ds_read_b128 v[12:15], v87 offset:57344
	ds_read_b128 v[16:19], v88 offset:49152
	ds_read_b128 v[88:91], v88 offset:57344
	v_mov_b32_e32 v87, 0xf149f2ca
	s_waitcnt lgkmcnt(3)
	v_mfma_f32_16x16x32_bf16 v[8:11], v[8:11], v[4:7], 0
	s_waitcnt lgkmcnt(1)
	v_mfma_f32_16x16x32_bf16 v[20:23], v[16:19], v[0:3], v[8:11]
	s_nop 5
	v_add_u32_e32 v8, 0x184, v82
	v_bfe_u32 v17, v8, 3, 2
	v_lshlrev_b32_e32 v16, 7, v8
	v_bitop3_b32 v8, v17, v81, v83 bitop3:0x36
	v_lshlrev_b32_e32 v8, 4, v8
	v_add3_u32 v8, 0, v8, v16
	ds_read_b128 v[8:11], v8
	v_bitop3_b32 v17, v17, v86, v83 bitop3:0x36
	v_lshlrev_b32_e32 v17, 4, v17
	v_add3_u32 v16, 0, v17, v16
	ds_read_b128 v[16:19], v16
	s_waitcnt lgkmcnt(1)
	v_mfma_f32_16x16x32_bf16 v[8:11], v[8:11], v[4:7], 0
	s_waitcnt lgkmcnt(0)
	v_mfma_f32_16x16x32_bf16 v[16:19], v[16:19], v[0:3], v[8:11]
	v_mfma_f32_16x16x32_bf16 v[8:11], v[12:15], v[4:7], 0
	v_add_u32_e32 v12, 0x1c4, v82
	v_lshlrev_b32_e32 v13, 7, v12
	v_bfe_u32 v12, v12, 3, 2
	v_bitop3_b32 v14, v12, v81, v83 bitop3:0x36
	v_lshlrev_b32_e32 v14, 4, v14
	v_add3_u32 v14, 0, v14, v13
	ds_read_b128 v[92:95], v14
	v_bitop3_b32 v12, v12, v86, v83 bitop3:0x36
	v_lshlrev_b32_e32 v12, 4, v12
	v_add3_u32 v12, 0, v12, v13
	ds_read_b128 v[96:99], v12
	v_mfma_f32_16x16x32_bf16 v[12:15], v[88:91], v[0:3], v[8:11]
	v_add_u32_e32 v89, 0x22100, v80
	s_waitcnt lgkmcnt(1)
	v_mfma_f32_16x16x32_bf16 v[8:11], v[92:95], v[4:7], 0
	v_or_b32_e32 v95, s18, v79
	v_med3_u32 v80, v95, 8, 56
	v_add_u32_e32 v94, -8, v80
	s_waitcnt lgkmcnt(0)
	v_mfma_f32_16x16x32_bf16 v[8:11], v[96:99], v[0:3], v[8:11]
	v_lshl_add_u32 v97, v81, 3, v84
	v_add_u32_e32 v96, 8, v80
	v_sub_u32_e32 v80, v97, v95
	v_med3_i32 v80, v80, -15, 15
	v_cmp_ge_i32_e32 vcc, v97, v94
	v_cmp_lt_i32_e64 s[0:1], v97, v96
	v_add_u32_e32 v80, 15, v80
	s_and_b64 vcc, vcc, s[0:1]
	v_cndmask_b32_e32 v82, -1, v80, vcc
	v_cmp_lt_i32_e32 vcc, -1, v82
	v_mov_b32_e32 v80, 0xf149f2ca
	v_lshl_add_u32 v82, v82, 2, v89
	s_and_saveexec_b64 s[0:1], vcc
	s_nop 0
	ds_read_b32 v91, v82 offset:372
	s_mov_b32 s4, 0x3e38aa3b
	v_mov_b32_e32 v90, v68
	s_mov_b32 s5, 0x3fb8aa3b
	s_waitcnt lgkmcnt(0)
	v_pk_mul_f32 v[90:91], v[90:91], s[4:5]
	s_nop 0
	v_add_f32_e32 v87, v90, v91
.LBB0_1441:
	s_or_b64 exec, exec, s[0:1]
	v_or_b32_e32 v68, 1, v97
	v_sub_u32_e32 v83, v68, v95
	v_med3_i32 v83, v83, -15, 15
	v_cmp_ge_i32_e64 s[0:1], v68, v94
	v_cmp_lt_i32_e64 s[4:5], v68, v96
	v_add_u32_e32 v68, 15, v83
	s_and_b64 s[0:1], s[0:1], s[4:5]
	v_cndmask_b32_e64 v68, -1, v68, s[0:1]
	v_cmp_lt_i32_e64 s[4:5], -1, v68
	v_lshl_add_u32 v83, v68, 2, v89
	s_and_saveexec_b64 s[0:1], s[4:5]
	s_nop 0
	ds_read_b32 v91, v83 offset:372
	s_mov_b32 s6, 0x3e38aa3b
	v_mov_b32_e32 v90, v69
	s_mov_b32 s7, 0x3fb8aa3b
	s_waitcnt lgkmcnt(0)
	v_pk_mul_f32 v[68:69], v[90:91], s[6:7]
	s_nop 0
	v_add_f32_e32 v80, v68, v69
.LBB0_1443:
	s_or_b64 exec, exec, s[0:1]
	v_or_b32_e32 v68, 2, v97
	v_sub_u32_e32 v69, v68, v95
	v_med3_i32 v69, v69, -15, 15
	v_cmp_ge_i32_e64 s[0:1], v68, v94
	v_cmp_lt_i32_e64 s[6:7], v68, v96
	v_add_u32_e32 v68, 15, v69
	s_and_b64 s[0:1], s[0:1], s[6:7]
	v_cndmask_b32_e64 v69, -1, v68, s[0:1]
	v_cmp_lt_i32_e64 s[6:7], -1, v69
	v_mov_b32_e32 v68, 0xf149f2ca
	v_lshl_add_u32 v88, v69, 2, v89
	v_mov_b32_e32 v69, 0xf149f2ca
	s_and_saveexec_b64 s[0:1], s[6:7]
	s_nop 0
	ds_read_b32 v91, v88 offset:372
	s_mov_b32 s8, 0x3e38aa3b
	v_mov_b32_e32 v90, v70
	s_mov_b32 s9, 0x3fb8aa3b
	s_waitcnt lgkmcnt(0)
	v_pk_mul_f32 v[90:91], v[90:91], s[8:9]
	s_nop 0
	v_add_f32_e32 v69, v90, v91
.LBB0_1445:
	s_or_b64 exec, exec, s[0:1]
	v_or_b32_e32 v70, 3, v97
	v_sub_u32_e32 v90, v70, v95
	v_med3_i32 v90, v90, -15, 15
	v_cmp_ge_i32_e64 s[0:1], v70, v94
	v_cmp_lt_i32_e64 s[8:9], v70, v96
	v_add_u32_e32 v70, 15, v90
	s_and_b64 s[0:1], s[0:1], s[8:9]
	v_cndmask_b32_e64 v70, -1, v70, s[0:1]
	v_cmp_lt_i32_e64 s[8:9], -1, v70
	v_lshl_add_u32 v90, v70, 2, v89
	s_and_saveexec_b64 s[0:1], s[8:9]
	s_nop 0
	ds_read_b32 v93, v90 offset:372
	s_mov_b32 s10, 0x3e38aa3b
	v_mov_b32_e32 v92, v71
	s_mov_b32 s11, 0x3fb8aa3b
	s_waitcnt lgkmcnt(0)
	v_pk_mul_f32 v[70:71], v[92:93], s[10:11]
	s_nop 0
	v_add_f32_e32 v68, v70, v71
.LBB0_1447:
	s_or_b64 exec, exec, s[0:1]
	v_or_b32_e32 v70, 4, v97
	v_sub_u32_e32 v71, v70, v95
	v_med3_i32 v71, v71, -15, 15
	v_cmp_ge_i32_e64 s[0:1], v70, v94
	v_cmp_lt_i32_e64 s[10:11], v70, v96
	v_add_u32_e32 v70, 15, v71
	s_and_b64 s[0:1], s[0:1], s[10:11]
	v_cndmask_b32_e64 v71, -1, v70, s[0:1]
	v_cmp_lt_i32_e64 s[10:11], -1, v71
	v_mov_b32_e32 v70, 0xf149f2ca
	v_lshl_add_u32 v91, v71, 2, v89
	v_mov_b32_e32 v71, 0xf149f2ca
	s_and_saveexec_b64 s[0:1], s[10:11]
	s_nop 0
	ds_read_b32 v93, v91 offset:372
	s_mov_b32 s12, 0x3e38aa3b
	v_mov_b32_e32 v92, v64
	s_mov_b32 s13, 0x3fb8aa3b
	s_waitcnt lgkmcnt(0)
	v_pk_mul_f32 v[92:93], v[92:93], s[12:13]
	s_nop 0
	v_add_f32_e32 v71, v92, v93
.LBB0_1449:
	s_or_b64 exec, exec, s[0:1]
	v_or_b32_e32 v64, 5, v97
	v_sub_u32_e32 v92, v64, v95
	v_med3_i32 v92, v92, -15, 15
	v_cmp_ge_i32_e64 s[0:1], v64, v94
	v_cmp_lt_i32_e64 s[12:13], v64, v96
	v_add_u32_e32 v64, 15, v92
	s_and_b64 s[0:1], s[0:1], s[12:13]
	v_cndmask_b32_e64 v64, -1, v64, s[0:1]
	v_cmp_lt_i32_e64 s[12:13], -1, v64
	v_lshl_add_u32 v92, v64, 2, v89
	s_and_saveexec_b64 s[0:1], s[12:13]
	s_nop 0
	ds_read_b32 v99, v92 offset:372
	s_mov_b32 s14, 0x3e38aa3b
	v_mov_b32_e32 v98, v65
	s_mov_b32 s15, 0x3fb8aa3b
	s_waitcnt lgkmcnt(0)
	v_pk_mul_f32 v[64:65], v[98:99], s[14:15]
	s_nop 0
	v_add_f32_e32 v70, v64, v65
.LBB0_1451:
	s_or_b64 exec, exec, s[0:1]
	v_or_b32_e32 v64, 6, v97
	v_sub_u32_e32 v65, v64, v95
	v_med3_i32 v65, v65, -15, 15
	v_cmp_ge_i32_e64 s[0:1], v64, v94
	v_cmp_lt_i32_e64 s[14:15], v64, v96
	v_add_u32_e32 v64, 15, v65
	s_and_b64 s[0:1], s[0:1], s[14:15]
	v_cndmask_b32_e64 v65, -1, v64, s[0:1]
	v_cmp_lt_i32_e64 s[14:15], -1, v65
	v_mov_b32_e32 v64, 0xf149f2ca
	v_lshl_add_u32 v93, v65, 2, v89
	v_mov_b32_e32 v65, 0xf149f2ca
	s_and_saveexec_b64 s[0:1], s[14:15]
	s_nop 0
	ds_read_b32 v99, v93 offset:372
	s_mov_b32 s16, 0x3e38aa3b
	v_mov_b32_e32 v98, v66
	s_mov_b32 s17, 0x3fb8aa3b
	s_waitcnt lgkmcnt(0)
	v_pk_mul_f32 v[98:99], v[98:99], s[16:17]
	s_nop 0
	v_add_f32_e32 v65, v98, v99
.LBB0_1453:
	s_or_b64 exec, exec, s[0:1]
	v_or_b32_e32 v66, 7, v97
	v_sub_u32_e32 v95, v66, v95
	v_med3_i32 v95, v95, -15, 15
	v_cmp_ge_i32_e64 s[0:1], v66, v94
	v_cmp_lt_i32_e64 s[16:17], v66, v96
	v_add_u32_e32 v66, 15, v95
	s_and_b64 s[0:1], s[0:1], s[16:17]
	v_cndmask_b32_e64 v66, -1, v66, s[0:1]
	v_cmp_lt_i32_e64 s[16:17], -1, v66
	v_lshl_add_u32 v94, v66, 2, v89
	s_and_saveexec_b64 s[0:1], s[16:17]
	s_nop 0
	ds_read_b32 v97, v94 offset:372
	s_mov_b32 s34, 0x3e38aa3b
	v_mov_b32_e32 v96, v67
	s_mov_b32 s35, 0x3fb8aa3b
	s_waitcnt lgkmcnt(0)
	v_pk_mul_f32 v[66:67], v[96:97], s[34:35]
	s_nop 0
	v_add_f32_e32 v64, v66, v67
.LBB0_1455:
	s_or_b64 exec, exec, s[0:1]
	v_mov_b32_e32 v66, 0xf149f2ca
	v_mov_b32_e32 v67, 0xf149f2ca
	ds_read_b32 v176, v82 offset:496
	ds_read_b32 v177, v83 offset:496
	ds_read_b32 v178, v88 offset:496
	ds_read_b32 v179, v90 offset:496
	ds_read_b32 v180, v91 offset:496
	ds_read_b32 v181, v92 offset:496
	ds_read_b32 v182, v93 offset:496
	ds_read_b32 v183, v94 offset:496
	s_waitcnt lgkmcnt(0)
	s_and_saveexec_b64 s[0:1], vcc
	s_nop 0
	v_mov_b32_e32 v97, v176
	s_mov_b32 s34, 0x3e38aa3b
	v_mov_b32_e32 v96, v60
	s_mov_b32 s35, 0x3fb8aa3b
	s_waitcnt lgkmcnt(0)
	v_pk_mul_f32 v[96:97], v[96:97], s[34:35]
	s_nop 0
	v_add_f32_e32 v67, v96, v97
.LBB0_1457:
	s_or_b64 exec, exec, s[0:1]
	s_and_saveexec_b64 s[0:1], s[4:5]
	s_nop 0
	v_mov_b32_e32 v97, v177
	s_mov_b32 s34, 0x3e38aa3b
	v_mov_b32_e32 v96, v61
	s_mov_b32 s35, 0x3fb8aa3b
	s_waitcnt lgkmcnt(0)
	v_pk_mul_f32 v[60:61], v[96:97], s[34:35]
	s_nop 0
	v_add_f32_e32 v66, v60, v61
.LBB0_1459:
	s_or_b64 exec, exec, s[0:1]
	v_mov_b32_e32 v60, 0xf149f2ca
	v_mov_b32_e32 v61, 0xf149f2ca
	s_and_saveexec_b64 s[0:1], s[6:7]
	s_nop 0
	v_mov_b32_e32 v97, v178
	s_mov_b32 s34, 0x3e38aa3b
	v_mov_b32_e32 v96, v62
	s_mov_b32 s35, 0x3fb8aa3b
	s_waitcnt lgkmcnt(0)
	v_pk_mul_f32 v[96:97], v[96:97], s[34:35]
	s_nop 0
	v_add_f32_e32 v61, v96, v97
.LBB0_1461:
	s_or_b64 exec, exec, s[0:1]
	s_and_saveexec_b64 s[0:1], s[8:9]
	s_nop 0
	v_mov_b32_e32 v97, v179
	s_mov_b32 s34, 0x3e38aa3b
	v_mov_b32_e32 v96, v63
	s_mov_b32 s35, 0x3fb8aa3b
	s_waitcnt lgkmcnt(0)
	v_pk_mul_f32 v[62:63], v[96:97], s[34:35]
	s_nop 0
	v_add_f32_e32 v60, v62, v63
.LBB0_1463:
	s_or_b64 exec, exec, s[0:1]
	v_mov_b32_e32 v62, 0xf149f2ca
	v_mov_b32_e32 v63, 0xf149f2ca
	s_and_saveexec_b64 s[0:1], s[10:11]
	s_nop 0
	v_mov_b32_e32 v97, v180
	s_mov_b32 s34, 0x3e38aa3b
	v_mov_b32_e32 v96, v56
	s_mov_b32 s35, 0x3fb8aa3b
	s_waitcnt lgkmcnt(0)
	v_pk_mul_f32 v[96:97], v[96:97], s[34:35]
	s_nop 0
	v_add_f32_e32 v63, v96, v97
.LBB0_1465:
	s_or_b64 exec, exec, s[0:1]
	s_and_saveexec_b64 s[0:1], s[12:13]
	s_nop 0
	v_mov_b32_e32 v97, v181
	s_mov_b32 s34, 0x3e38aa3b
	v_mov_b32_e32 v96, v57
	s_mov_b32 s35, 0x3fb8aa3b
	s_waitcnt lgkmcnt(0)
	v_pk_mul_f32 v[56:57], v[96:97], s[34:35]
	s_nop 0
	v_add_f32_e32 v62, v56, v57
.LBB0_1467:
	s_or_b64 exec, exec, s[0:1]
	v_mov_b32_e32 v56, 0xf149f2ca
	v_mov_b32_e32 v89, 0xf149f2ca
	s_and_saveexec_b64 s[0:1], s[14:15]
	s_nop 0
	v_mov_b32_e32 v97, v182
	s_mov_b32 s34, 0x3e38aa3b
	v_mov_b32_e32 v96, v58
	s_mov_b32 s35, 0x3fb8aa3b
	s_waitcnt lgkmcnt(0)
	v_pk_mul_f32 v[96:97], v[96:97], s[34:35]
	s_nop 0
	v_add_f32_e32 v89, v96, v97
.LBB0_1469:
	s_or_b64 exec, exec, s[0:1]
	s_and_saveexec_b64 s[0:1], s[16:17]
	s_nop 0
	v_mov_b32_e32 v57, v183
	s_mov_b32 s34, 0x3e38aa3b
	v_mov_b32_e32 v56, v59
	s_mov_b32 s35, 0x3fb8aa3b
	s_waitcnt lgkmcnt(0)
	v_pk_mul_f32 v[56:57], v[56:57], s[34:35]
	s_nop 0
	v_add_f32_e32 v56, v56, v57
.LBB0_1471:
	s_or_b64 exec, exec, s[0:1]
	v_mov_b32_e32 v57, 0xf149f2ca
	v_mov_b32_e32 v58, 0xf149f2ca
	ds_read_b32 v176, v82 offset:620
	ds_read_b32 v177, v83 offset:620
	ds_read_b32 v178, v88 offset:620
	ds_read_b32 v179, v90 offset:620
	ds_read_b32 v180, v91 offset:620
	ds_read_b32 v181, v92 offset:620
	ds_read_b32 v182, v93 offset:620
	ds_read_b32 v183, v94 offset:620
	s_waitcnt lgkmcnt(0)
	s_and_saveexec_b64 s[0:1], vcc
	s_nop 0
	v_mov_b32_e32 v59, v176
	s_mov_b32 s34, 0x3e38aa3b
	v_mov_b32_e32 v58, v52
	s_mov_b32 s35, 0x3fb8aa3b
	s_waitcnt lgkmcnt(0)
	v_pk_mul_f32 v[58:59], v[58:59], s[34:35]
	s_nop 0
	v_add_f32_e32 v58, v58, v59
.LBB0_1473:
	s_or_b64 exec, exec, s[0:1]
	s_and_saveexec_b64 s[0:1], s[4:5]
	s_nop 0
	v_mov_b32_e32 v97, v177
	s_mov_b32 s34, 0x3e38aa3b
	v_mov_b32_e32 v96, v53
	s_mov_b32 s35, 0x3fb8aa3b
	s_waitcnt lgkmcnt(0)
	v_pk_mul_f32 v[52:53], v[96:97], s[34:35]
	s_nop 0
	v_add_f32_e32 v57, v52, v53
.LBB0_1475:
	s_or_b64 exec, exec, s[0:1]
	v_mov_b32_e32 v52, 0xf149f2ca
	v_mov_b32_e32 v53, 0xf149f2ca
	s_and_saveexec_b64 s[0:1], s[6:7]
	s_nop 0
	v_mov_b32_e32 v97, v178
	s_mov_b32 s34, 0x3e38aa3b
	v_mov_b32_e32 v96, v54
	s_mov_b32 s35, 0x3fb8aa3b
	s_waitcnt lgkmcnt(0)
	v_pk_mul_f32 v[96:97], v[96:97], s[34:35]
	s_nop 0
	v_add_f32_e32 v53, v96, v97
.LBB0_1477:
	s_or_b64 exec, exec, s[0:1]
	s_and_saveexec_b64 s[0:1], s[8:9]
	s_nop 0
	v_mov_b32_e32 v97, v179
	s_mov_b32 s34, 0x3e38aa3b
	v_mov_b32_e32 v96, v55
	s_mov_b32 s35, 0x3fb8aa3b
	s_waitcnt lgkmcnt(0)
	v_pk_mul_f32 v[54:55], v[96:97], s[34:35]
	s_nop 0
	v_add_f32_e32 v52, v54, v55
.LBB0_1479:
	s_or_b64 exec, exec, s[0:1]
	v_mov_b32_e32 v54, 0xf149f2ca
	v_mov_b32_e32 v55, 0xf149f2ca
	s_and_saveexec_b64 s[0:1], s[10:11]
	s_nop 0
	v_mov_b32_e32 v97, v180
	s_mov_b32 s34, 0x3e38aa3b
	v_mov_b32_e32 v96, v48
	s_mov_b32 s35, 0x3fb8aa3b
	s_waitcnt lgkmcnt(0)
	v_pk_mul_f32 v[96:97], v[96:97], s[34:35]
	s_nop 0
	v_add_f32_e32 v55, v96, v97
.LBB0_1481:
	s_or_b64 exec, exec, s[0:1]
	s_and_saveexec_b64 s[0:1], s[12:13]
	s_nop 0
	v_mov_b32_e32 v97, v181
	s_mov_b32 s34, 0x3e38aa3b
	v_mov_b32_e32 v96, v49
	s_mov_b32 s35, 0x3fb8aa3b
	s_waitcnt lgkmcnt(0)
	v_pk_mul_f32 v[48:49], v[96:97], s[34:35]
	s_nop 0
	v_add_f32_e32 v54, v48, v49
.LBB0_1483:
	s_or_b64 exec, exec, s[0:1]
	v_mov_b32_e32 v48, 0xf149f2ca
	v_mov_b32_e32 v59, 0xf149f2ca
	s_and_saveexec_b64 s[0:1], s[14:15]
	s_nop 0
	v_mov_b32_e32 v97, v182
	s_mov_b32 s34, 0x3e38aa3b
	v_mov_b32_e32 v96, v50
	s_mov_b32 s35, 0x3fb8aa3b
	s_waitcnt lgkmcnt(0)
	v_pk_mul_f32 v[96:97], v[96:97], s[34:35]
	s_nop 0
	v_add_f32_e32 v59, v96, v97
.LBB0_1485:
	s_or_b64 exec, exec, s[0:1]
	s_and_saveexec_b64 s[0:1], s[16:17]
	s_nop 0
	v_mov_b32_e32 v49, v183
	s_mov_b32 s34, 0x3e38aa3b
	v_mov_b32_e32 v48, v51
	s_mov_b32 s35, 0x3fb8aa3b
	s_waitcnt lgkmcnt(0)
	v_pk_mul_f32 v[48:49], v[48:49], s[34:35]
	s_nop 0
	v_add_f32_e32 v48, v48, v49
.LBB0_1487:
	s_or_b64 exec, exec, s[0:1]
	v_mov_b32_e32 v49, 0xf149f2ca
	v_mov_b32_e32 v50, 0xf149f2ca
	ds_read_b32 v176, v82 offset:744
	ds_read_b32 v177, v83 offset:744
	ds_read_b32 v178, v88 offset:744
	ds_read_b32 v179, v90 offset:744
	ds_read_b32 v180, v91 offset:744
	ds_read_b32 v181, v92 offset:744
	ds_read_b32 v182, v93 offset:744
	ds_read_b32 v183, v94 offset:744
	s_waitcnt lgkmcnt(0)
	s_and_saveexec_b64 s[0:1], vcc
	s_nop 0
	v_mov_b32_e32 v51, v176
	s_mov_b32 s34, 0x3e38aa3b
	v_mov_b32_e32 v50, v44
	s_mov_b32 s35, 0x3fb8aa3b
	s_waitcnt lgkmcnt(0)
	v_pk_mul_f32 v[50:51], v[50:51], s[34:35]
	s_nop 0
	v_add_f32_e32 v50, v50, v51
.LBB0_1489:
	s_or_b64 exec, exec, s[0:1]
	s_and_saveexec_b64 s[0:1], s[4:5]
	s_nop 0
	v_mov_b32_e32 v97, v177
	s_mov_b32 s34, 0x3e38aa3b
	v_mov_b32_e32 v96, v45
	s_mov_b32 s35, 0x3fb8aa3b
	s_waitcnt lgkmcnt(0)
	v_pk_mul_f32 v[44:45], v[96:97], s[34:35]
	s_nop 0
	v_add_f32_e32 v49, v44, v45
.LBB0_1491:
	s_or_b64 exec, exec, s[0:1]
	v_mov_b32_e32 v44, 0xf149f2ca
	v_mov_b32_e32 v45, 0xf149f2ca
	s_and_saveexec_b64 s[0:1], s[6:7]
	s_nop 0
	v_mov_b32_e32 v97, v178
	s_mov_b32 s34, 0x3e38aa3b
	v_mov_b32_e32 v96, v46
	s_mov_b32 s35, 0x3fb8aa3b
	s_waitcnt lgkmcnt(0)
	v_pk_mul_f32 v[96:97], v[96:97], s[34:35]
	s_nop 0
	v_add_f32_e32 v45, v96, v97
.LBB0_1493:
	s_or_b64 exec, exec, s[0:1]
	s_and_saveexec_b64 s[0:1], s[8:9]
	s_nop 0
	v_mov_b32_e32 v97, v179
	s_mov_b32 s34, 0x3e38aa3b
	v_mov_b32_e32 v96, v47
	s_mov_b32 s35, 0x3fb8aa3b
	s_waitcnt lgkmcnt(0)
	v_pk_mul_f32 v[46:47], v[96:97], s[34:35]
	s_nop 0
	v_add_f32_e32 v44, v46, v47
.LBB0_1495:
	s_or_b64 exec, exec, s[0:1]
	v_mov_b32_e32 v46, 0xf149f2ca
	v_mov_b32_e32 v47, 0xf149f2ca
	s_and_saveexec_b64 s[0:1], s[10:11]
	s_nop 0
	v_mov_b32_e32 v97, v180
	s_mov_b32 s34, 0x3e38aa3b
	v_mov_b32_e32 v96, v40
	s_mov_b32 s35, 0x3fb8aa3b
	s_waitcnt lgkmcnt(0)
	v_pk_mul_f32 v[96:97], v[96:97], s[34:35]
	s_nop 0
	v_add_f32_e32 v47, v96, v97
.LBB0_1497:
	s_or_b64 exec, exec, s[0:1]
	s_and_saveexec_b64 s[0:1], s[12:13]
	s_nop 0
	v_mov_b32_e32 v97, v181
	s_mov_b32 s34, 0x3e38aa3b
	v_mov_b32_e32 v96, v41
	s_mov_b32 s35, 0x3fb8aa3b
	s_waitcnt lgkmcnt(0)
	v_pk_mul_f32 v[40:41], v[96:97], s[34:35]
	s_nop 0
	v_add_f32_e32 v46, v40, v41
.LBB0_1499:
	s_or_b64 exec, exec, s[0:1]
	v_mov_b32_e32 v40, 0xf149f2ca
	v_mov_b32_e32 v51, 0xf149f2ca
	s_and_saveexec_b64 s[0:1], s[14:15]
	s_nop 0
	v_mov_b32_e32 v97, v182
	s_mov_b32 s34, 0x3e38aa3b
	v_mov_b32_e32 v96, v42
	s_mov_b32 s35, 0x3fb8aa3b
	s_waitcnt lgkmcnt(0)
	v_pk_mul_f32 v[96:97], v[96:97], s[34:35]
	s_nop 0
	v_add_f32_e32 v51, v96, v97
.LBB0_1501:
	s_or_b64 exec, exec, s[0:1]
	s_and_saveexec_b64 s[0:1], s[16:17]
	s_nop 0
	v_mov_b32_e32 v41, v183
	s_mov_b32 s34, 0x3e38aa3b
	v_mov_b32_e32 v40, v43
	s_mov_b32 s35, 0x3fb8aa3b
	s_waitcnt lgkmcnt(0)
	v_pk_mul_f32 v[40:41], v[40:41], s[34:35]
	s_nop 0
	v_add_f32_e32 v40, v40, v41
.LBB0_1503:
	s_or_b64 exec, exec, s[0:1]
	v_mov_b32_e32 v41, 0xf149f2ca
	v_mov_b32_e32 v42, 0xf149f2ca
	ds_read_b32 v176, v82 offset:868
	ds_read_b32 v177, v83 offset:868
	ds_read_b32 v178, v88 offset:868
	ds_read_b32 v179, v90 offset:868
	ds_read_b32 v180, v91 offset:868
	ds_read_b32 v181, v92 offset:868
	ds_read_b32 v182, v93 offset:868
	ds_read_b32 v183, v94 offset:868
	s_waitcnt lgkmcnt(0)
	s_and_saveexec_b64 s[0:1], vcc
	s_nop 0
	v_mov_b32_e32 v43, v176
	s_mov_b32 s34, 0x3e38aa3b
	v_mov_b32_e32 v42, v36
	s_mov_b32 s35, 0x3fb8aa3b
	s_waitcnt lgkmcnt(0)
	v_pk_mul_f32 v[42:43], v[42:43], s[34:35]
	s_nop 0
	v_add_f32_e32 v42, v42, v43
.LBB0_1505:
	s_or_b64 exec, exec, s[0:1]
	s_and_saveexec_b64 s[0:1], s[4:5]
	s_nop 0
	v_mov_b32_e32 v97, v177
	s_mov_b32 s34, 0x3e38aa3b
	v_mov_b32_e32 v96, v37
	s_mov_b32 s35, 0x3fb8aa3b
	s_waitcnt lgkmcnt(0)
	v_pk_mul_f32 v[36:37], v[96:97], s[34:35]
	s_nop 0
	v_add_f32_e32 v41, v36, v37
.LBB0_1507:
	s_or_b64 exec, exec, s[0:1]
	v_mov_b32_e32 v36, 0xf149f2ca
	v_mov_b32_e32 v37, 0xf149f2ca
	s_and_saveexec_b64 s[0:1], s[6:7]
	s_nop 0
	v_mov_b32_e32 v97, v178
	s_mov_b32 s34, 0x3e38aa3b
	v_mov_b32_e32 v96, v38
	s_mov_b32 s35, 0x3fb8aa3b
	s_waitcnt lgkmcnt(0)
	v_pk_mul_f32 v[96:97], v[96:97], s[34:35]
	s_nop 0
	v_add_f32_e32 v37, v96, v97
.LBB0_1509:
	s_or_b64 exec, exec, s[0:1]
	s_and_saveexec_b64 s[0:1], s[8:9]
	s_nop 0
	v_mov_b32_e32 v97, v179
	s_mov_b32 s34, 0x3e38aa3b
	v_mov_b32_e32 v96, v39
	s_mov_b32 s35, 0x3fb8aa3b
	s_waitcnt lgkmcnt(0)
	v_pk_mul_f32 v[38:39], v[96:97], s[34:35]
	s_nop 0
	v_add_f32_e32 v36, v38, v39
.LBB0_1511:
	s_or_b64 exec, exec, s[0:1]
	v_mov_b32_e32 v38, 0xf149f2ca
	v_mov_b32_e32 v39, 0xf149f2ca
	s_and_saveexec_b64 s[0:1], s[10:11]
	s_nop 0
	v_mov_b32_e32 v97, v180
	s_mov_b32 s34, 0x3e38aa3b
	v_mov_b32_e32 v96, v32
	s_mov_b32 s35, 0x3fb8aa3b
	s_waitcnt lgkmcnt(0)
	v_pk_mul_f32 v[96:97], v[96:97], s[34:35]
	s_nop 0
	v_add_f32_e32 v39, v96, v97
.LBB0_1513:
	s_or_b64 exec, exec, s[0:1]
	s_and_saveexec_b64 s[0:1], s[12:13]
	s_nop 0
	v_mov_b32_e32 v97, v181
	s_mov_b32 s34, 0x3e38aa3b
	v_mov_b32_e32 v96, v33
	s_mov_b32 s35, 0x3fb8aa3b
	s_waitcnt lgkmcnt(0)
	v_pk_mul_f32 v[32:33], v[96:97], s[34:35]
	s_nop 0
	v_add_f32_e32 v38, v32, v33
.LBB0_1515:
	s_or_b64 exec, exec, s[0:1]
	v_mov_b32_e32 v32, 0xf149f2ca
	v_mov_b32_e32 v43, 0xf149f2ca
	s_and_saveexec_b64 s[0:1], s[14:15]
	s_nop 0
	v_mov_b32_e32 v97, v182
	s_mov_b32 s34, 0x3e38aa3b
	v_mov_b32_e32 v96, v34
	s_mov_b32 s35, 0x3fb8aa3b
	s_waitcnt lgkmcnt(0)
	v_pk_mul_f32 v[96:97], v[96:97], s[34:35]
	s_nop 0
	v_add_f32_e32 v43, v96, v97
.LBB0_1517:
	s_or_b64 exec, exec, s[0:1]
	s_and_saveexec_b64 s[0:1], s[16:17]
	s_nop 0
	v_mov_b32_e32 v33, v183
	s_mov_b32 s34, 0x3e38aa3b
	v_mov_b32_e32 v32, v35
	s_mov_b32 s35, 0x3fb8aa3b
	s_waitcnt lgkmcnt(0)
	v_pk_mul_f32 v[32:33], v[32:33], s[34:35]
	s_nop 0
	v_add_f32_e32 v32, v32, v33
.LBB0_1519:
	s_or_b64 exec, exec, s[0:1]
	v_mov_b32_e32 v33, 0xf149f2ca
	v_mov_b32_e32 v34, 0xf149f2ca
	ds_read_b32 v176, v82 offset:992
	ds_read_b32 v177, v83 offset:992
	ds_read_b32 v178, v88 offset:992
	ds_read_b32 v179, v90 offset:992
	ds_read_b32 v180, v91 offset:992
	ds_read_b32 v181, v92 offset:992
	ds_read_b32 v182, v93 offset:992
	ds_read_b32 v183, v94 offset:992
	s_waitcnt lgkmcnt(0)
	s_and_saveexec_b64 s[0:1], vcc
	s_nop 0
	v_mov_b32_e32 v35, v176
	s_mov_b32 s34, 0x3e38aa3b
	v_mov_b32_e32 v34, v28
	s_mov_b32 s35, 0x3fb8aa3b
	s_waitcnt lgkmcnt(0)
	v_pk_mul_f32 v[34:35], v[34:35], s[34:35]
	s_nop 0
	v_add_f32_e32 v34, v34, v35
.LBB0_1521:
	s_or_b64 exec, exec, s[0:1]
	s_and_saveexec_b64 s[0:1], s[4:5]
	s_nop 0
	v_mov_b32_e32 v97, v177
	s_mov_b32 s34, 0x3e38aa3b
	v_mov_b32_e32 v96, v29
	s_mov_b32 s35, 0x3fb8aa3b
	s_waitcnt lgkmcnt(0)
	v_pk_mul_f32 v[28:29], v[96:97], s[34:35]
	s_nop 0
	v_add_f32_e32 v33, v28, v29
.LBB0_1523:
	s_or_b64 exec, exec, s[0:1]
	v_mov_b32_e32 v28, 0xf149f2ca
	v_mov_b32_e32 v29, 0xf149f2ca
	s_and_saveexec_b64 s[0:1], s[6:7]
	s_nop 0
	v_mov_b32_e32 v97, v178
	s_mov_b32 s34, 0x3e38aa3b
	v_mov_b32_e32 v96, v30
	s_mov_b32 s35, 0x3fb8aa3b
	s_waitcnt lgkmcnt(0)
	v_pk_mul_f32 v[96:97], v[96:97], s[34:35]
	s_nop 0
	v_add_f32_e32 v29, v96, v97
.LBB0_1525:
	s_or_b64 exec, exec, s[0:1]
	s_and_saveexec_b64 s[0:1], s[8:9]
	s_nop 0
	v_mov_b32_e32 v97, v179
	s_mov_b32 s34, 0x3e38aa3b
	v_mov_b32_e32 v96, v31
	s_mov_b32 s35, 0x3fb8aa3b
	s_waitcnt lgkmcnt(0)
	v_pk_mul_f32 v[30:31], v[96:97], s[34:35]
	s_nop 0
	v_add_f32_e32 v28, v30, v31
.LBB0_1527:
	s_or_b64 exec, exec, s[0:1]
	v_mov_b32_e32 v30, 0xf149f2ca
	v_mov_b32_e32 v31, 0xf149f2ca
	s_and_saveexec_b64 s[0:1], s[10:11]
	s_nop 0
	v_mov_b32_e32 v97, v180
	s_mov_b32 s34, 0x3e38aa3b
	v_mov_b32_e32 v96, v24
	s_mov_b32 s35, 0x3fb8aa3b
	s_waitcnt lgkmcnt(0)
	v_pk_mul_f32 v[96:97], v[96:97], s[34:35]
	s_nop 0
	v_add_f32_e32 v31, v96, v97
.LBB0_1529:
	s_or_b64 exec, exec, s[0:1]
	s_and_saveexec_b64 s[0:1], s[12:13]
	s_nop 0
	v_mov_b32_e32 v97, v181
	s_mov_b32 s34, 0x3e38aa3b
	v_mov_b32_e32 v96, v25
	s_mov_b32 s35, 0x3fb8aa3b
	s_waitcnt lgkmcnt(0)
	v_pk_mul_f32 v[24:25], v[96:97], s[34:35]
	s_nop 0
	v_add_f32_e32 v30, v24, v25
.LBB0_1531:
	s_or_b64 exec, exec, s[0:1]
	v_mov_b32_e32 v24, 0xf149f2ca
	v_mov_b32_e32 v35, 0xf149f2ca
	s_and_saveexec_b64 s[0:1], s[14:15]
	s_nop 0
	v_mov_b32_e32 v97, v182
	s_mov_b32 s34, 0x3e38aa3b
	v_mov_b32_e32 v96, v26
	s_mov_b32 s35, 0x3fb8aa3b
	s_waitcnt lgkmcnt(0)
	v_pk_mul_f32 v[96:97], v[96:97], s[34:35]
	s_nop 0
	v_add_f32_e32 v35, v96, v97
.LBB0_1533:
	s_or_b64 exec, exec, s[0:1]
	s_and_saveexec_b64 s[0:1], s[16:17]
	s_nop 0
	v_mov_b32_e32 v25, v183
	s_mov_b32 s34, 0x3e38aa3b
	v_mov_b32_e32 v24, v27
	s_mov_b32 s35, 0x3fb8aa3b
	s_waitcnt lgkmcnt(0)
	v_pk_mul_f32 v[24:25], v[24:25], s[34:35]
	s_nop 0
	v_add_f32_e32 v24, v24, v25
.LBB0_1535:
	s_or_b64 exec, exec, s[0:1]
	v_mov_b32_e32 v25, 0xf149f2ca
	v_mov_b32_e32 v26, 0xf149f2ca
	ds_read_b32 v176, v82 offset:1116
	ds_read_b32 v177, v83 offset:1116
	ds_read_b32 v178, v88 offset:1116
	ds_read_b32 v179, v90 offset:1116
	ds_read_b32 v180, v91 offset:1116
	ds_read_b32 v181, v92 offset:1116
	ds_read_b32 v182, v93 offset:1116
	ds_read_b32 v183, v94 offset:1116
	s_waitcnt lgkmcnt(0)
	s_and_saveexec_b64 s[0:1], vcc
	s_nop 0
	v_mov_b32_e32 v27, v176
	s_mov_b32 s34, 0x3e38aa3b
	v_mov_b32_e32 v26, v20
	s_mov_b32 s35, 0x3fb8aa3b
	s_waitcnt lgkmcnt(0)
	v_pk_mul_f32 v[26:27], v[26:27], s[34:35]
	s_nop 0
	v_add_f32_e32 v26, v26, v27
.LBB0_1537:
	s_or_b64 exec, exec, s[0:1]
	s_and_saveexec_b64 s[0:1], s[4:5]
	s_nop 0
	v_mov_b32_e32 v97, v177
	s_mov_b32 s34, 0x3e38aa3b
	v_mov_b32_e32 v96, v21
	s_mov_b32 s35, 0x3fb8aa3b
	s_waitcnt lgkmcnt(0)
	v_pk_mul_f32 v[20:21], v[96:97], s[34:35]
	s_nop 0
	v_add_f32_e32 v25, v20, v21
.LBB0_1539:
	s_or_b64 exec, exec, s[0:1]
	v_mov_b32_e32 v20, 0xf149f2ca
	v_mov_b32_e32 v21, 0xf149f2ca
	s_and_saveexec_b64 s[0:1], s[6:7]
	s_nop 0
	v_mov_b32_e32 v97, v178
	s_mov_b32 s34, 0x3e38aa3b
	v_mov_b32_e32 v96, v22
	s_mov_b32 s35, 0x3fb8aa3b
	s_waitcnt lgkmcnt(0)
	v_pk_mul_f32 v[96:97], v[96:97], s[34:35]
	s_nop 0
	v_add_f32_e32 v21, v96, v97
.LBB0_1541:
	s_or_b64 exec, exec, s[0:1]
	s_and_saveexec_b64 s[0:1], s[8:9]
	s_nop 0
	v_mov_b32_e32 v97, v179
	s_mov_b32 s34, 0x3e38aa3b
	v_mov_b32_e32 v96, v23
	s_mov_b32 s35, 0x3fb8aa3b
	s_waitcnt lgkmcnt(0)
	v_pk_mul_f32 v[22:23], v[96:97], s[34:35]
	s_nop 0
	v_add_f32_e32 v20, v22, v23
.LBB0_1543:
	s_or_b64 exec, exec, s[0:1]
	v_mov_b32_e32 v22, 0xf149f2ca
	v_mov_b32_e32 v23, 0xf149f2ca
	s_and_saveexec_b64 s[0:1], s[10:11]
	s_nop 0
	v_mov_b32_e32 v97, v180
	s_mov_b32 s34, 0x3e38aa3b
	v_mov_b32_e32 v96, v16
	s_mov_b32 s35, 0x3fb8aa3b
	s_waitcnt lgkmcnt(0)
	v_pk_mul_f32 v[96:97], v[96:97], s[34:35]
	s_nop 0
	v_add_f32_e32 v23, v96, v97
.LBB0_1545:
	s_or_b64 exec, exec, s[0:1]
	s_and_saveexec_b64 s[0:1], s[12:13]
	s_nop 0
	v_mov_b32_e32 v97, v181
	s_mov_b32 s34, 0x3e38aa3b
	v_mov_b32_e32 v96, v17
	s_mov_b32 s35, 0x3fb8aa3b
	s_waitcnt lgkmcnt(0)
	v_pk_mul_f32 v[16:17], v[96:97], s[34:35]
	s_nop 0
	v_add_f32_e32 v22, v16, v17
.LBB0_1547:
	s_or_b64 exec, exec, s[0:1]
	v_mov_b32_e32 v17, 0xf149f2ca
	v_mov_b32_e32 v27, 0xf149f2ca
	s_and_saveexec_b64 s[0:1], s[14:15]
	s_nop 0
	v_mov_b32_e32 v97, v182
	s_mov_b32 s34, 0x3e38aa3b
	v_mov_b32_e32 v96, v18
	s_mov_b32 s35, 0x3fb8aa3b
	s_waitcnt lgkmcnt(0)
	v_pk_mul_f32 v[96:97], v[96:97], s[34:35]
	s_nop 0
	v_add_f32_e32 v27, v96, v97
.LBB0_1549:
	s_or_b64 exec, exec, s[0:1]
	s_and_saveexec_b64 s[0:1], s[16:17]
	s_nop 0
	v_mov_b32_e32 v17, v183
	s_mov_b32 s34, 0x3e38aa3b
	v_mov_b32_e32 v16, v19
	s_mov_b32 s35, 0x3fb8aa3b
	s_waitcnt lgkmcnt(0)
	v_pk_mul_f32 v[16:17], v[16:17], s[34:35]
	s_nop 0
	v_add_f32_e32 v17, v16, v17
.LBB0_1551:
	s_or_b64 exec, exec, s[0:1]
	v_mov_b32_e32 v16, 0xf149f2ca
	v_mov_b32_e32 v18, 0xf149f2ca
	ds_read_b32 v176, v82 offset:1240
	ds_read_b32 v177, v83 offset:1240
	ds_read_b32 v178, v88 offset:1240
	ds_read_b32 v179, v90 offset:1240
	ds_read_b32 v180, v91 offset:1240
	ds_read_b32 v181, v92 offset:1240
	ds_read_b32 v182, v93 offset:1240
	ds_read_b32 v183, v94 offset:1240
	s_waitcnt lgkmcnt(0)
	s_and_saveexec_b64 s[0:1], vcc
	s_nop 0
	v_mov_b32_e32 v19, v176
	s_mov_b32 s34, 0x3e38aa3b
	v_mov_b32_e32 v18, v12
	s_mov_b32 s35, 0x3fb8aa3b
	s_waitcnt lgkmcnt(0)
	v_pk_mul_f32 v[18:19], v[18:19], s[34:35]
	s_nop 0
	v_add_f32_e32 v18, v18, v19
.LBB0_1553:
	s_or_b64 exec, exec, s[0:1]
	s_and_saveexec_b64 s[0:1], s[4:5]
	s_nop 0
	v_mov_b32_e32 v83, v177
	s_mov_b32 s4, 0x3e38aa3b
	v_mov_b32_e32 v82, v13
	s_mov_b32 s5, 0x3fb8aa3b
	s_waitcnt lgkmcnt(0)
	v_pk_mul_f32 v[12:13], v[82:83], s[4:5]
	s_nop 0
	v_add_f32_e32 v16, v12, v13
.LBB0_1555:
	s_or_b64 exec, exec, s[0:1]
	v_mov_b32_e32 v12, 0xf149f2ca
	v_mov_b32_e32 v13, 0xf149f2ca
	s_and_saveexec_b64 s[0:1], s[6:7]
	s_nop 0
	v_mov_b32_e32 v83, v178
	s_mov_b32 s4, 0x3e38aa3b
	v_mov_b32_e32 v82, v14
	s_mov_b32 s5, 0x3fb8aa3b
	s_waitcnt lgkmcnt(0)
	v_pk_mul_f32 v[82:83], v[82:83], s[4:5]
	s_nop 0
	v_add_f32_e32 v13, v82, v83
.LBB0_1557:
	s_or_b64 exec, exec, s[0:1]
	s_and_saveexec_b64 s[0:1], s[8:9]
	s_nop 0
	v_mov_b32_e32 v83, v179
	s_mov_b32 s4, 0x3e38aa3b
	v_mov_b32_e32 v82, v15
	s_mov_b32 s5, 0x3fb8aa3b
	s_waitcnt lgkmcnt(0)
	v_pk_mul_f32 v[14:15], v[82:83], s[4:5]
	s_nop 0
	v_add_f32_e32 v12, v14, v15
.LBB0_1559:
	s_or_b64 exec, exec, s[0:1]
	v_mov_b32_e32 v14, 0xf149f2ca
	v_mov_b32_e32 v15, 0xf149f2ca
	s_and_saveexec_b64 s[0:1], s[10:11]
	s_nop 0
	v_mov_b32_e32 v83, v180
	s_mov_b32 s4, 0x3e38aa3b
	v_mov_b32_e32 v82, v8
	s_mov_b32 s5, 0x3fb8aa3b
	s_waitcnt lgkmcnt(0)
	v_pk_mul_f32 v[82:83], v[82:83], s[4:5]
	s_nop 0
	v_add_f32_e32 v15, v82, v83
.LBB0_1561:
	s_or_b64 exec, exec, s[0:1]
	s_and_saveexec_b64 s[0:1], s[12:13]
	s_nop 0
	v_mov_b32_e32 v83, v181
	s_mov_b32 s4, 0x3e38aa3b
	v_mov_b32_e32 v82, v9
	s_mov_b32 s5, 0x3fb8aa3b
	s_waitcnt lgkmcnt(0)
	v_pk_mul_f32 v[8:9], v[82:83], s[4:5]
	s_nop 0
	v_add_f32_e32 v14, v8, v9
.LBB0_1563:
	s_or_b64 exec, exec, s[0:1]
	v_mov_b32_e32 v8, 0xf149f2ca
	v_mov_b32_e32 v9, 0xf149f2ca
	s_and_saveexec_b64 s[0:1], s[14:15]
	s_nop 0
	v_mov_b32_e32 v83, v182
	s_mov_b32 s4, 0x3e38aa3b
	v_mov_b32_e32 v82, v10
	s_mov_b32 s5, 0x3fb8aa3b
	s_waitcnt lgkmcnt(0)
	v_pk_mul_f32 v[82:83], v[82:83], s[4:5]
	s_nop 0
	v_add_f32_e32 v9, v82, v83
.LBB0_1565:
	s_or_b64 exec, exec, s[0:1]
	s_and_saveexec_b64 s[0:1], s[16:17]
	s_nop 0
	v_mov_b32_e32 v83, v183
	s_mov_b32 s4, 0x3e38aa3b
	v_mov_b32_e32 v82, v11
	s_mov_b32 s5, 0x3fb8aa3b
	s_waitcnt lgkmcnt(0)
	v_pk_mul_f32 v[10:11], v[82:83], s[4:5]
	s_nop 0
	v_add_f32_e32 v8, v10, v11

.LBB0_1580:
	v_med3_u32 v87, s70, 4, 28
	v_sub_u32_e32 v8, v87, v78
	v_lshlrev_b32_e32 v8, 6, v8
	v_add_u32_e32 v80, v8, v84
	v_lshlrev_b32_e32 v8, 1, v79
	v_and_b32_e32 v72, 3, v85
	v_and_or_b32 v8, v8, 24, v72
	v_add_u32_e32 v92, v8, v80
	v_lshlrev_b32_e32 v8, 1, v92
	v_ashrrev_i32_e32 v81, 4, v85
	v_bfe_u32 v12, v92, 3, 2
	v_and_b32_e32 v96, 4, v8
	v_bitop3_b32 v8, v12, v81, v96 bitop3:0x36
	v_lshlrev_b32_e32 v20, 7, v92
	v_lshl_add_u32 v21, v8, 4, 0
	v_add_u32_e32 v88, v21, v20
	s_waitcnt vmcnt(0) lgkmcnt(0)
	s_waitcnt vmcnt(0) lgkmcnt(0)
	s_barrier
	ds_read_b128 v[8:11], v88
	v_add_u32_e32 v86, 4, v81
	v_bitop3_b32 v12, v12, v86, v96 bitop3:0x36
	v_lshl_add_u32 v28, v12, 4, 0
	v_add_u32_e32 v89, v28, v20
	ds_read_b128 v[12:15], v89
	ds_read_b128 v[16:19], v88 offset:8192
	s_waitcnt lgkmcnt(2)
	v_mfma_f32_16x16x32_bf16 v[8:11], v[8:11], v[4:7], 0
	v_or_b32_e32 v29, 0x200, v20
	v_add_u32_e32 v20, v21, v29
	ds_read_b128 v[20:23], v20
	ds_read_b128 v[24:27], v89 offset:8192
	s_waitcnt lgkmcnt(3)
	v_mfma_f32_16x16x32_bf16 v[68:71], v[12:15], v[0:3], v[8:11]
	s_mul_i32 s0, s25, 0x744
	v_subrev_u32_e32 v87, s70, v87
	s_movk_i32 s1, 0x7c
	v_add_u32_e32 v8, v28, v29
	ds_read_b128 v[8:11], v8
	s_waitcnt lgkmcnt(2)
	v_mfma_f32_16x16x32_bf16 v[12:15], v[20:23], v[4:7], 0
	s_add_i32 s0, s0, 0
	v_mul_lo_u32 v87, v87, s1
	v_add_u32_e32 v87, s0, v87
	s_waitcnt lgkmcnt(0)
	v_mfma_f32_16x16x32_bf16 v[64:67], v[8:11], v[0:3], v[12:15]
	v_mfma_f32_16x16x32_bf16 v[8:11], v[16:19], v[4:7], 0
	v_mfma_f32_16x16x32_bf16 v[60:63], v[24:27], v[0:3], v[8:11]
	s_nop 6
	v_add_u32_e32 v8, 0x44, v92
	v_bfe_u32 v13, v8, 3, 2
	v_lshlrev_b32_e32 v12, 7, v8
	v_bitop3_b32 v8, v13, v81, v96 bitop3:0x36
	v_lshlrev_b32_e32 v8, 4, v8
	v_add3_u32 v8, 0, v8, v12
	ds_read_b128 v[8:11], v8
	v_bitop3_b32 v13, v13, v86, v96 bitop3:0x36
	v_lshlrev_b32_e32 v13, 4, v13
	v_add3_u32 v12, 0, v13, v12
	ds_read_b128 v[12:15], v12
	s_waitcnt lgkmcnt(1)
	v_mfma_f32_16x16x32_bf16 v[8:11], v[8:11], v[4:7], 0
	s_waitcnt lgkmcnt(0)
	v_mfma_f32_16x16x32_bf16 v[56:59], v[12:15], v[0:3], v[8:11]
	s_nop 5
	ds_read_b128 v[8:11], v88 offset:16384
	ds_read_b128 v[12:15], v88 offset:24576
	ds_read_b128 v[16:19], v89 offset:16384
	ds_read_b128 v[20:23], v89 offset:24576
	s_waitcnt lgkmcnt(3)
	v_mfma_f32_16x16x32_bf16 v[8:11], v[8:11], v[4:7], 0
	s_waitcnt lgkmcnt(1)
	v_mfma_f32_16x16x32_bf16 v[52:55], v[16:19], v[0:3], v[8:11]
	s_nop 5
	v_add_u32_e32 v8, 0x84, v92
	v_bfe_u32 v17, v8, 3, 2
	v_lshlrev_b32_e32 v16, 7, v8
	v_bitop3_b32 v8, v17, v81, v96 bitop3:0x36
	v_lshlrev_b32_e32 v8, 4, v8
	v_add3_u32 v8, 0, v8, v16
	ds_read_b128 v[8:11], v8
	v_bitop3_b32 v17, v17, v86, v96 bitop3:0x36
	v_lshlrev_b32_e32 v17, 4, v17
	v_add3_u32 v16, 0, v17, v16
	ds_read_b128 v[16:19], v16
	s_waitcnt lgkmcnt(1)
	v_mfma_f32_16x16x32_bf16 v[8:11], v[8:11], v[4:7], 0
	s_waitcnt lgkmcnt(0)
	v_mfma_f32_16x16x32_bf16 v[48:51], v[16:19], v[0:3], v[8:11]
	v_mfma_f32_16x16x32_bf16 v[8:11], v[12:15], v[4:7], 0
	v_mfma_f32_16x16x32_bf16 v[44:47], v[20:23], v[0:3], v[8:11]
	s_nop 6
	v_add_u32_e32 v8, 0xc4, v92
	v_bfe_u32 v13, v8, 3, 2
	v_lshlrev_b32_e32 v12, 7, v8
	v_bitop3_b32 v8, v13, v81, v96 bitop3:0x36
	v_lshlrev_b32_e32 v8, 4, v8
	v_add3_u32 v8, 0, v8, v12
	ds_read_b128 v[8:11], v8
	v_bitop3_b32 v13, v13, v86, v96 bitop3:0x36
	v_lshlrev_b32_e32 v13, 4, v13
	v_add3_u32 v12, 0, v13, v12
	ds_read_b128 v[12:15], v12
	s_waitcnt lgkmcnt(1)
	v_mfma_f32_16x16x32_bf16 v[8:11], v[8:11], v[4:7], 0
	s_waitcnt lgkmcnt(0)
	v_mfma_f32_16x16x32_bf16 v[40:43], v[12:15], v[0:3], v[8:11]
	s_nop 5
	ds_read_b128 v[8:11], v88 offset:32768
	ds_read_b128 v[12:15], v88 offset:40960
	ds_read_b128 v[16:19], v89 offset:32768
	ds_read_b128 v[20:23], v89 offset:40960
	s_waitcnt lgkmcnt(3)
	v_mfma_f32_16x16x32_bf16 v[8:11], v[8:11], v[4:7], 0
	s_waitcnt lgkmcnt(1)
	v_mfma_f32_16x16x32_bf16 v[36:39], v[16:19], v[0:3], v[8:11]
	s_nop 5
	v_add_u32_e32 v8, 0x104, v92
	v_bfe_u32 v17, v8, 3, 2
	v_lshlrev_b32_e32 v16, 7, v8
	v_bitop3_b32 v8, v17, v81, v96 bitop3:0x36
	v_lshlrev_b32_e32 v8, 4, v8
	v_add3_u32 v8, 0, v8, v16
	ds_read_b128 v[8:11], v8
	v_bitop3_b32 v17, v17, v86, v96 bitop3:0x36
	v_lshlrev_b32_e32 v17, 4, v17
	v_add3_u32 v16, 0, v17, v16
	ds_read_b128 v[16:19], v16
	s_waitcnt lgkmcnt(1)
	v_mfma_f32_16x16x32_bf16 v[8:11], v[8:11], v[4:7], 0
	s_waitcnt lgkmcnt(0)
	v_mfma_f32_16x16x32_bf16 v[32:35], v[16:19], v[0:3], v[8:11]
	v_mfma_f32_16x16x32_bf16 v[8:11], v[12:15], v[4:7], 0
	v_mfma_f32_16x16x32_bf16 v[28:31], v[20:23], v[0:3], v[8:11]
	s_nop 6
	v_add_u32_e32 v8, 0x144, v92
	v_bfe_u32 v13, v8, 3, 2
	v_lshlrev_b32_e32 v12, 7, v8
	v_bitop3_b32 v8, v13, v81, v96 bitop3:0x36
	v_lshlrev_b32_e32 v8, 4, v8
	v_add3_u32 v8, 0, v8, v12
	ds_read_b128 v[8:11], v8
	v_bitop3_b32 v13, v13, v86, v96 bitop3:0x36
	v_lshlrev_b32_e32 v13, 4, v13
	v_add3_u32 v12, 0, v13, v12
	ds_read_b128 v[12:15], v12
	s_waitcnt lgkmcnt(1)
	v_mfma_f32_16x16x32_bf16 v[8:11], v[8:11], v[4:7], 0
	s_waitcnt lgkmcnt(0)
	v_mfma_f32_16x16x32_bf16 v[24:27], v[12:15], v[0:3], v[8:11]
	s_nop 5
	ds_read_b128 v[8:11], v88 offset:49152
	ds_read_b128 v[12:15], v88 offset:57344
	ds_read_b128 v[16:19], v89 offset:49152
	ds_read_b128 v[88:91], v89 offset:57344
	s_waitcnt lgkmcnt(3)
	v_mfma_f32_16x16x32_bf16 v[8:11], v[8:11], v[4:7], 0
	s_waitcnt lgkmcnt(1)
	v_mfma_f32_16x16x32_bf16 v[20:23], v[16:19], v[0:3], v[8:11]
	s_nop 5
	v_add_u32_e32 v8, 0x184, v92
	v_bfe_u32 v17, v8, 3, 2
	v_lshlrev_b32_e32 v16, 7, v8
	v_bitop3_b32 v8, v17, v81, v96 bitop3:0x36
	v_lshlrev_b32_e32 v8, 4, v8
	v_add3_u32 v8, 0, v8, v16
	ds_read_b128 v[8:11], v8
	v_bitop3_b32 v17, v17, v86, v96 bitop3:0x36
	v_lshlrev_b32_e32 v17, 4, v17
	v_add3_u32 v16, 0, v17, v16
	ds_read_b128 v[16:19], v16
	s_waitcnt lgkmcnt(1)
	v_mfma_f32_16x16x32_bf16 v[8:11], v[8:11], v[4:7], 0
	s_waitcnt lgkmcnt(0)
	v_mfma_f32_16x16x32_bf16 v[16:19], v[16:19], v[0:3], v[8:11]
	v_mfma_f32_16x16x32_bf16 v[8:11], v[12:15], v[4:7], 0
	v_add_u32_e32 v12, 0x1c4, v92
	v_lshlrev_b32_e32 v13, 7, v12
	v_bfe_u32 v12, v12, 3, 2
	v_bitop3_b32 v14, v12, v81, v96 bitop3:0x36
	v_lshlrev_b32_e32 v14, 4, v14
	v_add3_u32 v14, 0, v14, v13
	ds_read_b128 v[92:95], v14
	v_bitop3_b32 v12, v12, v86, v96 bitop3:0x36
	v_lshlrev_b32_e32 v12, 4, v12
	v_add3_u32 v12, 0, v12, v13
	ds_read_b128 v[96:99], v12
	v_mfma_f32_16x16x32_bf16 v[12:15], v[88:91], v[0:3], v[8:11]
	s_waitcnt lgkmcnt(1)
	v_mfma_f32_16x16x32_bf16 v[8:11], v[92:95], v[4:7], 0
	v_add_u32_e32 v92, 0x22100, v87
	s_waitcnt lgkmcnt(0)
	v_mfma_f32_16x16x32_bf16 v[8:11], v[96:99], v[0:3], v[8:11]
	v_or_b32_e32 v97, s18, v79
	v_med3_u32 v87, v97, 8, 56
	v_lshl_add_u32 v99, v81, 3, v84
	v_add_u32_e32 v96, -8, v87
	v_add_u32_e32 v98, 8, v87
	v_sub_u32_e32 v84, v99, v97
	v_med3_i32 v84, v84, -15, 15
	v_cmp_ge_i32_e32 vcc, v99, v96
	v_cmp_lt_i32_e64 s[0:1], v99, v98
	v_add_u32_e32 v84, 15, v84
	s_and_b64 vcc, vcc, s[0:1]
	v_cndmask_b32_e32 v87, -1, v84, vcc
	v_cmp_lt_i32_e32 vcc, -1, v87
	v_mov_b32_e32 v84, 0xf149f2ca
	v_lshl_add_u32 v88, v87, 2, v92
	v_mov_b32_e32 v87, 0xf149f2ca
	s_and_saveexec_b64 s[0:1], vcc
	s_nop 0
	ds_read_b32 v91, v88 offset:372
	s_mov_b32 s8, 0x3e38aa3b
	v_mov_b32_e32 v90, v68
	s_mov_b32 s9, 0x3fb8aa3b
	s_waitcnt lgkmcnt(0)
	v_pk_mul_f32 v[90:91], v[90:91], s[8:9]
	s_nop 0
	v_add_f32_e32 v87, v90, v91
.LBB0_1582:
	s_or_b64 exec, exec, s[0:1]
	v_or_b32_e32 v68, 1, v99
	v_sub_u32_e32 v89, v68, v97
	v_med3_i32 v89, v89, -15, 15
	v_cmp_ge_i32_e64 s[0:1], v68, v96
	v_cmp_lt_i32_e64 s[8:9], v68, v98
	v_add_u32_e32 v68, 15, v89
	s_and_b64 s[0:1], s[0:1], s[8:9]
	v_cndmask_b32_e64 v68, -1, v68, s[0:1]
	v_cmp_lt_i32_e64 s[8:9], -1, v68
	v_lshl_add_u32 v89, v68, 2, v92
	s_and_saveexec_b64 s[0:1], s[8:9]
	s_nop 0
	ds_read_b32 v91, v89 offset:372
	s_mov_b32 s10, 0x3e38aa3b
	v_mov_b32_e32 v90, v69
	s_mov_b32 s11, 0x3fb8aa3b
	s_waitcnt lgkmcnt(0)
	v_pk_mul_f32 v[68:69], v[90:91], s[10:11]
	s_nop 0
	v_add_f32_e32 v84, v68, v69
.LBB0_1584:
	s_or_b64 exec, exec, s[0:1]
	v_or_b32_e32 v68, 2, v99
	v_sub_u32_e32 v69, v68, v97
	v_med3_i32 v69, v69, -15, 15
	v_cmp_ge_i32_e64 s[0:1], v68, v96
	v_cmp_lt_i32_e64 s[10:11], v68, v98
	v_add_u32_e32 v68, 15, v69
	s_and_b64 s[0:1], s[0:1], s[10:11]
	v_cndmask_b32_e64 v69, -1, v68, s[0:1]
	v_cmp_lt_i32_e64 s[10:11], -1, v69
	v_mov_b32_e32 v68, 0xf149f2ca
	v_lshl_add_u32 v90, v69, 2, v92
	v_mov_b32_e32 v69, 0xf149f2ca
	s_and_saveexec_b64 s[0:1], s[10:11]
	s_nop 0
	ds_read_b32 v95, v90 offset:372
	s_mov_b32 s12, 0x3e38aa3b
	v_mov_b32_e32 v94, v70
	s_mov_b32 s13, 0x3fb8aa3b
	s_waitcnt lgkmcnt(0)
	v_pk_mul_f32 v[94:95], v[94:95], s[12:13]
	s_nop 0
	v_add_f32_e32 v69, v94, v95
.LBB0_1586:
	s_or_b64 exec, exec, s[0:1]
	v_or_b32_e32 v70, 3, v99
	v_sub_u32_e32 v91, v70, v97
	v_med3_i32 v91, v91, -15, 15
	v_cmp_ge_i32_e64 s[0:1], v70, v96
	v_cmp_lt_i32_e64 s[12:13], v70, v98
	v_add_u32_e32 v70, 15, v91
	s_and_b64 s[0:1], s[0:1], s[12:13]
	v_cndmask_b32_e64 v70, -1, v70, s[0:1]
	v_cmp_lt_i32_e64 s[12:13], -1, v70
	v_lshl_add_u32 v91, v70, 2, v92
	s_and_saveexec_b64 s[0:1], s[12:13]
	s_nop 0
	ds_read_b32 v95, v91 offset:372
	s_mov_b32 s14, 0x3e38aa3b
	v_mov_b32_e32 v94, v71
	s_mov_b32 s15, 0x3fb8aa3b
	s_waitcnt lgkmcnt(0)
	v_pk_mul_f32 v[70:71], v[94:95], s[14:15]
	s_nop 0
	v_add_f32_e32 v68, v70, v71
.LBB0_1588:
	s_or_b64 exec, exec, s[0:1]
	v_or_b32_e32 v70, 4, v99
	v_sub_u32_e32 v71, v70, v97
	v_med3_i32 v71, v71, -15, 15
	v_cmp_ge_i32_e64 s[0:1], v70, v96
	v_cmp_lt_i32_e64 s[14:15], v70, v98
	v_add_u32_e32 v70, 15, v71
	s_and_b64 s[0:1], s[0:1], s[14:15]
	v_cndmask_b32_e64 v71, -1, v70, s[0:1]
	v_cmp_lt_i32_e64 s[14:15], -1, v71
	v_mov_b32_e32 v70, 0xf149f2ca
	v_lshl_add_u32 v93, v71, 2, v92
	v_mov_b32_e32 v71, 0xf149f2ca
	s_and_saveexec_b64 s[0:1], s[14:15]
	s_nop 0
	ds_read_b32 v95, v93 offset:372
	s_mov_b32 s16, 0x3e38aa3b
	v_mov_b32_e32 v94, v64
	s_mov_b32 s17, 0x3fb8aa3b
	s_waitcnt lgkmcnt(0)
	v_pk_mul_f32 v[94:95], v[94:95], s[16:17]
	s_nop 0
	v_add_f32_e32 v71, v94, v95
.LBB0_1590:
	s_or_b64 exec, exec, s[0:1]
	v_or_b32_e32 v64, 5, v99
	v_sub_u32_e32 v94, v64, v97
	v_med3_i32 v94, v94, -15, 15
	v_cmp_ge_i32_e64 s[0:1], v64, v96
	v_cmp_lt_i32_e64 s[16:17], v64, v98
	v_add_u32_e32 v64, 15, v94
	s_and_b64 s[0:1], s[0:1], s[16:17]
	v_cndmask_b32_e64 v64, -1, v64, s[0:1]
	v_cmp_lt_i32_e64 s[16:17], -1, v64
	v_lshl_add_u32 v94, v64, 2, v92
	s_and_saveexec_b64 s[0:1], s[16:17]
	s_nop 0
	ds_read_b32 v101, v94 offset:372
	s_mov_b32 s18, 0x3e38aa3b
	v_mov_b32_e32 v100, v65
	s_mov_b32 s19, 0x3fb8aa3b
	s_waitcnt lgkmcnt(0)
	v_pk_mul_f32 v[64:65], v[100:101], s[18:19]
	s_nop 0
	v_add_f32_e32 v70, v64, v65
.LBB0_1592:
	s_or_b64 exec, exec, s[0:1]
	v_or_b32_e32 v64, 6, v99
	v_sub_u32_e32 v65, v64, v97
	v_med3_i32 v65, v65, -15, 15
	v_cmp_ge_i32_e64 s[0:1], v64, v96
	v_cmp_lt_i32_e64 s[18:19], v64, v98
	v_add_u32_e32 v64, 15, v65
	s_and_b64 s[0:1], s[0:1], s[18:19]
	v_cndmask_b32_e64 v65, -1, v64, s[0:1]
	v_cmp_lt_i32_e64 s[18:19], -1, v65
	v_mov_b32_e32 v64, 0xf149f2ca
	v_lshl_add_u32 v95, v65, 2, v92
	v_mov_b32_e32 v65, 0xf149f2ca
	s_and_saveexec_b64 s[0:1], s[18:19]
	s_nop 0
	ds_read_b32 v101, v95 offset:372
	s_mov_b32 s20, 0x3e38aa3b
	v_mov_b32_e32 v100, v66
	s_mov_b32 s21, 0x3fb8aa3b
	s_waitcnt lgkmcnt(0)
	v_pk_mul_f32 v[100:101], v[100:101], s[20:21]
	s_nop 0
	v_add_f32_e32 v65, v100, v101
.LBB0_1594:
	s_or_b64 exec, exec, s[0:1]
	v_or_b32_e32 v66, 7, v99
	v_sub_u32_e32 v97, v66, v97
	v_med3_i32 v97, v97, -15, 15
	v_cmp_ge_i32_e64 s[0:1], v66, v96
	v_cmp_lt_i32_e64 s[20:21], v66, v98
	v_add_u32_e32 v66, 15, v97
	s_and_b64 s[0:1], s[0:1], s[20:21]
	v_cndmask_b32_e64 v66, -1, v66, s[0:1]
	v_cmp_lt_i32_e64 s[20:21], -1, v66
	v_lshl_add_u32 v96, v66, 2, v92
	s_and_saveexec_b64 s[0:1], s[20:21]
	s_nop 0
	ds_read_b32 v99, v96 offset:372
	s_mov_b32 s34, 0x3e38aa3b
	v_mov_b32_e32 v98, v67
	s_mov_b32 s35, 0x3fb8aa3b
	s_waitcnt lgkmcnt(0)
	v_pk_mul_f32 v[66:67], v[98:99], s[34:35]
	s_nop 0
	v_add_f32_e32 v64, v66, v67
.LBB0_1596:
	s_or_b64 exec, exec, s[0:1]
	v_mov_b32_e32 v66, 0xf149f2ca
	v_mov_b32_e32 v67, 0xf149f2ca
	ds_read_b32 v176, v88 offset:496
	ds_read_b32 v177, v89 offset:496
	ds_read_b32 v178, v90 offset:496
	ds_read_b32 v179, v91 offset:496
	ds_read_b32 v180, v93 offset:496
	ds_read_b32 v181, v94 offset:496
	ds_read_b32 v182, v95 offset:496
	ds_read_b32 v183, v96 offset:496
	s_waitcnt lgkmcnt(0)
	s_and_saveexec_b64 s[0:1], vcc
	s_nop 0
	v_mov_b32_e32 v99, v176
	s_mov_b32 s34, 0x3e38aa3b
	v_mov_b32_e32 v98, v60
	s_mov_b32 s35, 0x3fb8aa3b
	s_waitcnt lgkmcnt(0)
	v_pk_mul_f32 v[98:99], v[98:99], s[34:35]
	s_nop 0
	v_add_f32_e32 v67, v98, v99
.LBB0_1598:
	s_or_b64 exec, exec, s[0:1]
	s_and_saveexec_b64 s[0:1], s[8:9]
	s_nop 0
	v_mov_b32_e32 v99, v177
	s_mov_b32 s34, 0x3e38aa3b
	v_mov_b32_e32 v98, v61
	s_mov_b32 s35, 0x3fb8aa3b
	s_waitcnt lgkmcnt(0)
	v_pk_mul_f32 v[60:61], v[98:99], s[34:35]
	s_nop 0
	v_add_f32_e32 v66, v60, v61
.LBB0_1600:
	s_or_b64 exec, exec, s[0:1]
	v_mov_b32_e32 v60, 0xf149f2ca
	v_mov_b32_e32 v61, 0xf149f2ca
	s_and_saveexec_b64 s[0:1], s[10:11]
	s_nop 0
	v_mov_b32_e32 v99, v178
	s_mov_b32 s34, 0x3e38aa3b
	v_mov_b32_e32 v98, v62
	s_mov_b32 s35, 0x3fb8aa3b
	s_waitcnt lgkmcnt(0)
	v_pk_mul_f32 v[98:99], v[98:99], s[34:35]
	s_nop 0
	v_add_f32_e32 v61, v98, v99
.LBB0_1602:
	s_or_b64 exec, exec, s[0:1]
	s_and_saveexec_b64 s[0:1], s[12:13]
	s_nop 0
	v_mov_b32_e32 v99, v179
	s_mov_b32 s34, 0x3e38aa3b
	v_mov_b32_e32 v98, v63
	s_mov_b32 s35, 0x3fb8aa3b
	s_waitcnt lgkmcnt(0)
	v_pk_mul_f32 v[62:63], v[98:99], s[34:35]
	s_nop 0
	v_add_f32_e32 v60, v62, v63
.LBB0_1604:
	s_or_b64 exec, exec, s[0:1]
	v_mov_b32_e32 v62, 0xf149f2ca
	v_mov_b32_e32 v63, 0xf149f2ca
	s_and_saveexec_b64 s[0:1], s[14:15]
	s_nop 0
	v_mov_b32_e32 v99, v180
	s_mov_b32 s34, 0x3e38aa3b
	v_mov_b32_e32 v98, v56
	s_mov_b32 s35, 0x3fb8aa3b
	s_waitcnt lgkmcnt(0)
	v_pk_mul_f32 v[98:99], v[98:99], s[34:35]
	s_nop 0
	v_add_f32_e32 v63, v98, v99
.LBB0_1606:
	s_or_b64 exec, exec, s[0:1]
	s_and_saveexec_b64 s[0:1], s[16:17]
	s_nop 0
	v_mov_b32_e32 v99, v181
	s_mov_b32 s34, 0x3e38aa3b
	v_mov_b32_e32 v98, v57
	s_mov_b32 s35, 0x3fb8aa3b
	s_waitcnt lgkmcnt(0)
	v_pk_mul_f32 v[56:57], v[98:99], s[34:35]
	s_nop 0
	v_add_f32_e32 v62, v56, v57
.LBB0_1608:
	s_or_b64 exec, exec, s[0:1]
	v_mov_b32_e32 v56, 0xf149f2ca
	v_mov_b32_e32 v92, 0xf149f2ca
	s_and_saveexec_b64 s[0:1], s[18:19]
	s_nop 0
	v_mov_b32_e32 v99, v182
	s_mov_b32 s34, 0x3e38aa3b
	v_mov_b32_e32 v98, v58
	s_mov_b32 s35, 0x3fb8aa3b
	s_waitcnt lgkmcnt(0)
	v_pk_mul_f32 v[98:99], v[98:99], s[34:35]
	s_nop 0
	v_add_f32_e32 v92, v98, v99
.LBB0_1610:
	s_or_b64 exec, exec, s[0:1]
	s_and_saveexec_b64 s[0:1], s[20:21]
	s_nop 0
	v_mov_b32_e32 v57, v183
	s_mov_b32 s34, 0x3e38aa3b
	v_mov_b32_e32 v56, v59
	s_mov_b32 s35, 0x3fb8aa3b
	s_waitcnt lgkmcnt(0)
	v_pk_mul_f32 v[56:57], v[56:57], s[34:35]
	s_nop 0
	v_add_f32_e32 v56, v56, v57
.LBB0_1612:
	s_or_b64 exec, exec, s[0:1]
	v_mov_b32_e32 v57, 0xf149f2ca
	v_mov_b32_e32 v58, 0xf149f2ca
	ds_read_b32 v176, v88 offset:620
	ds_read_b32 v177, v89 offset:620
	ds_read_b32 v178, v90 offset:620
	ds_read_b32 v179, v91 offset:620
	ds_read_b32 v180, v93 offset:620
	ds_read_b32 v181, v94 offset:620
	ds_read_b32 v182, v95 offset:620
	ds_read_b32 v183, v96 offset:620
	s_waitcnt lgkmcnt(0)
	s_and_saveexec_b64 s[0:1], vcc
	s_nop 0
	v_mov_b32_e32 v59, v176
	s_mov_b32 s34, 0x3e38aa3b
	v_mov_b32_e32 v58, v52
	s_mov_b32 s35, 0x3fb8aa3b
	s_waitcnt lgkmcnt(0)
	v_pk_mul_f32 v[58:59], v[58:59], s[34:35]
	s_nop 0
	v_add_f32_e32 v58, v58, v59
.LBB0_1614:
	s_or_b64 exec, exec, s[0:1]
	s_and_saveexec_b64 s[0:1], s[8:9]
	s_nop 0
	v_mov_b32_e32 v99, v177
	s_mov_b32 s34, 0x3e38aa3b
	v_mov_b32_e32 v98, v53
	s_mov_b32 s35, 0x3fb8aa3b
	s_waitcnt lgkmcnt(0)
	v_pk_mul_f32 v[52:53], v[98:99], s[34:35]
	s_nop 0
	v_add_f32_e32 v57, v52, v53
.LBB0_1616:
	s_or_b64 exec, exec, s[0:1]
	v_mov_b32_e32 v52, 0xf149f2ca
	v_mov_b32_e32 v53, 0xf149f2ca
	s_and_saveexec_b64 s[0:1], s[10:11]
	s_nop 0
	v_mov_b32_e32 v99, v178
	s_mov_b32 s34, 0x3e38aa3b
	v_mov_b32_e32 v98, v54
	s_mov_b32 s35, 0x3fb8aa3b
	s_waitcnt lgkmcnt(0)
	v_pk_mul_f32 v[98:99], v[98:99], s[34:35]
	s_nop 0
	v_add_f32_e32 v53, v98, v99
.LBB0_1618:
	s_or_b64 exec, exec, s[0:1]
	s_and_saveexec_b64 s[0:1], s[12:13]
	s_nop 0
	v_mov_b32_e32 v99, v179
	s_mov_b32 s34, 0x3e38aa3b
	v_mov_b32_e32 v98, v55
	s_mov_b32 s35, 0x3fb8aa3b
	s_waitcnt lgkmcnt(0)
	v_pk_mul_f32 v[54:55], v[98:99], s[34:35]
	s_nop 0
	v_add_f32_e32 v52, v54, v55
.LBB0_1620:
	s_or_b64 exec, exec, s[0:1]
	v_mov_b32_e32 v54, 0xf149f2ca
	v_mov_b32_e32 v55, 0xf149f2ca
	s_and_saveexec_b64 s[0:1], s[14:15]
	s_nop 0
	v_mov_b32_e32 v99, v180
	s_mov_b32 s34, 0x3e38aa3b
	v_mov_b32_e32 v98, v48
	s_mov_b32 s35, 0x3fb8aa3b
	s_waitcnt lgkmcnt(0)
	v_pk_mul_f32 v[98:99], v[98:99], s[34:35]
	s_nop 0
	v_add_f32_e32 v55, v98, v99
.LBB0_1622:
	s_or_b64 exec, exec, s[0:1]
	s_and_saveexec_b64 s[0:1], s[16:17]
	s_nop 0
	v_mov_b32_e32 v99, v181
	s_mov_b32 s34, 0x3e38aa3b
	v_mov_b32_e32 v98, v49
	s_mov_b32 s35, 0x3fb8aa3b
	s_waitcnt lgkmcnt(0)
	v_pk_mul_f32 v[48:49], v[98:99], s[34:35]
	s_nop 0
	v_add_f32_e32 v54, v48, v49
.LBB0_1624:
	s_or_b64 exec, exec, s[0:1]
	v_mov_b32_e32 v48, 0xf149f2ca
	v_mov_b32_e32 v59, 0xf149f2ca
	s_and_saveexec_b64 s[0:1], s[18:19]
	s_nop 0
	v_mov_b32_e32 v99, v182
	s_mov_b32 s34, 0x3e38aa3b
	v_mov_b32_e32 v98, v50
	s_mov_b32 s35, 0x3fb8aa3b
	s_waitcnt lgkmcnt(0)
	v_pk_mul_f32 v[98:99], v[98:99], s[34:35]
	s_nop 0
	v_add_f32_e32 v59, v98, v99
.LBB0_1626:
	s_or_b64 exec, exec, s[0:1]
	s_and_saveexec_b64 s[0:1], s[20:21]
	s_nop 0
	v_mov_b32_e32 v49, v183
	s_mov_b32 s34, 0x3e38aa3b
	v_mov_b32_e32 v48, v51
	s_mov_b32 s35, 0x3fb8aa3b
	s_waitcnt lgkmcnt(0)
	v_pk_mul_f32 v[48:49], v[48:49], s[34:35]
	s_nop 0
	v_add_f32_e32 v48, v48, v49
.LBB0_1628:
	s_or_b64 exec, exec, s[0:1]
	v_mov_b32_e32 v49, 0xf149f2ca
	v_mov_b32_e32 v50, 0xf149f2ca
	ds_read_b32 v176, v88 offset:744
	ds_read_b32 v177, v89 offset:744
	ds_read_b32 v178, v90 offset:744
	ds_read_b32 v179, v91 offset:744
	ds_read_b32 v180, v93 offset:744
	ds_read_b32 v181, v94 offset:744
	ds_read_b32 v182, v95 offset:744
	ds_read_b32 v183, v96 offset:744
	s_waitcnt lgkmcnt(0)
	s_and_saveexec_b64 s[0:1], vcc
	s_nop 0
	v_mov_b32_e32 v51, v176
	s_mov_b32 s34, 0x3e38aa3b
	v_mov_b32_e32 v50, v44
	s_mov_b32 s35, 0x3fb8aa3b
	s_waitcnt lgkmcnt(0)
	v_pk_mul_f32 v[50:51], v[50:51], s[34:35]
	s_nop 0
	v_add_f32_e32 v50, v50, v51
.LBB0_1630:
	s_or_b64 exec, exec, s[0:1]
	s_and_saveexec_b64 s[0:1], s[8:9]
	s_nop 0
	v_mov_b32_e32 v99, v177
	s_mov_b32 s34, 0x3e38aa3b
	v_mov_b32_e32 v98, v45
	s_mov_b32 s35, 0x3fb8aa3b
	s_waitcnt lgkmcnt(0)
	v_pk_mul_f32 v[44:45], v[98:99], s[34:35]
	s_nop 0
	v_add_f32_e32 v49, v44, v45
.LBB0_1632:
	s_or_b64 exec, exec, s[0:1]
	v_mov_b32_e32 v44, 0xf149f2ca
	v_mov_b32_e32 v45, 0xf149f2ca
	s_and_saveexec_b64 s[0:1], s[10:11]
	s_nop 0
	v_mov_b32_e32 v99, v178
	s_mov_b32 s34, 0x3e38aa3b
	v_mov_b32_e32 v98, v46
	s_mov_b32 s35, 0x3fb8aa3b
	s_waitcnt lgkmcnt(0)
	v_pk_mul_f32 v[98:99], v[98:99], s[34:35]
	s_nop 0
	v_add_f32_e32 v45, v98, v99
.LBB0_1634:
	s_or_b64 exec, exec, s[0:1]
	s_and_saveexec_b64 s[0:1], s[12:13]
	s_nop 0
	v_mov_b32_e32 v99, v179
	s_mov_b32 s34, 0x3e38aa3b
	v_mov_b32_e32 v98, v47
	s_mov_b32 s35, 0x3fb8aa3b
	s_waitcnt lgkmcnt(0)
	v_pk_mul_f32 v[46:47], v[98:99], s[34:35]
	s_nop 0
	v_add_f32_e32 v44, v46, v47
.LBB0_1636:
	s_or_b64 exec, exec, s[0:1]
	v_mov_b32_e32 v46, 0xf149f2ca
	v_mov_b32_e32 v47, 0xf149f2ca
	s_and_saveexec_b64 s[0:1], s[14:15]
	s_nop 0
	v_mov_b32_e32 v99, v180
	s_mov_b32 s34, 0x3e38aa3b
	v_mov_b32_e32 v98, v40
	s_mov_b32 s35, 0x3fb8aa3b
	s_waitcnt lgkmcnt(0)
	v_pk_mul_f32 v[98:99], v[98:99], s[34:35]
	s_nop 0
	v_add_f32_e32 v47, v98, v99
.LBB0_1638:
	s_or_b64 exec, exec, s[0:1]
	s_and_saveexec_b64 s[0:1], s[16:17]
	s_nop 0
	v_mov_b32_e32 v99, v181
	s_mov_b32 s34, 0x3e38aa3b
	v_mov_b32_e32 v98, v41
	s_mov_b32 s35, 0x3fb8aa3b
	s_waitcnt lgkmcnt(0)
	v_pk_mul_f32 v[40:41], v[98:99], s[34:35]
	s_nop 0
	v_add_f32_e32 v46, v40, v41
.LBB0_1640:
	s_or_b64 exec, exec, s[0:1]
	v_mov_b32_e32 v40, 0xf149f2ca
	v_mov_b32_e32 v51, 0xf149f2ca
	s_and_saveexec_b64 s[0:1], s[18:19]
	s_nop 0
	v_mov_b32_e32 v99, v182
	s_mov_b32 s34, 0x3e38aa3b
	v_mov_b32_e32 v98, v42
	s_mov_b32 s35, 0x3fb8aa3b
	s_waitcnt lgkmcnt(0)
	v_pk_mul_f32 v[98:99], v[98:99], s[34:35]
	s_nop 0
	v_add_f32_e32 v51, v98, v99
.LBB0_1642:
	s_or_b64 exec, exec, s[0:1]
	s_and_saveexec_b64 s[0:1], s[20:21]
	s_nop 0
	v_mov_b32_e32 v41, v183
	s_mov_b32 s34, 0x3e38aa3b
	v_mov_b32_e32 v40, v43
	s_mov_b32 s35, 0x3fb8aa3b
	s_waitcnt lgkmcnt(0)
	v_pk_mul_f32 v[40:41], v[40:41], s[34:35]
	s_nop 0
	v_add_f32_e32 v40, v40, v41
.LBB0_1644:
	s_or_b64 exec, exec, s[0:1]
	v_mov_b32_e32 v41, 0xf149f2ca
	v_mov_b32_e32 v42, 0xf149f2ca
	ds_read_b32 v176, v88 offset:868
	ds_read_b32 v177, v89 offset:868
	ds_read_b32 v178, v90 offset:868
	ds_read_b32 v179, v91 offset:868
	ds_read_b32 v180, v93 offset:868
	ds_read_b32 v181, v94 offset:868
	ds_read_b32 v182, v95 offset:868
	ds_read_b32 v183, v96 offset:868
	s_waitcnt lgkmcnt(0)
	s_and_saveexec_b64 s[0:1], vcc
	s_nop 0
	v_mov_b32_e32 v43, v176
	s_mov_b32 s34, 0x3e38aa3b
	v_mov_b32_e32 v42, v36
	s_mov_b32 s35, 0x3fb8aa3b
	s_waitcnt lgkmcnt(0)
	v_pk_mul_f32 v[42:43], v[42:43], s[34:35]
	s_nop 0
	v_add_f32_e32 v42, v42, v43
.LBB0_1646:
	s_or_b64 exec, exec, s[0:1]
	s_and_saveexec_b64 s[0:1], s[8:9]
	s_nop 0
	v_mov_b32_e32 v99, v177
	s_mov_b32 s34, 0x3e38aa3b
	v_mov_b32_e32 v98, v37
	s_mov_b32 s35, 0x3fb8aa3b
	s_waitcnt lgkmcnt(0)
	v_pk_mul_f32 v[36:37], v[98:99], s[34:35]
	s_nop 0
	v_add_f32_e32 v41, v36, v37
.LBB0_1648:
	s_or_b64 exec, exec, s[0:1]
	v_mov_b32_e32 v36, 0xf149f2ca
	v_mov_b32_e32 v37, 0xf149f2ca
	s_and_saveexec_b64 s[0:1], s[10:11]
	s_nop 0
	v_mov_b32_e32 v99, v178
	s_mov_b32 s34, 0x3e38aa3b
	v_mov_b32_e32 v98, v38
	s_mov_b32 s35, 0x3fb8aa3b
	s_waitcnt lgkmcnt(0)
	v_pk_mul_f32 v[98:99], v[98:99], s[34:35]
	s_nop 0
	v_add_f32_e32 v37, v98, v99
.LBB0_1650:
	s_or_b64 exec, exec, s[0:1]
	s_and_saveexec_b64 s[0:1], s[12:13]
	s_nop 0
	v_mov_b32_e32 v99, v179
	s_mov_b32 s34, 0x3e38aa3b
	v_mov_b32_e32 v98, v39
	s_mov_b32 s35, 0x3fb8aa3b
	s_waitcnt lgkmcnt(0)
	v_pk_mul_f32 v[38:39], v[98:99], s[34:35]
	s_nop 0
	v_add_f32_e32 v36, v38, v39
.LBB0_1652:
	s_or_b64 exec, exec, s[0:1]
	v_mov_b32_e32 v38, 0xf149f2ca
	v_mov_b32_e32 v39, 0xf149f2ca
	s_and_saveexec_b64 s[0:1], s[14:15]
	s_nop 0
	v_mov_b32_e32 v99, v180
	s_mov_b32 s34, 0x3e38aa3b
	v_mov_b32_e32 v98, v32
	s_mov_b32 s35, 0x3fb8aa3b
	s_waitcnt lgkmcnt(0)
	v_pk_mul_f32 v[98:99], v[98:99], s[34:35]
	s_nop 0
	v_add_f32_e32 v39, v98, v99
.LBB0_1654:
	s_or_b64 exec, exec, s[0:1]
	s_and_saveexec_b64 s[0:1], s[16:17]
	s_nop 0
	v_mov_b32_e32 v99, v181
	s_mov_b32 s34, 0x3e38aa3b
	v_mov_b32_e32 v98, v33
	s_mov_b32 s35, 0x3fb8aa3b
	s_waitcnt lgkmcnt(0)
	v_pk_mul_f32 v[32:33], v[98:99], s[34:35]
	s_nop 0
	v_add_f32_e32 v38, v32, v33
.LBB0_1656:
	s_or_b64 exec, exec, s[0:1]
	v_mov_b32_e32 v32, 0xf149f2ca
	v_mov_b32_e32 v43, 0xf149f2ca
	s_and_saveexec_b64 s[0:1], s[18:19]
	s_nop 0
	v_mov_b32_e32 v99, v182
	s_mov_b32 s34, 0x3e38aa3b
	v_mov_b32_e32 v98, v34
	s_mov_b32 s35, 0x3fb8aa3b
	s_waitcnt lgkmcnt(0)
	v_pk_mul_f32 v[98:99], v[98:99], s[34:35]
	s_nop 0
	v_add_f32_e32 v43, v98, v99
.LBB0_1658:
	s_or_b64 exec, exec, s[0:1]
	s_and_saveexec_b64 s[0:1], s[20:21]
	s_nop 0
	v_mov_b32_e32 v33, v183
	s_mov_b32 s34, 0x3e38aa3b
	v_mov_b32_e32 v32, v35
	s_mov_b32 s35, 0x3fb8aa3b
	s_waitcnt lgkmcnt(0)
	v_pk_mul_f32 v[32:33], v[32:33], s[34:35]
	s_nop 0
	v_add_f32_e32 v32, v32, v33
.LBB0_1660:
	s_or_b64 exec, exec, s[0:1]
	v_mov_b32_e32 v33, 0xf149f2ca
	v_mov_b32_e32 v34, 0xf149f2ca
	ds_read_b32 v176, v88 offset:992
	ds_read_b32 v177, v89 offset:992
	ds_read_b32 v178, v90 offset:992
	ds_read_b32 v179, v91 offset:992
	ds_read_b32 v180, v93 offset:992
	ds_read_b32 v181, v94 offset:992
	ds_read_b32 v182, v95 offset:992
	ds_read_b32 v183, v96 offset:992
	s_waitcnt lgkmcnt(0)
	s_and_saveexec_b64 s[0:1], vcc
	s_nop 0
	v_mov_b32_e32 v35, v176
	s_mov_b32 s34, 0x3e38aa3b
	v_mov_b32_e32 v34, v28
	s_mov_b32 s35, 0x3fb8aa3b
	s_waitcnt lgkmcnt(0)
	v_pk_mul_f32 v[34:35], v[34:35], s[34:35]
	s_nop 0
	v_add_f32_e32 v34, v34, v35
.LBB0_1662:
	s_or_b64 exec, exec, s[0:1]
	s_and_saveexec_b64 s[0:1], s[8:9]
	s_nop 0
	v_mov_b32_e32 v99, v177
	s_mov_b32 s34, 0x3e38aa3b
	v_mov_b32_e32 v98, v29
	s_mov_b32 s35, 0x3fb8aa3b
	s_waitcnt lgkmcnt(0)
	v_pk_mul_f32 v[28:29], v[98:99], s[34:35]
	s_nop 0
	v_add_f32_e32 v33, v28, v29
.LBB0_1664:
	s_or_b64 exec, exec, s[0:1]
	v_mov_b32_e32 v28, 0xf149f2ca
	v_mov_b32_e32 v29, 0xf149f2ca
	s_and_saveexec_b64 s[0:1], s[10:11]
	s_nop 0
	v_mov_b32_e32 v99, v178
	s_mov_b32 s34, 0x3e38aa3b
	v_mov_b32_e32 v98, v30
	s_mov_b32 s35, 0x3fb8aa3b
	s_waitcnt lgkmcnt(0)
	v_pk_mul_f32 v[98:99], v[98:99], s[34:35]
	s_nop 0
	v_add_f32_e32 v29, v98, v99
.LBB0_1666:
	s_or_b64 exec, exec, s[0:1]
	s_and_saveexec_b64 s[0:1], s[12:13]
	s_nop 0
	v_mov_b32_e32 v99, v179
	s_mov_b32 s34, 0x3e38aa3b
	v_mov_b32_e32 v98, v31
	s_mov_b32 s35, 0x3fb8aa3b
	s_waitcnt lgkmcnt(0)
	v_pk_mul_f32 v[30:31], v[98:99], s[34:35]
	s_nop 0
	v_add_f32_e32 v28, v30, v31
.LBB0_1668:
	s_or_b64 exec, exec, s[0:1]
	v_mov_b32_e32 v30, 0xf149f2ca
	v_mov_b32_e32 v31, 0xf149f2ca
	s_and_saveexec_b64 s[0:1], s[14:15]
	s_nop 0
	v_mov_b32_e32 v99, v180
	s_mov_b32 s34, 0x3e38aa3b
	v_mov_b32_e32 v98, v24
	s_mov_b32 s35, 0x3fb8aa3b
	s_waitcnt lgkmcnt(0)
	v_pk_mul_f32 v[98:99], v[98:99], s[34:35]
	s_nop 0
	v_add_f32_e32 v31, v98, v99
.LBB0_1670:
	s_or_b64 exec, exec, s[0:1]
	s_and_saveexec_b64 s[0:1], s[16:17]
	s_nop 0
	v_mov_b32_e32 v99, v181
	s_mov_b32 s34, 0x3e38aa3b
	v_mov_b32_e32 v98, v25
	s_mov_b32 s35, 0x3fb8aa3b
	s_waitcnt lgkmcnt(0)
	v_pk_mul_f32 v[24:25], v[98:99], s[34:35]
	s_nop 0
	v_add_f32_e32 v30, v24, v25
.LBB0_1672:
	s_or_b64 exec, exec, s[0:1]
	v_mov_b32_e32 v24, 0xf149f2ca
	v_mov_b32_e32 v35, 0xf149f2ca
	s_and_saveexec_b64 s[0:1], s[18:19]
	s_nop 0
	v_mov_b32_e32 v99, v182
	s_mov_b32 s34, 0x3e38aa3b
	v_mov_b32_e32 v98, v26
	s_mov_b32 s35, 0x3fb8aa3b
	s_waitcnt lgkmcnt(0)
	v_pk_mul_f32 v[98:99], v[98:99], s[34:35]
	s_nop 0
	v_add_f32_e32 v35, v98, v99
.LBB0_1674:
	s_or_b64 exec, exec, s[0:1]
	s_and_saveexec_b64 s[0:1], s[20:21]
	s_nop 0
	v_mov_b32_e32 v25, v183
	s_mov_b32 s34, 0x3e38aa3b
	v_mov_b32_e32 v24, v27
	s_mov_b32 s35, 0x3fb8aa3b
	s_waitcnt lgkmcnt(0)
	v_pk_mul_f32 v[24:25], v[24:25], s[34:35]
	s_nop 0
	v_add_f32_e32 v24, v24, v25
.LBB0_1676:
	s_or_b64 exec, exec, s[0:1]
	v_mov_b32_e32 v25, 0xf149f2ca
	v_mov_b32_e32 v26, 0xf149f2ca
	ds_read_b32 v176, v88 offset:1116
	ds_read_b32 v177, v89 offset:1116
	ds_read_b32 v178, v90 offset:1116
	ds_read_b32 v179, v91 offset:1116
	ds_read_b32 v180, v93 offset:1116
	ds_read_b32 v181, v94 offset:1116
	ds_read_b32 v182, v95 offset:1116
	ds_read_b32 v183, v96 offset:1116
	s_waitcnt lgkmcnt(0)
	s_and_saveexec_b64 s[0:1], vcc
	s_nop 0
	v_mov_b32_e32 v27, v176
	s_mov_b32 s34, 0x3e38aa3b
	v_mov_b32_e32 v26, v20
	s_mov_b32 s35, 0x3fb8aa3b
	s_waitcnt lgkmcnt(0)
	v_pk_mul_f32 v[26:27], v[26:27], s[34:35]
	s_nop 0
	v_add_f32_e32 v26, v26, v27
.LBB0_1678:
	s_or_b64 exec, exec, s[0:1]
	s_and_saveexec_b64 s[0:1], s[8:9]
	s_nop 0
	v_mov_b32_e32 v99, v177
	s_mov_b32 s34, 0x3e38aa3b
	v_mov_b32_e32 v98, v21
	s_mov_b32 s35, 0x3fb8aa3b
	s_waitcnt lgkmcnt(0)
	v_pk_mul_f32 v[20:21], v[98:99], s[34:35]
	s_nop 0
	v_add_f32_e32 v25, v20, v21
.LBB0_1680:
	s_or_b64 exec, exec, s[0:1]
	v_mov_b32_e32 v20, 0xf149f2ca
	v_mov_b32_e32 v21, 0xf149f2ca
	s_and_saveexec_b64 s[0:1], s[10:11]
	s_nop 0
	v_mov_b32_e32 v99, v178
	s_mov_b32 s34, 0x3e38aa3b
	v_mov_b32_e32 v98, v22
	s_mov_b32 s35, 0x3fb8aa3b
	s_waitcnt lgkmcnt(0)
	v_pk_mul_f32 v[98:99], v[98:99], s[34:35]
	s_nop 0
	v_add_f32_e32 v21, v98, v99
.LBB0_1682:
	s_or_b64 exec, exec, s[0:1]
	s_and_saveexec_b64 s[0:1], s[12:13]
	s_nop 0
	v_mov_b32_e32 v99, v179
	s_mov_b32 s34, 0x3e38aa3b
	v_mov_b32_e32 v98, v23
	s_mov_b32 s35, 0x3fb8aa3b
	s_waitcnt lgkmcnt(0)
	v_pk_mul_f32 v[22:23], v[98:99], s[34:35]
	s_nop 0
	v_add_f32_e32 v20, v22, v23
.LBB0_1684:
	s_or_b64 exec, exec, s[0:1]
	v_mov_b32_e32 v22, 0xf149f2ca
	v_mov_b32_e32 v23, 0xf149f2ca
	s_and_saveexec_b64 s[0:1], s[14:15]
	s_nop 0
	v_mov_b32_e32 v99, v180
	s_mov_b32 s34, 0x3e38aa3b
	v_mov_b32_e32 v98, v16
	s_mov_b32 s35, 0x3fb8aa3b
	s_waitcnt lgkmcnt(0)
	v_pk_mul_f32 v[98:99], v[98:99], s[34:35]
	s_nop 0
	v_add_f32_e32 v23, v98, v99
.LBB0_1686:
	s_or_b64 exec, exec, s[0:1]
	s_and_saveexec_b64 s[0:1], s[16:17]
	s_nop 0
	v_mov_b32_e32 v99, v181
	s_mov_b32 s34, 0x3e38aa3b
	v_mov_b32_e32 v98, v17
	s_mov_b32 s35, 0x3fb8aa3b
	s_waitcnt lgkmcnt(0)
	v_pk_mul_f32 v[16:17], v[98:99], s[34:35]
	s_nop 0
	v_add_f32_e32 v22, v16, v17
.LBB0_1688:
	s_or_b64 exec, exec, s[0:1]
	v_mov_b32_e32 v17, 0xf149f2ca
	v_mov_b32_e32 v27, 0xf149f2ca
	s_and_saveexec_b64 s[0:1], s[18:19]
	s_nop 0
	v_mov_b32_e32 v99, v182
	s_mov_b32 s34, 0x3e38aa3b
	v_mov_b32_e32 v98, v18
	s_mov_b32 s35, 0x3fb8aa3b
	s_waitcnt lgkmcnt(0)
	v_pk_mul_f32 v[98:99], v[98:99], s[34:35]
	s_nop 0
	v_add_f32_e32 v27, v98, v99
.LBB0_1690:
	s_or_b64 exec, exec, s[0:1]
	s_and_saveexec_b64 s[0:1], s[20:21]
	s_nop 0
	v_mov_b32_e32 v17, v183
	s_mov_b32 s34, 0x3e38aa3b
	v_mov_b32_e32 v16, v19
	s_mov_b32 s35, 0x3fb8aa3b
	s_waitcnt lgkmcnt(0)
	v_pk_mul_f32 v[16:17], v[16:17], s[34:35]
	s_nop 0
	v_add_f32_e32 v17, v16, v17
.LBB0_1692:
	s_or_b64 exec, exec, s[0:1]
	v_mov_b32_e32 v16, 0xf149f2ca
	v_mov_b32_e32 v18, 0xf149f2ca
	ds_read_b32 v176, v88 offset:1240
	ds_read_b32 v177, v89 offset:1240
	ds_read_b32 v178, v90 offset:1240
	ds_read_b32 v179, v91 offset:1240
	ds_read_b32 v180, v93 offset:1240
	ds_read_b32 v181, v94 offset:1240
	ds_read_b32 v182, v95 offset:1240
	ds_read_b32 v183, v96 offset:1240
	s_waitcnt lgkmcnt(0)
	s_and_saveexec_b64 s[0:1], vcc
	s_nop 0
	v_mov_b32_e32 v19, v176
	s_mov_b32 s34, 0x3e38aa3b
	v_mov_b32_e32 v18, v12
	s_mov_b32 s35, 0x3fb8aa3b
	s_waitcnt lgkmcnt(0)
	v_pk_mul_f32 v[18:19], v[18:19], s[34:35]
	s_nop 0
	v_add_f32_e32 v18, v18, v19
.LBB0_1694:
	s_or_b64 exec, exec, s[0:1]
	s_and_saveexec_b64 s[0:1], s[8:9]
	s_nop 0
	v_mov_b32_e32 v89, v177
	s_mov_b32 s8, 0x3e38aa3b
	v_mov_b32_e32 v88, v13
	s_mov_b32 s9, 0x3fb8aa3b
	s_waitcnt lgkmcnt(0)
	v_pk_mul_f32 v[12:13], v[88:89], s[8:9]
	s_nop 0
	v_add_f32_e32 v16, v12, v13
.LBB0_1696:
	s_or_b64 exec, exec, s[0:1]
	v_mov_b32_e32 v12, 0xf149f2ca
	v_mov_b32_e32 v13, 0xf149f2ca
	s_and_saveexec_b64 s[0:1], s[10:11]
	s_nop 0
	v_mov_b32_e32 v89, v178
	s_mov_b32 s8, 0x3e38aa3b
	v_mov_b32_e32 v88, v14
	s_mov_b32 s9, 0x3fb8aa3b
	s_waitcnt lgkmcnt(0)
	v_pk_mul_f32 v[88:89], v[88:89], s[8:9]
	s_nop 0
	v_add_f32_e32 v13, v88, v89
.LBB0_1698:
	s_or_b64 exec, exec, s[0:1]
	s_and_saveexec_b64 s[0:1], s[12:13]
	s_nop 0
	v_mov_b32_e32 v89, v179
	s_mov_b32 s8, 0x3e38aa3b
	v_mov_b32_e32 v88, v15
	s_mov_b32 s9, 0x3fb8aa3b
	s_waitcnt lgkmcnt(0)
	v_pk_mul_f32 v[14:15], v[88:89], s[8:9]
	s_nop 0
	v_add_f32_e32 v12, v14, v15
.LBB0_1700:
	s_or_b64 exec, exec, s[0:1]
	v_mov_b32_e32 v14, 0xf149f2ca
	v_mov_b32_e32 v15, 0xf149f2ca
	s_and_saveexec_b64 s[0:1], s[14:15]
	s_nop 0
	v_mov_b32_e32 v89, v180
	s_mov_b32 s8, 0x3e38aa3b
	v_mov_b32_e32 v88, v8
	s_mov_b32 s9, 0x3fb8aa3b
	s_waitcnt lgkmcnt(0)
	v_pk_mul_f32 v[88:89], v[88:89], s[8:9]
	s_nop 0
	v_add_f32_e32 v15, v88, v89
.LBB0_1702:
	s_or_b64 exec, exec, s[0:1]
	s_and_saveexec_b64 s[0:1], s[16:17]
	s_nop 0
	v_mov_b32_e32 v89, v181
	s_mov_b32 s8, 0x3e38aa3b
	v_mov_b32_e32 v88, v9
	s_mov_b32 s9, 0x3fb8aa3b
	s_waitcnt lgkmcnt(0)
	v_pk_mul_f32 v[8:9], v[88:89], s[8:9]
	s_nop 0
	v_add_f32_e32 v14, v8, v9
.LBB0_1704:
	s_or_b64 exec, exec, s[0:1]
	v_mov_b32_e32 v19, 0xf149f2ca
	v_mov_b32_e32 v91, 0xf149f2ca
	s_and_saveexec_b64 s[0:1], s[18:19]
	s_nop 0
	v_mov_b32_e32 v9, v182
	s_mov_b32 s8, 0x3e38aa3b
	v_mov_b32_e32 v8, v10
	s_mov_b32 s9, 0x3fb8aa3b
	s_waitcnt lgkmcnt(0)
	v_pk_mul_f32 v[8:9], v[8:9], s[8:9]
	s_nop 0
	v_add_f32_e32 v91, v8, v9
.LBB0_1706:
	s_or_b64 exec, exec, s[0:1]
	s_and_saveexec_b64 s[0:1], s[20:21]
	s_nop 0
	v_mov_b32_e32 v9, v183
	s_mov_b32 s8, 0x3e38aa3b
	v_mov_b32_e32 v8, v11
	s_mov_b32 s9, 0x3fb8aa3b
	s_waitcnt lgkmcnt(0)
	v_pk_mul_f32 v[8:9], v[8:9], s[8:9]
	s_nop 0
	v_add_f32_e32 v19, v8, v9
